# hand-off overlap: block-closing barrier signalled one MFMA early with s_setprio 2 so the leftover MFMA wins arbitration over the partner's starting block
# baseline (speedup 1.0000x reference)
;     __device__ __forceinline__ bool next(int i, Unit& u) const { if (!base.next(i >> 1, u)) return false; if (i & 1) { u.pm += 64; u.pn += 8; } return true; }
; #define PG8_STAGE(bufoff, gbase, voff) do { _Pragma("unroll") for (int _i = 0; _i < 2; ++_i) \
;         __builtin_amdgcn_global_load_lds((const unsigned*)((const char*)(gbase) + (voff)[_i]), (PG8_LAS unsigned*)(lds + (bufoff) + ldsw + _i * 8192), 16, 0, 0); } while (0)
; #define PG8_WAIT_V(n) asm volatile("s_waitcnt vmcnt(" #n ")" ::: "memory")
; template <class Epi, class Sched, bool ALIGN_EPI = false, bool SP2 = false>
; __device__ __forceinline__ void gemm_phase(PG8_LAS unsigned char* lds, const Gemm g, const Sched& S, const Epi& E) {
;     ...
;         const bool has_next = S.next(ui + 1, nxt);
;         const char* nA = has_next ? (const char*)g.A + (size_t)nxt.pm * tstep : cA; const char* nB = has_next ? (const char*)g.Bt + (size_t)nxt.pn * tstep : cB;
;         for (int t = 0; t < nt; t += 2) {
;             const bool last = (t == nt - 2);
;             const char* a1 = cA + (size_t)(t + 1) * kstep;
;             const char* a2 = last ? nA : cA + (size_t)(t + 2) * kstep; const char* b2 = last ? nB : cB + (size_t)(t + 2) * kstep;
;             const char* a3 = a2 + kstep; const char* b3 = b2 + kstep;
;             if (last && has_next) S.a_ready(nxt);
;             if constexpr (SP2) {
;             PG8_LDB(B0, 0, 0); PG8_LDB(B1, 0, 1); PG8_SCHED; PG8_LDA(At, 0, 0); PG8_STAGE(PG8_SA(1, 1), a1 + hstep, voffA);
;             PG8_WAIT_V(8); PG8_WAIT_L(0); PG8_BAR; PG8_MMA(0, 0, At, B0); PG8_MMA(0, 1, At, B1); PG8_BAR; PG8_SCHED;
;             PG8_LDA(At, 0, 1); PG8_STAGE(PG8_SB(0, 0), b2, voffB); PG8_STAGE(PG8_SB(0, 1), b2 + hstep, voffB); PG8_STAGE(PG8_SA(0, 0), a2, voffA);
;             PG8_WAIT_V(8); PG8_WAIT_L(0); PG8_BAR; PG8_MMA(1, 0, At, B0); PG8_MMA(1, 1, At, B1); PG8_BAR; PG8_SCHED;
;             PG8_LDB(B0, 1, 0); PG8_LDB(B1, 1, 1); PG8_SCHED; PG8_LDA(At, 1, 0); PG8_STAGE(PG8_SA(0, 1), a2 + hstep, voffA);
;             PG8_WAIT_V(8); PG8_WAIT_L(0); PG8_BAR; PG8_MMA(0, 0, At, B0); PG8_MMA(0, 1, At, B1); PG8_BAR; PG8_SCHED;
;             PG8_LDA(At, 1, 1); PG8_STAGE(PG8_SB(1, 0), b3, voffB); PG8_STAGE(PG8_SB(1, 1), b3 + hstep, voffB); PG8_STAGE(PG8_SA(1, 0), a3, voffA);
;             PG8_WAIT_V(8); PG8_WAIT_L(0); PG8_BAR; PG8_MMA(1, 0, At, B0); PG8_MMA(1, 1, At, B1); PG8_BAR; PG8_SCHED;
.LBB0_204:
	s_ashr_i32 s21, s20, 31
	s_lshl_b64 s[24:25], s[20:21], 20
	v_readlane_b32 s26, v236, 50
	v_readlane_b32 s27, v236, 51
	s_add_u32 s24, s26, s24
	s_addc_u32 s25, s27, s25
	s_and_b64 s[26:27], s[8:9], exec
	s_cselect_b32 s1, s25, s5
	s_cselect_b32 s3, s24, s4
	s_ashr_i32 s23, s22, 31
	s_lshl_b64 s[26:27], s[22:23], 20
	s_add_u32 s26, s10, s26
	s_addc_u32 s27, s11, s27
	s_and_b64 s[28:29], s[8:9], exec
	s_cselect_b32 s21, s27, s7
	s_cselect_b32 s23, s26, s6
	s_add_u32 s4, s4, 0x80080
	s_addc_u32 s5, s5, 0
	s_add_u32 s33, s6, 0x100
	s_addc_u32 s50, s7, 0
	s_mov_b32 s51, -2
	s_waitcnt vmcnt(0)
	ds_read_b128 v[128:131], v190
	ds_read_b128 v[132:135], v190 offset:1024
	ds_read_b128 v[136:139], v190 offset:2048
	ds_read_b128 v[140:143], v190 offset:3072
	ds_read_b128 v[144:147], v191
	ds_read_b128 v[148:151], v191 offset:1024
	ds_read_b128 v[152:155], v191 offset:2048
	ds_read_b128 v[156:159], v191 offset:3072
	s_add_u32 s6, s4, 0xfff80080
	s_addc_u32 s7, s5, -1
	s_cmp_eq_u32 s51, 28
	s_cselect_b32 s29, s1, s7
	s_cselect_b32 s28, s3, s6
	s_cselect_b32 s7, s21, s50
	s_cselect_b32 s6, s23, s33
	v_lshl_add_u64 v[184:185], s[4:5], 0, v[172:173]
	s_add_i32 m0, s31, 0xc000
	ds_read_b128 v[180:183], v192
	ds_read_b128 v[194:197], v192 offset:1024
	ds_read_b128 v[198:201], v192 offset:2048
	ds_read_b128 v[202:205], v192 offset:3072
	ds_read_b128 v[206:209], v192 offset:4096
	ds_read_b128 v[210:213], v192 offset:5120
	ds_read_b128 v[214:217], v192 offset:6144
	ds_read_b128 v[218:221], v192 offset:7168
	global_load_lds_dwordx4 v[184:185], off
	v_lshl_add_u64 v[184:185], s[4:5], 0, v[174:175]
	s_add_i32 m0, s31, 0xe000
	s_nop 0
	global_load_lds_dwordx4 v[184:185], off
	s_setprio 1
	s_waitcnt vmcnt(8)
	s_waitcnt lgkmcnt(0)
	s_barrier
	v_mfma_f32_16x16x32_bf16 v[124:127], v[128:131], v[180:183], 0
	v_mfma_f32_16x16x32_bf16 v[120:123], v[136:139], v[180:183], 0
	v_mfma_f32_16x16x32_bf16 v[108:111], v[128:131], v[198:201], 0
	v_mfma_f32_16x16x32_bf16 v[104:107], v[136:139], v[198:201], 0
	v_mfma_f32_16x16x32_bf16 v[92:95], v[128:131], v[206:209], 0
	v_mfma_f32_16x16x32_bf16 v[88:91], v[136:139], v[206:209], 0
	v_mfma_f32_16x16x32_bf16 v[76:79], v[128:131], v[214:217], 0
	v_mfma_f32_16x16x32_bf16 v[72:75], v[136:139], v[214:217], 0
	v_mfma_f32_16x16x32_bf16 v[124:127], v[132:135], v[194:197], v[124:127]
	v_mfma_f32_16x16x32_bf16 v[120:123], v[140:143], v[194:197], v[120:123]
	v_mfma_f32_16x16x32_bf16 v[108:111], v[132:135], v[202:205], v[108:111]
	v_mfma_f32_16x16x32_bf16 v[104:107], v[140:143], v[202:205], v[104:107]
	v_mfma_f32_16x16x32_bf16 v[92:95], v[132:135], v[210:213], v[92:95]
	v_mfma_f32_16x16x32_bf16 v[88:91], v[140:143], v[210:213], v[88:91]
	v_mfma_f32_16x16x32_bf16 v[76:79], v[132:135], v[218:221], v[76:79]
	v_mfma_f32_16x16x32_bf16 v[72:75], v[140:143], v[218:221], v[72:75]
	s_setprio 0
	s_setprio 1
	v_mfma_f32_16x16x32_bf16 v[116:119], v[144:147], v[180:183], 0
	v_mfma_f32_16x16x32_bf16 v[112:115], v[152:155], v[180:183], 0
	v_mfma_f32_16x16x32_bf16 v[100:103], v[144:147], v[198:201], 0
	v_mfma_f32_16x16x32_bf16 v[96:99], v[152:155], v[198:201], 0
	v_mfma_f32_16x16x32_bf16 v[84:87], v[144:147], v[206:209], 0
	v_mfma_f32_16x16x32_bf16 v[80:83], v[152:155], v[206:209], 0
	v_mfma_f32_16x16x32_bf16 v[68:71], v[144:147], v[214:217], 0
	v_mfma_f32_16x16x32_bf16 v[64:67], v[152:155], v[214:217], 0
	v_mfma_f32_16x16x32_bf16 v[116:119], v[148:151], v[194:197], v[116:119]
	v_mfma_f32_16x16x32_bf16 v[112:115], v[156:159], v[194:197], v[112:115]
	v_mfma_f32_16x16x32_bf16 v[100:103], v[148:151], v[202:205], v[100:103]
	v_mfma_f32_16x16x32_bf16 v[96:99], v[156:159], v[202:205], v[96:99]
	v_mfma_f32_16x16x32_bf16 v[84:87], v[148:151], v[210:213], v[84:87]
	v_mfma_f32_16x16x32_bf16 v[80:83], v[156:159], v[210:213], v[80:83]
	v_mfma_f32_16x16x32_bf16 v[68:71], v[148:151], v[218:221], v[68:71]
	s_setprio 2
	s_barrier
	v_mfma_f32_16x16x32_bf16 v[64:67], v[156:159], v[218:221], v[64:67]
	s_setprio 0
	s_add_i32 s52, s43, s30
	v_lshl_add_u64 v[184:185], s[6:7], 0, v[164:165]
	s_mov_b32 m0, s52
	ds_read_b128 v[180:183], v192 offset:16384
	ds_read_b128 v[194:197], v192 offset:17408
	ds_read_b128 v[198:201], v192 offset:18432
	ds_read_b128 v[202:205], v192 offset:19456
	ds_read_b128 v[206:209], v192 offset:20480
	ds_read_b128 v[210:213], v192 offset:21504
	ds_read_b128 v[214:217], v192 offset:22528
	ds_read_b128 v[218:221], v192 offset:23552
	global_load_lds_dwordx4 v[184:185], off
	s_add_i32 m0, s52, 0x2000
	s_add_u32 s52, s6, 0x80000
	v_lshl_add_u64 v[222:223], s[6:7], 0, v[168:169]
	s_addc_u32 s53, s7, 0
	s_add_i32 s54, s44, s30
	global_load_lds_dwordx4 v[222:223], off
	v_lshl_add_u64 v[224:225], s[52:53], 0, v[164:165]
	s_mov_b32 m0, s54
	v_lshl_add_u64 v[226:227], s[28:29], 0, v[166:167]
	global_load_lds_dwordx4 v[224:225], off
	v_lshl_add_u64 v[224:225], s[52:53], 0, v[168:169]
	s_add_i32 m0, s54, 0x2000
	s_nop 0
	global_load_lds_dwordx4 v[224:225], off
	v_lshl_add_u64 v[224:225], s[28:29], 0, v[162:163]
	s_mov_b32 m0, s31
	s_nop 0
	global_load_lds_dwordx4 v[224:225], off
	s_mov_b32 m0, s34
	s_nop 0
	global_load_lds_dwordx4 v[226:227], off
	s_setprio 1
	s_waitcnt vmcnt(8)
	s_waitcnt lgkmcnt(0)
	s_barrier
; #define PG8_STAGE(bufoff, gbase, voff) do { _Pragma("unroll") for (int _i = 0; _i < 2; ++_i) \
;         __builtin_amdgcn_global_load_lds((const unsigned*)((const char*)(gbase) + (voff)[_i]), (PG8_LAS unsigned*)(lds + (bufoff) + ldsw + _i * 8192), 16, 0, 0); } while (0)
; #define PG8_LDA(dst, b, h) do { _Pragma("unroll") for (int m = 0; m < 4; ++m) _Pragma("unroll") for (int k = 0; k < 2; ++k) dst[m][k] = *(const PG8_LAS bf16x8*)(lds + PG8_SA(b, h) + aoff + m * 2048 + k * 1024); } while (0)
; #define PG8_LDB(dst, b, h) do { _Pragma("unroll") for (int n = 0; n < 2; ++n) _Pragma("unroll") for (int k = 0; k < 2; ++k) dst[n][k] = *(const PG8_LAS bf16x8*)(lds + PG8_SB(b, h) + boff + n * 2048 + k * 1024); } while (0)
; #define PG8_MMA(ai, bj, At, Bt) do { __builtin_amdgcn_s_setprio(1); _Pragma("unroll") for (int m = 0; m < 4; ++m) _Pragma("unroll") for (int n = 0; n < 2; ++n) _Pragma("unroll") for (int k = 0; k < 2; ++k) \
;         acc[ai][bj][m][n] = __builtin_amdgcn_mfma_f32_16x16x32_bf16(Bt[n][k], At[m][k], acc[ai][bj][m][n], 0, 0, 0); __builtin_amdgcn_s_setprio(0); } while (0)
; #define PG8_WAIT_V(n) asm volatile("s_waitcnt vmcnt(" #n ")" ::: "memory")
; #define PG8_WAIT_L(n) asm volatile("s_waitcnt lgkmcnt(" #n ")" ::: "memory")
; #define PG8_BAR __builtin_amdgcn_s_barrier()
; template <class Epi, class Sched, bool ALIGN_EPI = false, bool SP2 = false>
; __device__ __forceinline__ void gemm_phase(PG8_LAS unsigned char* lds, const Gemm g, const Sched& S, const Epi& E) {
;     ...
;             PG8_WAIT_V(8); PG8_WAIT_L(0); PG8_BAR; PG8_MMA(0, 0, At, B0); PG8_MMA(0, 1, At, B1); PG8_BAR; PG8_SCHED;
;             PG8_LDA(At, 0, 1); PG8_STAGE(PG8_SB(0, 0), b2, voffB); PG8_STAGE(PG8_SB(0, 1), b2 + hstep, voffB); PG8_STAGE(PG8_SA(0, 0), a2, voffA);
;             PG8_WAIT_V(8); PG8_WAIT_L(0); PG8_BAR; PG8_MMA(1, 0, At, B0); PG8_MMA(1, 1, At, B1); PG8_BAR; PG8_SCHED;
;             PG8_LDB(B0, 1, 0); PG8_LDB(B1, 1, 1); PG8_SCHED; PG8_LDA(At, 1, 0); PG8_STAGE(PG8_SA(0, 1), a2 + hstep, voffA);
;             PG8_WAIT_V(8); PG8_WAIT_L(0); PG8_BAR; PG8_MMA(0, 0, At, B0); PG8_MMA(0, 1, At, B1); PG8_BAR; PG8_SCHED;
;             PG8_LDA(At, 1, 1); PG8_STAGE(PG8_SB(1, 0), b3, voffB); PG8_STAGE(PG8_SB(1, 1), b3 + hstep, voffB); PG8_STAGE(PG8_SA(1, 0), a3, voffA);
;             PG8_WAIT_V(8); PG8_WAIT_L(0); PG8_BAR; PG8_MMA(1, 0, At, B0); PG8_MMA(1, 1, At, B1); PG8_BAR; PG8_SCHED;
	v_mfma_f32_16x16x32_bf16 v[60:63], v[128:131], v[180:183], 0
	v_mfma_f32_16x16x32_bf16 v[56:59], v[136:139], v[180:183], 0
	v_mfma_f32_16x16x32_bf16 v[44:47], v[128:131], v[198:201], 0
	v_mfma_f32_16x16x32_bf16 v[40:43], v[136:139], v[198:201], 0
	v_mfma_f32_16x16x32_bf16 v[28:31], v[128:131], v[206:209], 0
	v_mfma_f32_16x16x32_bf16 v[24:27], v[136:139], v[206:209], 0
	v_mfma_f32_16x16x32_bf16 v[12:15], v[128:131], v[214:217], 0
	v_mfma_f32_16x16x32_bf16 v[8:11], v[136:139], v[214:217], 0
	v_mfma_f32_16x16x32_bf16 v[60:63], v[132:135], v[194:197], v[60:63]
	v_mfma_f32_16x16x32_bf16 v[56:59], v[140:143], v[194:197], v[56:59]
	v_mfma_f32_16x16x32_bf16 v[44:47], v[132:135], v[202:205], v[44:47]
	v_mfma_f32_16x16x32_bf16 v[40:43], v[140:143], v[202:205], v[40:43]
	v_mfma_f32_16x16x32_bf16 v[28:31], v[132:135], v[210:213], v[28:31]
	v_mfma_f32_16x16x32_bf16 v[24:27], v[140:143], v[210:213], v[24:27]
	v_mfma_f32_16x16x32_bf16 v[12:15], v[132:135], v[218:221], v[12:15]
	v_mfma_f32_16x16x32_bf16 v[8:11], v[140:143], v[218:221], v[8:11]
	s_setprio 0
	s_setprio 1
	v_mfma_f32_16x16x32_bf16 v[52:55], v[144:147], v[180:183], 0
	v_mfma_f32_16x16x32_bf16 v[48:51], v[152:155], v[180:183], 0
	v_mfma_f32_16x16x32_bf16 v[36:39], v[144:147], v[198:201], 0
	v_mfma_f32_16x16x32_bf16 v[32:35], v[152:155], v[198:201], 0
	v_mfma_f32_16x16x32_bf16 v[20:23], v[144:147], v[206:209], 0
	v_mfma_f32_16x16x32_bf16 v[16:19], v[152:155], v[206:209], 0
	v_mfma_f32_16x16x32_bf16 v[4:7], v[144:147], v[214:217], 0
	v_mfma_f32_16x16x32_bf16 v[0:3], v[152:155], v[214:217], 0
	v_mfma_f32_16x16x32_bf16 v[52:55], v[148:151], v[194:197], v[52:55]
	v_mfma_f32_16x16x32_bf16 v[48:51], v[156:159], v[194:197], v[48:51]
	v_mfma_f32_16x16x32_bf16 v[36:39], v[148:151], v[202:205], v[36:39]
	v_mfma_f32_16x16x32_bf16 v[32:35], v[156:159], v[202:205], v[32:35]
	v_mfma_f32_16x16x32_bf16 v[20:23], v[148:151], v[210:213], v[20:23]
	v_mfma_f32_16x16x32_bf16 v[16:19], v[156:159], v[210:213], v[16:19]
	v_mfma_f32_16x16x32_bf16 v[4:7], v[148:151], v[218:221], v[4:7]
	s_setprio 2
	s_barrier
	v_mfma_f32_16x16x32_bf16 v[0:3], v[156:159], v[218:221], v[0:3]
	s_setprio 0
	s_add_i32 s52, 0, 0x18000
	s_add_i32 s53, 0, 0x1c000
	v_add_u32_e32 v140, s52, v188
	v_add_u32_e32 v156, s53, v188
	ds_read_b128 v[128:131], v140
	ds_read_b128 v[132:135], v140 offset:1024
	ds_read_b128 v[136:139], v140 offset:2048
	ds_read_b128 v[140:143], v140 offset:3072
	ds_read_b128 v[144:147], v156
	ds_read_b128 v[148:151], v156 offset:1024
	ds_read_b128 v[152:155], v156 offset:2048
	ds_read_b128 v[156:159], v156 offset:3072
	s_add_u32 s28, s28, 0x80000
	s_addc_u32 s29, s29, 0
	s_mov_b32 m0, s35
	v_lshl_add_u64 v[228:229], s[28:29], 0, v[162:163]
	ds_read_b128 v[180:183], v192 offset:32768
	ds_read_b128 v[194:197], v192 offset:33792
	ds_read_b128 v[198:201], v192 offset:34816
	ds_read_b128 v[202:205], v192 offset:35840
	ds_read_b128 v[206:209], v192 offset:36864
	ds_read_b128 v[210:213], v192 offset:37888
	ds_read_b128 v[214:217], v192 offset:38912
	ds_read_b128 v[218:221], v192 offset:39936
	global_load_lds_dwordx4 v[228:229], off
	v_lshl_add_u64 v[228:229], s[28:29], 0, v[166:167]
	s_mov_b32 m0, s36
	s_nop 0
	global_load_lds_dwordx4 v[228:229], off
	s_setprio 1
	s_waitcnt vmcnt(8)
	s_waitcnt lgkmcnt(0)
	s_barrier
	v_mfma_f32_16x16x32_bf16 v[124:127], v[128:131], v[180:183], v[124:127]
	v_mfma_f32_16x16x32_bf16 v[120:123], v[136:139], v[180:183], v[120:123]
	v_mfma_f32_16x16x32_bf16 v[108:111], v[128:131], v[198:201], v[108:111]
	v_mfma_f32_16x16x32_bf16 v[104:107], v[136:139], v[198:201], v[104:107]
	v_mfma_f32_16x16x32_bf16 v[92:95], v[128:131], v[206:209], v[92:95]
	v_mfma_f32_16x16x32_bf16 v[88:91], v[136:139], v[206:209], v[88:91]
	v_mfma_f32_16x16x32_bf16 v[76:79], v[128:131], v[214:217], v[76:79]
	v_mfma_f32_16x16x32_bf16 v[72:75], v[136:139], v[214:217], v[72:75]
	v_mfma_f32_16x16x32_bf16 v[124:127], v[132:135], v[194:197], v[124:127]
	v_mfma_f32_16x16x32_bf16 v[120:123], v[140:143], v[194:197], v[120:123]
	v_mfma_f32_16x16x32_bf16 v[108:111], v[132:135], v[202:205], v[108:111]
	v_mfma_f32_16x16x32_bf16 v[104:107], v[140:143], v[202:205], v[104:107]
	v_mfma_f32_16x16x32_bf16 v[92:95], v[132:135], v[210:213], v[92:95]
	v_mfma_f32_16x16x32_bf16 v[88:91], v[140:143], v[210:213], v[88:91]
	v_mfma_f32_16x16x32_bf16 v[76:79], v[132:135], v[218:221], v[76:79]
	v_mfma_f32_16x16x32_bf16 v[72:75], v[140:143], v[218:221], v[72:75]
	s_setprio 0
	s_setprio 1
	v_mfma_f32_16x16x32_bf16 v[116:119], v[144:147], v[180:183], v[116:119]
	v_mfma_f32_16x16x32_bf16 v[112:115], v[152:155], v[180:183], v[112:115]
	v_mfma_f32_16x16x32_bf16 v[100:103], v[144:147], v[198:201], v[100:103]
	v_mfma_f32_16x16x32_bf16 v[96:99], v[152:155], v[198:201], v[96:99]
	v_mfma_f32_16x16x32_bf16 v[84:87], v[144:147], v[206:209], v[84:87]
	v_mfma_f32_16x16x32_bf16 v[80:83], v[152:155], v[206:209], v[80:83]
	v_mfma_f32_16x16x32_bf16 v[68:71], v[144:147], v[214:217], v[68:71]
	v_mfma_f32_16x16x32_bf16 v[64:67], v[152:155], v[214:217], v[64:67]
	v_mfma_f32_16x16x32_bf16 v[116:119], v[148:151], v[194:197], v[116:119]
	v_mfma_f32_16x16x32_bf16 v[112:115], v[156:159], v[194:197], v[112:115]
	v_mfma_f32_16x16x32_bf16 v[100:103], v[148:151], v[202:205], v[100:103]
	v_mfma_f32_16x16x32_bf16 v[96:99], v[156:159], v[202:205], v[96:99]
	v_mfma_f32_16x16x32_bf16 v[84:87], v[148:151], v[210:213], v[84:87]
	v_mfma_f32_16x16x32_bf16 v[80:83], v[156:159], v[210:213], v[80:83]
	v_mfma_f32_16x16x32_bf16 v[68:71], v[148:151], v[218:221], v[68:71]
	s_setprio 2
	s_barrier
; #define PG8_STAGE(bufoff, gbase, voff) do { _Pragma("unroll") for (int _i = 0; _i < 2; ++_i) \
;         __builtin_amdgcn_global_load_lds((const unsigned*)((const char*)(gbase) + (voff)[_i]), (PG8_LAS unsigned*)(lds + (bufoff) + ldsw + _i * 8192), 16, 0, 0); } while (0)
; #define PG8_LDA(dst, b, h) do { _Pragma("unroll") for (int m = 0; m < 4; ++m) _Pragma("unroll") for (int k = 0; k < 2; ++k) dst[m][k] = *(const PG8_LAS bf16x8*)(lds + PG8_SA(b, h) + aoff + m * 2048 + k * 1024); } while (0)
; #define PG8_LDB(dst, b, h) do { _Pragma("unroll") for (int n = 0; n < 2; ++n) _Pragma("unroll") for (int k = 0; k < 2; ++k) dst[n][k] = *(const PG8_LAS bf16x8*)(lds + PG8_SB(b, h) + boff + n * 2048 + k * 1024); } while (0)
; #define PG8_MMA(ai, bj, At, Bt) do { __builtin_amdgcn_s_setprio(1); _Pragma("unroll") for (int m = 0; m < 4; ++m) _Pragma("unroll") for (int n = 0; n < 2; ++n) _Pragma("unroll") for (int k = 0; k < 2; ++k) \
;         acc[ai][bj][m][n] = __builtin_amdgcn_mfma_f32_16x16x32_bf16(Bt[n][k], At[m][k], acc[ai][bj][m][n], 0, 0, 0); __builtin_amdgcn_s_setprio(0); } while (0)
; #define PG8_WAIT_V(n) asm volatile("s_waitcnt vmcnt(" #n ")" ::: "memory")
; #define PG8_WAIT_L(n) asm volatile("s_waitcnt lgkmcnt(" #n ")" ::: "memory")
; #define PG8_BAR __builtin_amdgcn_s_barrier()
; template <class Epi, class Sched, bool ALIGN_EPI = false, bool SP2 = false>
; __device__ __forceinline__ void gemm_phase(PG8_LAS unsigned char* lds, const Gemm g, const Sched& S, const Epi& E) {
;     ...
;             PG8_WAIT_V(8); PG8_WAIT_L(0); PG8_BAR; PG8_MMA(0, 0, At, B0); PG8_MMA(0, 1, At, B1); PG8_BAR; PG8_SCHED;
;             PG8_LDA(At, 0, 1); PG8_STAGE(PG8_SB(0, 0), b2, voffB); PG8_STAGE(PG8_SB(0, 1), b2 + hstep, voffB); PG8_STAGE(PG8_SA(0, 0), a2, voffA);
;             PG8_WAIT_V(8); PG8_WAIT_L(0); PG8_BAR; PG8_MMA(1, 0, At, B0); PG8_MMA(1, 1, At, B1); PG8_BAR; PG8_SCHED;
;             PG8_LDB(B0, 1, 0); PG8_LDB(B1, 1, 1); PG8_SCHED; PG8_LDA(At, 1, 0); PG8_STAGE(PG8_SA(0, 1), a2 + hstep, voffA);
;             PG8_WAIT_V(8); PG8_WAIT_L(0); PG8_BAR; PG8_MMA(0, 0, At, B0); PG8_MMA(0, 1, At, B1); PG8_BAR; PG8_SCHED;
;             PG8_LDA(At, 1, 1); PG8_STAGE(PG8_SB(1, 0), b3, voffB); PG8_STAGE(PG8_SB(1, 1), b3 + hstep, voffB); PG8_STAGE(PG8_SA(1, 0), a3, voffA);
;             PG8_WAIT_V(8); PG8_WAIT_L(0); PG8_BAR; PG8_MMA(1, 0, At, B0); PG8_MMA(1, 1, At, B1); PG8_BAR; PG8_SCHED;
	v_mfma_f32_16x16x32_bf16 v[64:67], v[156:159], v[218:221], v[64:67]
	s_setprio 0
	s_add_i32 s28, s52, s30
	v_lshl_add_u64 v[184:185], v[184:185], 0, s[16:17]
	s_mov_b32 m0, s28
	ds_read_b128 v[180:183], v192 offset:49152
	ds_read_b128 v[194:197], v192 offset:50176
	ds_read_b128 v[198:201], v192 offset:51200
	ds_read_b128 v[202:205], v192 offset:52224
	ds_read_b128 v[206:209], v192 offset:53248
	ds_read_b128 v[210:213], v192 offset:54272
	ds_read_b128 v[214:217], v192 offset:55296
	ds_read_b128 v[218:221], v192 offset:56320
	global_load_lds_dwordx4 v[184:185], off
	s_add_i32 m0, s28, 0x2000
	s_add_u32 s6, s6, 0x80080
	v_lshl_add_u64 v[184:185], v[222:223], 0, s[16:17]
	s_addc_u32 s7, s7, 0
	s_add_i32 s28, s53, s30
	global_load_lds_dwordx4 v[184:185], off
	v_lshl_add_u64 v[184:185], s[6:7], 0, v[164:165]
	s_mov_b32 m0, s28
	s_nop 0
	global_load_lds_dwordx4 v[184:185], off
	v_lshl_add_u64 v[184:185], s[6:7], 0, v[168:169]
	s_add_i32 m0, s28, 0x2000
	s_nop 0
	global_load_lds_dwordx4 v[184:185], off
	v_lshl_add_u64 v[184:185], v[224:225], 0, s[16:17]
	s_mov_b32 m0, s38
	s_nop 0
	global_load_lds_dwordx4 v[184:185], off
	v_lshl_add_u64 v[184:185], v[226:227], 0, s[16:17]
	s_mov_b32 m0, s39
	s_nop 0
	global_load_lds_dwordx4 v[184:185], off
	s_setprio 1
	s_waitcnt vmcnt(8)
	s_waitcnt lgkmcnt(0)
	s_barrier
	v_mfma_f32_16x16x32_bf16 v[60:63], v[128:131], v[180:183], v[60:63]
	v_mfma_f32_16x16x32_bf16 v[56:59], v[136:139], v[180:183], v[56:59]
	v_mfma_f32_16x16x32_bf16 v[44:47], v[128:131], v[198:201], v[44:47]
	v_mfma_f32_16x16x32_bf16 v[40:43], v[136:139], v[198:201], v[40:43]
	v_mfma_f32_16x16x32_bf16 v[28:31], v[128:131], v[206:209], v[28:31]
	v_mfma_f32_16x16x32_bf16 v[24:27], v[136:139], v[206:209], v[24:27]
	v_mfma_f32_16x16x32_bf16 v[12:15], v[128:131], v[214:217], v[12:15]
	v_mfma_f32_16x16x32_bf16 v[8:11], v[136:139], v[214:217], v[8:11]
	v_mfma_f32_16x16x32_bf16 v[60:63], v[132:135], v[194:197], v[60:63]
	v_mfma_f32_16x16x32_bf16 v[56:59], v[140:143], v[194:197], v[56:59]
	v_mfma_f32_16x16x32_bf16 v[44:47], v[132:135], v[202:205], v[44:47]
	v_mfma_f32_16x16x32_bf16 v[40:43], v[140:143], v[202:205], v[40:43]
	v_mfma_f32_16x16x32_bf16 v[28:31], v[132:135], v[210:213], v[28:31]
	v_mfma_f32_16x16x32_bf16 v[24:27], v[140:143], v[210:213], v[24:27]
	v_mfma_f32_16x16x32_bf16 v[12:15], v[132:135], v[218:221], v[12:15]
	v_mfma_f32_16x16x32_bf16 v[8:11], v[140:143], v[218:221], v[8:11]
	s_setprio 0
	s_setprio 1
	v_mfma_f32_16x16x32_bf16 v[52:55], v[144:147], v[180:183], v[52:55]
	v_mfma_f32_16x16x32_bf16 v[48:51], v[152:155], v[180:183], v[48:51]
	v_mfma_f32_16x16x32_bf16 v[36:39], v[144:147], v[198:201], v[36:39]
	v_mfma_f32_16x16x32_bf16 v[32:35], v[152:155], v[198:201], v[32:35]
	v_mfma_f32_16x16x32_bf16 v[20:23], v[144:147], v[206:209], v[20:23]
	v_mfma_f32_16x16x32_bf16 v[16:19], v[152:155], v[206:209], v[16:19]
	v_mfma_f32_16x16x32_bf16 v[4:7], v[144:147], v[214:217], v[4:7]
	v_mfma_f32_16x16x32_bf16 v[0:3], v[152:155], v[214:217], v[0:3]
	v_mfma_f32_16x16x32_bf16 v[52:55], v[148:151], v[194:197], v[52:55]
	v_mfma_f32_16x16x32_bf16 v[48:51], v[156:159], v[194:197], v[48:51]
	v_mfma_f32_16x16x32_bf16 v[36:39], v[148:151], v[202:205], v[36:39]
	v_mfma_f32_16x16x32_bf16 v[32:35], v[156:159], v[202:205], v[32:35]
	v_mfma_f32_16x16x32_bf16 v[20:23], v[148:151], v[210:213], v[20:23]
	v_mfma_f32_16x16x32_bf16 v[16:19], v[156:159], v[210:213], v[16:19]
	v_mfma_f32_16x16x32_bf16 v[4:7], v[148:151], v[218:221], v[4:7]
	s_setprio 2
	s_barrier
	v_mfma_f32_16x16x32_bf16 v[0:3], v[156:159], v[218:221], v[0:3]
	s_setprio 0
	s_add_i32 s51, s51, 2
	s_add_u32 s4, s4, 0x100
	s_addc_u32 s5, s5, 0
	s_add_u32 s33, s33, 0x100
	s_addc_u32 s50, s50, 0
	s_cmp_gt_u32 s51, 29
.LBB0_205:
	ds_read_b128 v[128:131], v190
	ds_read_b128 v[132:135], v190 offset:1024
	ds_read_b128 v[136:139], v190 offset:2048
	ds_read_b128 v[140:143], v190 offset:3072
	ds_read_b128 v[144:147], v191
	ds_read_b128 v[148:151], v191 offset:1024
	ds_read_b128 v[152:155], v191 offset:2048
	ds_read_b128 v[156:159], v191 offset:3072
	s_add_u32 s6, s4, 0xfff80080
	s_addc_u32 s7, s5, -1
	s_cmp_eq_u32 s51, 28
	s_cselect_b32 s29, s1, s7
	s_cselect_b32 s28, s3, s6
	s_cselect_b32 s7, s21, s50
	s_cselect_b32 s6, s23, s33
	v_lshl_add_u64 v[184:185], s[4:5], 0, v[172:173]
	s_add_i32 m0, s31, 0xc000
	ds_read_b128 v[180:183], v192
	ds_read_b128 v[194:197], v192 offset:1024
	ds_read_b128 v[198:201], v192 offset:2048
	ds_read_b128 v[202:205], v192 offset:3072
	ds_read_b128 v[206:209], v192 offset:4096
	ds_read_b128 v[210:213], v192 offset:5120
	ds_read_b128 v[214:217], v192 offset:6144
	ds_read_b128 v[218:221], v192 offset:7168
	global_load_lds_dwordx4 v[184:185], off
	v_lshl_add_u64 v[184:185], s[4:5], 0, v[174:175]
	s_add_i32 m0, s31, 0xe000
	s_nop 0
	global_load_lds_dwordx4 v[184:185], off
	s_setprio 1
	s_waitcnt vmcnt(8)
	s_waitcnt lgkmcnt(0)
	s_barrier
; #define PG8_STAGE(bufoff, gbase, voff) do { _Pragma("unroll") for (int _i = 0; _i < 2; ++_i) \
;         __builtin_amdgcn_global_load_lds((const unsigned*)((const char*)(gbase) + (voff)[_i]), (PG8_LAS unsigned*)(lds + (bufoff) + ldsw + _i * 8192), 16, 0, 0); } while (0)
; #define PG8_LDA(dst, b, h) do { _Pragma("unroll") for (int m = 0; m < 4; ++m) _Pragma("unroll") for (int k = 0; k < 2; ++k) dst[m][k] = *(const PG8_LAS bf16x8*)(lds + PG8_SA(b, h) + aoff + m * 2048 + k * 1024); } while (0)
; #define PG8_LDB(dst, b, h) do { _Pragma("unroll") for (int n = 0; n < 2; ++n) _Pragma("unroll") for (int k = 0; k < 2; ++k) dst[n][k] = *(const PG8_LAS bf16x8*)(lds + PG8_SB(b, h) + boff + n * 2048 + k * 1024); } while (0)
; #define PG8_MMA(ai, bj, At, Bt) do { __builtin_amdgcn_s_setprio(1); _Pragma("unroll") for (int m = 0; m < 4; ++m) _Pragma("unroll") for (int n = 0; n < 2; ++n) _Pragma("unroll") for (int k = 0; k < 2; ++k) \
;         acc[ai][bj][m][n] = __builtin_amdgcn_mfma_f32_16x16x32_bf16(Bt[n][k], At[m][k], acc[ai][bj][m][n], 0, 0, 0); __builtin_amdgcn_s_setprio(0); } while (0)
; #define PG8_WAIT_V(n) asm volatile("s_waitcnt vmcnt(" #n ")" ::: "memory")
; #define PG8_WAIT_L(n) asm volatile("s_waitcnt lgkmcnt(" #n ")" ::: "memory")
; #define PG8_BAR __builtin_amdgcn_s_barrier()
; template <class Epi, class Sched, bool ALIGN_EPI = false, bool SP2 = false>
; __device__ __forceinline__ void gemm_phase(PG8_LAS unsigned char* lds, const Gemm g, const Sched& S, const Epi& E) {
;     ...
;             PG8_WAIT_V(8); PG8_WAIT_L(0); PG8_BAR; PG8_MMA(0, 0, At, B0); PG8_MMA(0, 1, At, B1); PG8_BAR; PG8_SCHED;
;             PG8_LDA(At, 0, 1); PG8_STAGE(PG8_SB(0, 0), b2, voffB); PG8_STAGE(PG8_SB(0, 1), b2 + hstep, voffB); PG8_STAGE(PG8_SA(0, 0), a2, voffA);
;             PG8_WAIT_V(8); PG8_WAIT_L(0); PG8_BAR; PG8_MMA(1, 0, At, B0); PG8_MMA(1, 1, At, B1); PG8_BAR; PG8_SCHED;
;             PG8_LDB(B0, 1, 0); PG8_LDB(B1, 1, 1); PG8_SCHED; PG8_LDA(At, 1, 0); PG8_STAGE(PG8_SA(0, 1), a2 + hstep, voffA);
;             PG8_WAIT_V(8); PG8_WAIT_L(0); PG8_BAR; PG8_MMA(0, 0, At, B0); PG8_MMA(0, 1, At, B1); PG8_BAR; PG8_SCHED;
;             PG8_LDA(At, 1, 1); PG8_STAGE(PG8_SB(1, 0), b3, voffB); PG8_STAGE(PG8_SB(1, 1), b3 + hstep, voffB); PG8_STAGE(PG8_SA(1, 0), a3, voffA);
;             PG8_WAIT_V(8); PG8_WAIT_L(0); PG8_BAR; PG8_MMA(1, 0, At, B0); PG8_MMA(1, 1, At, B1); PG8_BAR; PG8_SCHED;
	v_mfma_f32_16x16x32_bf16 v[124:127], v[128:131], v[180:183], v[124:127]
	v_mfma_f32_16x16x32_bf16 v[120:123], v[136:139], v[180:183], v[120:123]
	v_mfma_f32_16x16x32_bf16 v[108:111], v[128:131], v[198:201], v[108:111]
	v_mfma_f32_16x16x32_bf16 v[104:107], v[136:139], v[198:201], v[104:107]
	v_mfma_f32_16x16x32_bf16 v[92:95], v[128:131], v[206:209], v[92:95]
	v_mfma_f32_16x16x32_bf16 v[88:91], v[136:139], v[206:209], v[88:91]
	v_mfma_f32_16x16x32_bf16 v[76:79], v[128:131], v[214:217], v[76:79]
	v_mfma_f32_16x16x32_bf16 v[72:75], v[136:139], v[214:217], v[72:75]
	v_mfma_f32_16x16x32_bf16 v[124:127], v[132:135], v[194:197], v[124:127]
	v_mfma_f32_16x16x32_bf16 v[120:123], v[140:143], v[194:197], v[120:123]
	v_mfma_f32_16x16x32_bf16 v[108:111], v[132:135], v[202:205], v[108:111]
	v_mfma_f32_16x16x32_bf16 v[104:107], v[140:143], v[202:205], v[104:107]
	v_mfma_f32_16x16x32_bf16 v[92:95], v[132:135], v[210:213], v[92:95]
	v_mfma_f32_16x16x32_bf16 v[88:91], v[140:143], v[210:213], v[88:91]
	v_mfma_f32_16x16x32_bf16 v[76:79], v[132:135], v[218:221], v[76:79]
	v_mfma_f32_16x16x32_bf16 v[72:75], v[140:143], v[218:221], v[72:75]
	s_setprio 0
	s_setprio 1
	v_mfma_f32_16x16x32_bf16 v[116:119], v[144:147], v[180:183], v[116:119]
	v_mfma_f32_16x16x32_bf16 v[112:115], v[152:155], v[180:183], v[112:115]
	v_mfma_f32_16x16x32_bf16 v[100:103], v[144:147], v[198:201], v[100:103]
	v_mfma_f32_16x16x32_bf16 v[96:99], v[152:155], v[198:201], v[96:99]
	v_mfma_f32_16x16x32_bf16 v[84:87], v[144:147], v[206:209], v[84:87]
	v_mfma_f32_16x16x32_bf16 v[80:83], v[152:155], v[206:209], v[80:83]
	v_mfma_f32_16x16x32_bf16 v[68:71], v[144:147], v[214:217], v[68:71]
	v_mfma_f32_16x16x32_bf16 v[64:67], v[152:155], v[214:217], v[64:67]
	v_mfma_f32_16x16x32_bf16 v[116:119], v[148:151], v[194:197], v[116:119]
	v_mfma_f32_16x16x32_bf16 v[112:115], v[156:159], v[194:197], v[112:115]
	v_mfma_f32_16x16x32_bf16 v[100:103], v[148:151], v[202:205], v[100:103]
	v_mfma_f32_16x16x32_bf16 v[96:99], v[156:159], v[202:205], v[96:99]
	v_mfma_f32_16x16x32_bf16 v[84:87], v[148:151], v[210:213], v[84:87]
	v_mfma_f32_16x16x32_bf16 v[80:83], v[156:159], v[210:213], v[80:83]
	v_mfma_f32_16x16x32_bf16 v[68:71], v[148:151], v[218:221], v[68:71]
	s_setprio 2
	s_barrier
	v_mfma_f32_16x16x32_bf16 v[64:67], v[156:159], v[218:221], v[64:67]
	s_setprio 0
	s_add_i32 s52, s43, s30
	v_lshl_add_u64 v[184:185], s[6:7], 0, v[164:165]
	s_mov_b32 m0, s52
	ds_read_b128 v[180:183], v192 offset:16384
	ds_read_b128 v[194:197], v192 offset:17408
	ds_read_b128 v[198:201], v192 offset:18432
	ds_read_b128 v[202:205], v192 offset:19456
	ds_read_b128 v[206:209], v192 offset:20480
	ds_read_b128 v[210:213], v192 offset:21504
	ds_read_b128 v[214:217], v192 offset:22528
	ds_read_b128 v[218:221], v192 offset:23552
	global_load_lds_dwordx4 v[184:185], off
	s_add_i32 m0, s52, 0x2000
	s_add_u32 s52, s6, 0x80000
	v_lshl_add_u64 v[222:223], s[6:7], 0, v[168:169]
	s_addc_u32 s53, s7, 0
	s_add_i32 s54, s44, s30
	global_load_lds_dwordx4 v[222:223], off
	v_lshl_add_u64 v[224:225], s[52:53], 0, v[164:165]
	s_mov_b32 m0, s54
	v_lshl_add_u64 v[226:227], s[28:29], 0, v[166:167]
	global_load_lds_dwordx4 v[224:225], off
	v_lshl_add_u64 v[224:225], s[52:53], 0, v[168:169]
	s_add_i32 m0, s54, 0x2000
	s_nop 0
	global_load_lds_dwordx4 v[224:225], off
	v_lshl_add_u64 v[224:225], s[28:29], 0, v[162:163]
	s_mov_b32 m0, s31
	s_nop 0
	global_load_lds_dwordx4 v[224:225], off
	s_mov_b32 m0, s34
	s_nop 0
	global_load_lds_dwordx4 v[226:227], off
	s_setprio 1
	s_waitcnt vmcnt(8)
	s_waitcnt lgkmcnt(0)
	s_barrier
	v_mfma_f32_16x16x32_bf16 v[60:63], v[128:131], v[180:183], v[60:63]
	v_mfma_f32_16x16x32_bf16 v[56:59], v[136:139], v[180:183], v[56:59]
	v_mfma_f32_16x16x32_bf16 v[44:47], v[128:131], v[198:201], v[44:47]
	v_mfma_f32_16x16x32_bf16 v[40:43], v[136:139], v[198:201], v[40:43]
	v_mfma_f32_16x16x32_bf16 v[28:31], v[128:131], v[206:209], v[28:31]
	v_mfma_f32_16x16x32_bf16 v[24:27], v[136:139], v[206:209], v[24:27]
	v_mfma_f32_16x16x32_bf16 v[12:15], v[128:131], v[214:217], v[12:15]
	v_mfma_f32_16x16x32_bf16 v[8:11], v[136:139], v[214:217], v[8:11]
	v_mfma_f32_16x16x32_bf16 v[60:63], v[132:135], v[194:197], v[60:63]
	v_mfma_f32_16x16x32_bf16 v[56:59], v[140:143], v[194:197], v[56:59]
	v_mfma_f32_16x16x32_bf16 v[44:47], v[132:135], v[202:205], v[44:47]
	v_mfma_f32_16x16x32_bf16 v[40:43], v[140:143], v[202:205], v[40:43]
	v_mfma_f32_16x16x32_bf16 v[28:31], v[132:135], v[210:213], v[28:31]
	v_mfma_f32_16x16x32_bf16 v[24:27], v[140:143], v[210:213], v[24:27]
	v_mfma_f32_16x16x32_bf16 v[12:15], v[132:135], v[218:221], v[12:15]
	v_mfma_f32_16x16x32_bf16 v[8:11], v[140:143], v[218:221], v[8:11]
	s_setprio 0
	s_setprio 1
	v_mfma_f32_16x16x32_bf16 v[52:55], v[144:147], v[180:183], v[52:55]
	v_mfma_f32_16x16x32_bf16 v[48:51], v[152:155], v[180:183], v[48:51]
	v_mfma_f32_16x16x32_bf16 v[36:39], v[144:147], v[198:201], v[36:39]
	v_mfma_f32_16x16x32_bf16 v[32:35], v[152:155], v[198:201], v[32:35]
	v_mfma_f32_16x16x32_bf16 v[20:23], v[144:147], v[206:209], v[20:23]
	v_mfma_f32_16x16x32_bf16 v[16:19], v[152:155], v[206:209], v[16:19]
	v_mfma_f32_16x16x32_bf16 v[4:7], v[144:147], v[214:217], v[4:7]
	v_mfma_f32_16x16x32_bf16 v[0:3], v[152:155], v[214:217], v[0:3]
	v_mfma_f32_16x16x32_bf16 v[52:55], v[148:151], v[194:197], v[52:55]
	v_mfma_f32_16x16x32_bf16 v[48:51], v[156:159], v[194:197], v[48:51]
	v_mfma_f32_16x16x32_bf16 v[36:39], v[148:151], v[202:205], v[36:39]
	v_mfma_f32_16x16x32_bf16 v[32:35], v[156:159], v[202:205], v[32:35]
	v_mfma_f32_16x16x32_bf16 v[20:23], v[148:151], v[210:213], v[20:23]
	v_mfma_f32_16x16x32_bf16 v[16:19], v[156:159], v[210:213], v[16:19]
	v_mfma_f32_16x16x32_bf16 v[4:7], v[148:151], v[218:221], v[4:7]
	s_setprio 2
	s_barrier
; #define PG8_STAGE(bufoff, gbase, voff) do { _Pragma("unroll") for (int _i = 0; _i < 2; ++_i) \
;         __builtin_amdgcn_global_load_lds((const unsigned*)((const char*)(gbase) + (voff)[_i]), (PG8_LAS unsigned*)(lds + (bufoff) + ldsw + _i * 8192), 16, 0, 0); } while (0)
; #define PG8_LDA(dst, b, h) do { _Pragma("unroll") for (int m = 0; m < 4; ++m) _Pragma("unroll") for (int k = 0; k < 2; ++k) dst[m][k] = *(const PG8_LAS bf16x8*)(lds + PG8_SA(b, h) + aoff + m * 2048 + k * 1024); } while (0)
; #define PG8_LDB(dst, b, h) do { _Pragma("unroll") for (int n = 0; n < 2; ++n) _Pragma("unroll") for (int k = 0; k < 2; ++k) dst[n][k] = *(const PG8_LAS bf16x8*)(lds + PG8_SB(b, h) + boff + n * 2048 + k * 1024); } while (0)
; #define PG8_MMA(ai, bj, At, Bt) do { __builtin_amdgcn_s_setprio(1); _Pragma("unroll") for (int m = 0; m < 4; ++m) _Pragma("unroll") for (int n = 0; n < 2; ++n) _Pragma("unroll") for (int k = 0; k < 2; ++k) \
;         acc[ai][bj][m][n] = __builtin_amdgcn_mfma_f32_16x16x32_bf16(Bt[n][k], At[m][k], acc[ai][bj][m][n], 0, 0, 0); __builtin_amdgcn_s_setprio(0); } while (0)
; #define PG8_WAIT_V(n) asm volatile("s_waitcnt vmcnt(" #n ")" ::: "memory")
; #define PG8_WAIT_L(n) asm volatile("s_waitcnt lgkmcnt(" #n ")" ::: "memory")
; #define PG8_BAR __builtin_amdgcn_s_barrier()
; template <class Epi, class Sched, bool ALIGN_EPI = false, bool SP2 = false>
; __device__ __forceinline__ void gemm_phase(PG8_LAS unsigned char* lds, const Gemm g, const Sched& S, const Epi& E) {
;     ...
;             PG8_WAIT_V(8); PG8_WAIT_L(0); PG8_BAR; PG8_MMA(0, 0, At, B0); PG8_MMA(0, 1, At, B1); PG8_BAR; PG8_SCHED;
;             PG8_LDA(At, 0, 1); PG8_STAGE(PG8_SB(0, 0), b2, voffB); PG8_STAGE(PG8_SB(0, 1), b2 + hstep, voffB); PG8_STAGE(PG8_SA(0, 0), a2, voffA);
;             PG8_WAIT_V(8); PG8_WAIT_L(0); PG8_BAR; PG8_MMA(1, 0, At, B0); PG8_MMA(1, 1, At, B1); PG8_BAR; PG8_SCHED;
;             PG8_LDB(B0, 1, 0); PG8_LDB(B1, 1, 1); PG8_SCHED; PG8_LDA(At, 1, 0); PG8_STAGE(PG8_SA(0, 1), a2 + hstep, voffA);
;             PG8_WAIT_V(8); PG8_WAIT_L(0); PG8_BAR; PG8_MMA(0, 0, At, B0); PG8_MMA(0, 1, At, B1); PG8_BAR; PG8_SCHED;
;             PG8_LDA(At, 1, 1); PG8_STAGE(PG8_SB(1, 0), b3, voffB); PG8_STAGE(PG8_SB(1, 1), b3 + hstep, voffB); PG8_STAGE(PG8_SA(1, 0), a3, voffA);
;             PG8_WAIT_V(8); PG8_WAIT_L(0); PG8_BAR; PG8_MMA(1, 0, At, B0); PG8_MMA(1, 1, At, B1); PG8_BAR; PG8_SCHED;
	v_mfma_f32_16x16x32_bf16 v[0:3], v[156:159], v[218:221], v[0:3]
	s_setprio 0
	s_add_i32 s52, 0, 0x18000
	s_add_i32 s53, 0, 0x1c000
	v_add_u32_e32 v140, s52, v188
	v_add_u32_e32 v156, s53, v188
	ds_read_b128 v[128:131], v140
	ds_read_b128 v[132:135], v140 offset:1024
	ds_read_b128 v[136:139], v140 offset:2048
	ds_read_b128 v[140:143], v140 offset:3072
	ds_read_b128 v[144:147], v156
	ds_read_b128 v[148:151], v156 offset:1024
	ds_read_b128 v[152:155], v156 offset:2048
	ds_read_b128 v[156:159], v156 offset:3072
	s_add_u32 s28, s28, 0x80000
	s_addc_u32 s29, s29, 0
	s_mov_b32 m0, s35
	v_lshl_add_u64 v[228:229], s[28:29], 0, v[162:163]
	ds_read_b128 v[180:183], v192 offset:32768
	ds_read_b128 v[194:197], v192 offset:33792
	ds_read_b128 v[198:201], v192 offset:34816
	ds_read_b128 v[202:205], v192 offset:35840
	ds_read_b128 v[206:209], v192 offset:36864
	ds_read_b128 v[210:213], v192 offset:37888
	ds_read_b128 v[214:217], v192 offset:38912
	ds_read_b128 v[218:221], v192 offset:39936
	global_load_lds_dwordx4 v[228:229], off
	v_lshl_add_u64 v[228:229], s[28:29], 0, v[166:167]
	s_mov_b32 m0, s36
	s_nop 0
	global_load_lds_dwordx4 v[228:229], off
	s_setprio 1
	s_waitcnt vmcnt(8)
	s_waitcnt lgkmcnt(0)
	s_barrier
	v_mfma_f32_16x16x32_bf16 v[124:127], v[128:131], v[180:183], v[124:127]
	v_mfma_f32_16x16x32_bf16 v[120:123], v[136:139], v[180:183], v[120:123]
	v_mfma_f32_16x16x32_bf16 v[108:111], v[128:131], v[198:201], v[108:111]
	v_mfma_f32_16x16x32_bf16 v[104:107], v[136:139], v[198:201], v[104:107]
	v_mfma_f32_16x16x32_bf16 v[92:95], v[128:131], v[206:209], v[92:95]
	v_mfma_f32_16x16x32_bf16 v[88:91], v[136:139], v[206:209], v[88:91]
	v_mfma_f32_16x16x32_bf16 v[76:79], v[128:131], v[214:217], v[76:79]
	v_mfma_f32_16x16x32_bf16 v[72:75], v[136:139], v[214:217], v[72:75]
	v_mfma_f32_16x16x32_bf16 v[124:127], v[132:135], v[194:197], v[124:127]
	v_mfma_f32_16x16x32_bf16 v[120:123], v[140:143], v[194:197], v[120:123]
	v_mfma_f32_16x16x32_bf16 v[108:111], v[132:135], v[202:205], v[108:111]
	v_mfma_f32_16x16x32_bf16 v[104:107], v[140:143], v[202:205], v[104:107]
	v_mfma_f32_16x16x32_bf16 v[92:95], v[132:135], v[210:213], v[92:95]
	v_mfma_f32_16x16x32_bf16 v[88:91], v[140:143], v[210:213], v[88:91]
	v_mfma_f32_16x16x32_bf16 v[76:79], v[132:135], v[218:221], v[76:79]
	v_mfma_f32_16x16x32_bf16 v[72:75], v[140:143], v[218:221], v[72:75]
	s_setprio 0
	s_setprio 1
	v_mfma_f32_16x16x32_bf16 v[116:119], v[144:147], v[180:183], v[116:119]
	v_mfma_f32_16x16x32_bf16 v[112:115], v[152:155], v[180:183], v[112:115]
	v_mfma_f32_16x16x32_bf16 v[100:103], v[144:147], v[198:201], v[100:103]
	v_mfma_f32_16x16x32_bf16 v[96:99], v[152:155], v[198:201], v[96:99]
	v_mfma_f32_16x16x32_bf16 v[84:87], v[144:147], v[206:209], v[84:87]
	v_mfma_f32_16x16x32_bf16 v[80:83], v[152:155], v[206:209], v[80:83]
	v_mfma_f32_16x16x32_bf16 v[68:71], v[144:147], v[214:217], v[68:71]
	v_mfma_f32_16x16x32_bf16 v[64:67], v[152:155], v[214:217], v[64:67]
	v_mfma_f32_16x16x32_bf16 v[116:119], v[148:151], v[194:197], v[116:119]
	v_mfma_f32_16x16x32_bf16 v[112:115], v[156:159], v[194:197], v[112:115]
	v_mfma_f32_16x16x32_bf16 v[100:103], v[148:151], v[202:205], v[100:103]
	v_mfma_f32_16x16x32_bf16 v[96:99], v[156:159], v[202:205], v[96:99]
	v_mfma_f32_16x16x32_bf16 v[84:87], v[148:151], v[210:213], v[84:87]
	v_mfma_f32_16x16x32_bf16 v[80:83], v[156:159], v[210:213], v[80:83]
	v_mfma_f32_16x16x32_bf16 v[68:71], v[148:151], v[218:221], v[68:71]
	s_setprio 2
	s_barrier
; #define PG8_STAGE(bufoff, gbase, voff) do { _Pragma("unroll") for (int _i = 0; _i < 2; ++_i) \
;         __builtin_amdgcn_global_load_lds((const unsigned*)((const char*)(gbase) + (voff)[_i]), (PG8_LAS unsigned*)(lds + (bufoff) + ldsw + _i * 8192), 16, 0, 0); } while (0)
; #define PG8_LDA(dst, b, h) do { _Pragma("unroll") for (int m = 0; m < 4; ++m) _Pragma("unroll") for (int k = 0; k < 2; ++k) dst[m][k] = *(const PG8_LAS bf16x8*)(lds + PG8_SA(b, h) + aoff + m * 2048 + k * 1024); } while (0)
; #define PG8_LDB(dst, b, h) do { _Pragma("unroll") for (int n = 0; n < 2; ++n) _Pragma("unroll") for (int k = 0; k < 2; ++k) dst[n][k] = *(const PG8_LAS bf16x8*)(lds + PG8_SB(b, h) + boff + n * 2048 + k * 1024); } while (0)
; #define PG8_MMA(ai, bj, At, Bt) do { __builtin_amdgcn_s_setprio(1); _Pragma("unroll") for (int m = 0; m < 4; ++m) _Pragma("unroll") for (int n = 0; n < 2; ++n) _Pragma("unroll") for (int k = 0; k < 2; ++k) \
;         acc[ai][bj][m][n] = __builtin_amdgcn_mfma_f32_16x16x32_bf16(Bt[n][k], At[m][k], acc[ai][bj][m][n], 0, 0, 0); __builtin_amdgcn_s_setprio(0); } while (0)
; #define PG8_WAIT_V(n) asm volatile("s_waitcnt vmcnt(" #n ")" ::: "memory")
; #define PG8_WAIT_L(n) asm volatile("s_waitcnt lgkmcnt(" #n ")" ::: "memory")
; #define PG8_BAR __builtin_amdgcn_s_barrier()
; template <class Epi, class Sched, bool ALIGN_EPI = false, bool SP2 = false>
; __device__ __forceinline__ void gemm_phase(PG8_LAS unsigned char* lds, const Gemm g, const Sched& S, const Epi& E) {
;     ...
;             PG8_WAIT_V(8); PG8_WAIT_L(0); PG8_BAR; PG8_MMA(0, 0, At, B0); PG8_MMA(0, 1, At, B1); PG8_BAR; PG8_SCHED;
;             PG8_LDA(At, 0, 1); PG8_STAGE(PG8_SB(0, 0), b2, voffB); PG8_STAGE(PG8_SB(0, 1), b2 + hstep, voffB); PG8_STAGE(PG8_SA(0, 0), a2, voffA);
;             PG8_WAIT_V(8); PG8_WAIT_L(0); PG8_BAR; PG8_MMA(1, 0, At, B0); PG8_MMA(1, 1, At, B1); PG8_BAR; PG8_SCHED;
;             PG8_LDB(B0, 1, 0); PG8_LDB(B1, 1, 1); PG8_SCHED; PG8_LDA(At, 1, 0); PG8_STAGE(PG8_SA(0, 1), a2 + hstep, voffA);
;             PG8_WAIT_V(8); PG8_WAIT_L(0); PG8_BAR; PG8_MMA(0, 0, At, B0); PG8_MMA(0, 1, At, B1); PG8_BAR; PG8_SCHED;
;             PG8_LDA(At, 1, 1); PG8_STAGE(PG8_SB(1, 0), b3, voffB); PG8_STAGE(PG8_SB(1, 1), b3 + hstep, voffB); PG8_STAGE(PG8_SA(1, 0), a3, voffA);
;             PG8_WAIT_V(8); PG8_WAIT_L(0); PG8_BAR; PG8_MMA(1, 0, At, B0); PG8_MMA(1, 1, At, B1); PG8_BAR; PG8_SCHED;
	v_mfma_f32_16x16x32_bf16 v[64:67], v[156:159], v[218:221], v[64:67]
	s_setprio 0
	s_add_i32 s28, s52, s30
	v_lshl_add_u64 v[184:185], v[184:185], 0, s[16:17]
	s_mov_b32 m0, s28
	ds_read_b128 v[180:183], v192 offset:49152
	ds_read_b128 v[194:197], v192 offset:50176
	ds_read_b128 v[198:201], v192 offset:51200
	ds_read_b128 v[202:205], v192 offset:52224
	ds_read_b128 v[206:209], v192 offset:53248
	ds_read_b128 v[210:213], v192 offset:54272
	ds_read_b128 v[214:217], v192 offset:55296
	ds_read_b128 v[218:221], v192 offset:56320
	global_load_lds_dwordx4 v[184:185], off
	s_add_i32 m0, s28, 0x2000
	s_add_u32 s6, s6, 0x80080
	v_lshl_add_u64 v[184:185], v[222:223], 0, s[16:17]
	s_addc_u32 s7, s7, 0
	s_add_i32 s28, s53, s30
	global_load_lds_dwordx4 v[184:185], off
	v_lshl_add_u64 v[184:185], s[6:7], 0, v[164:165]
	s_mov_b32 m0, s28
	s_nop 0
	global_load_lds_dwordx4 v[184:185], off
	v_lshl_add_u64 v[184:185], s[6:7], 0, v[168:169]
	s_add_i32 m0, s28, 0x2000
	s_nop 0
	global_load_lds_dwordx4 v[184:185], off
	v_lshl_add_u64 v[184:185], v[224:225], 0, s[16:17]
	s_mov_b32 m0, s38
	s_nop 0
	global_load_lds_dwordx4 v[184:185], off
	v_lshl_add_u64 v[184:185], v[226:227], 0, s[16:17]
	s_mov_b32 m0, s39
	s_nop 0
	global_load_lds_dwordx4 v[184:185], off
	s_setprio 1
	s_waitcnt vmcnt(8)
	s_waitcnt lgkmcnt(0)
	s_barrier
	v_mfma_f32_16x16x32_bf16 v[60:63], v[128:131], v[180:183], v[60:63]
	v_mfma_f32_16x16x32_bf16 v[56:59], v[136:139], v[180:183], v[56:59]
	v_mfma_f32_16x16x32_bf16 v[44:47], v[128:131], v[198:201], v[44:47]
	v_mfma_f32_16x16x32_bf16 v[40:43], v[136:139], v[198:201], v[40:43]
	v_mfma_f32_16x16x32_bf16 v[28:31], v[128:131], v[206:209], v[28:31]
	v_mfma_f32_16x16x32_bf16 v[24:27], v[136:139], v[206:209], v[24:27]
	v_mfma_f32_16x16x32_bf16 v[12:15], v[128:131], v[214:217], v[12:15]
	v_mfma_f32_16x16x32_bf16 v[8:11], v[136:139], v[214:217], v[8:11]
	v_mfma_f32_16x16x32_bf16 v[60:63], v[132:135], v[194:197], v[60:63]
	v_mfma_f32_16x16x32_bf16 v[56:59], v[140:143], v[194:197], v[56:59]
	v_mfma_f32_16x16x32_bf16 v[44:47], v[132:135], v[202:205], v[44:47]
	v_mfma_f32_16x16x32_bf16 v[40:43], v[140:143], v[202:205], v[40:43]
	v_mfma_f32_16x16x32_bf16 v[28:31], v[132:135], v[210:213], v[28:31]
	v_mfma_f32_16x16x32_bf16 v[24:27], v[140:143], v[210:213], v[24:27]
	v_mfma_f32_16x16x32_bf16 v[12:15], v[132:135], v[218:221], v[12:15]
	v_mfma_f32_16x16x32_bf16 v[8:11], v[140:143], v[218:221], v[8:11]
	s_setprio 0
	s_setprio 1
	v_mfma_f32_16x16x32_bf16 v[52:55], v[144:147], v[180:183], v[52:55]
	v_mfma_f32_16x16x32_bf16 v[48:51], v[152:155], v[180:183], v[48:51]
	v_mfma_f32_16x16x32_bf16 v[36:39], v[144:147], v[198:201], v[36:39]
	v_mfma_f32_16x16x32_bf16 v[32:35], v[152:155], v[198:201], v[32:35]
	v_mfma_f32_16x16x32_bf16 v[20:23], v[144:147], v[206:209], v[20:23]
	v_mfma_f32_16x16x32_bf16 v[16:19], v[152:155], v[206:209], v[16:19]
	v_mfma_f32_16x16x32_bf16 v[4:7], v[144:147], v[214:217], v[4:7]
	v_mfma_f32_16x16x32_bf16 v[0:3], v[152:155], v[214:217], v[0:3]
	v_mfma_f32_16x16x32_bf16 v[52:55], v[148:151], v[194:197], v[52:55]
	v_mfma_f32_16x16x32_bf16 v[48:51], v[156:159], v[194:197], v[48:51]
	v_mfma_f32_16x16x32_bf16 v[36:39], v[148:151], v[202:205], v[36:39]
	v_mfma_f32_16x16x32_bf16 v[32:35], v[156:159], v[202:205], v[32:35]
	v_mfma_f32_16x16x32_bf16 v[20:23], v[148:151], v[210:213], v[20:23]
	v_mfma_f32_16x16x32_bf16 v[16:19], v[156:159], v[210:213], v[16:19]
	v_mfma_f32_16x16x32_bf16 v[4:7], v[148:151], v[218:221], v[4:7]
	s_setprio 2
	s_barrier
	v_mfma_f32_16x16x32_bf16 v[0:3], v[156:159], v[218:221], v[0:3]
	s_setprio 0
	s_add_i32 s51, s51, 2
	s_add_u32 s4, s4, 0x100
	s_addc_u32 s5, s5, 0
	s_add_u32 s33, s33, 0x100
	s_addc_u32 s50, s50, 0
	s_cmp_gt_u32 s51, 29
	s_cbranch_scc0 .LBB0_205
	s_and_b64 vcc, exec, s[18:19]
	s_cbranch_vccz .LBB0_208
	s_barrier

;     __device__ __forceinline__ bool next(int i, Unit& u) const { if (!base.next(i >> 1, u)) return false; if (i & 1) { u.pm += 64; u.pn += 8; } return true; }
; #define PG8_STAGE(bufoff, gbase, voff) do { _Pragma("unroll") for (int _i = 0; _i < 2; ++_i) \
;         __builtin_amdgcn_global_load_lds((const unsigned*)((const char*)(gbase) + (voff)[_i]), (PG8_LAS unsigned*)(lds + (bufoff) + ldsw + _i * 8192), 16, 0, 0); } while (0)
; #define PG8_WAIT_V(n) asm volatile("s_waitcnt vmcnt(" #n ")" ::: "memory")
; template <class Epi, class Sched, bool ALIGN_EPI = false, bool SP2 = false>
; __device__ __forceinline__ void gemm_phase(PG8_LAS unsigned char* lds, const Gemm g, const Sched& S, const Epi& E) {
;     ...
;         const bool has_next = S.next(ui + 1, nxt);
;         const char* nA = has_next ? (const char*)g.A + (size_t)nxt.pm * tstep : cA; const char* nB = has_next ? (const char*)g.Bt + (size_t)nxt.pn * tstep : cB;
;         for (int t = 0; t < nt; t += 2) {
;             const bool last = (t == nt - 2);
;             const char* a1 = cA + (size_t)(t + 1) * kstep;
;             const char* a2 = last ? nA : cA + (size_t)(t + 2) * kstep; const char* b2 = last ? nB : cB + (size_t)(t + 2) * kstep;
;             const char* a3 = a2 + kstep; const char* b3 = b2 + kstep;
;             if (last && has_next) S.a_ready(nxt);
;             if constexpr (SP2) {
;             PG8_LDB(B0, 0, 0); PG8_LDB(B1, 0, 1); PG8_SCHED; PG8_LDA(At, 0, 0); PG8_STAGE(PG8_SA(1, 1), a1 + hstep, voffA);
;             PG8_WAIT_V(8); PG8_WAIT_L(0); PG8_BAR; PG8_MMA(0, 0, At, B0); PG8_MMA(0, 1, At, B1); PG8_BAR; PG8_SCHED;
;             PG8_LDA(At, 0, 1); PG8_STAGE(PG8_SB(0, 0), b2, voffB); PG8_STAGE(PG8_SB(0, 1), b2 + hstep, voffB); PG8_STAGE(PG8_SA(0, 0), a2, voffA);
;             PG8_WAIT_V(8); PG8_WAIT_L(0); PG8_BAR; PG8_MMA(1, 0, At, B0); PG8_MMA(1, 1, At, B1); PG8_BAR; PG8_SCHED;
;             PG8_LDB(B0, 1, 0); PG8_LDB(B1, 1, 1); PG8_SCHED; PG8_LDA(At, 1, 0); PG8_STAGE(PG8_SA(0, 1), a2 + hstep, voffA);
;             PG8_WAIT_V(8); PG8_WAIT_L(0); PG8_BAR; PG8_MMA(0, 0, At, B0); PG8_MMA(0, 1, At, B1); PG8_BAR; PG8_SCHED;
;             PG8_LDA(At, 1, 1); PG8_STAGE(PG8_SB(1, 0), b3, voffB); PG8_STAGE(PG8_SB(1, 1), b3 + hstep, voffB); PG8_STAGE(PG8_SA(1, 0), a3, voffA);
;             PG8_WAIT_V(8); PG8_WAIT_L(0); PG8_BAR; PG8_MMA(1, 0, At, B0); PG8_MMA(1, 1, At, B1); PG8_BAR; PG8_SCHED;
.LBB0_571:
	s_bitcmp0_b32 s7, 0
	s_cselect_b64 s[16:17], -1, 0
	s_and_b64 s[16:17], s[16:17], s[4:5]
	s_add_i32 s7, s14, 64
	s_add_i32 s13, s12, 8
	s_and_b64 s[16:17], s[16:17], exec
	s_cselect_b32 s14, s7, s14
	s_cselect_b32 s12, s13, s12
	s_ashr_i32 s15, s14, 31
	s_lshl_b64 s[16:17], s[14:15], 19
	s_add_u32 s16, s29, s16
	s_addc_u32 s17, s30, s17
	s_and_b64 s[18:19], s[4:5], exec
	s_cselect_b32 s7, s17, s23
	s_cselect_b32 s15, s16, s22
	s_ashr_i32 s13, s12, 31
	s_lshl_b64 s[18:19], s[12:13], 19
	v_readlane_b32 s26, v236, 41
	v_readlane_b32 s27, v236, 42
	s_add_u32 s18, s26, s18
	s_addc_u32 s19, s27, s19
	s_and_b64 s[26:27], s[4:5], exec
	s_cselect_b32 s13, s19, s25
	s_cselect_b32 s21, s18, s24
	s_add_u32 s22, s22, 0x40080
	s_addc_u32 s23, s23, 0
	s_add_u32 s44, s24, 0x100
	s_addc_u32 s45, s25, 0
	s_mov_b32 s46, -2
	ds_read_b128 v[146:149], v159
	ds_read_b128 v[150:153], v159 offset:1024
	ds_read_b128 v[164:167], v159 offset:2048
	ds_read_b128 v[168:171], v159 offset:3072
	ds_read_b128 v[172:175], v161
	ds_read_b128 v[176:179], v161 offset:1024
	ds_read_b128 v[180:183], v161 offset:2048
	ds_read_b128 v[188:191], v161 offset:3072
	s_add_u32 s24, s22, 0xfffc0080
	s_addc_u32 s25, s23, -1
	s_cmp_eq_u32 s46, 12
	s_cselect_b32 s27, s7, s25
	s_cselect_b32 s26, s15, s24
	s_cselect_b32 s25, s13, s45
	s_cselect_b32 s24, s21, s44
	v_lshl_add_u64 v[154:155], s[22:23], 0, v[138:139]
	s_add_i32 m0, s31, 0xc000
	ds_read_b128 v[192:195], v162
	ds_read_b128 v[196:199], v162 offset:1024
	ds_read_b128 v[200:203], v162 offset:2048
	ds_read_b128 v[204:207], v162 offset:3072
	ds_read_b128 v[208:211], v162 offset:4096
	ds_read_b128 v[212:215], v162 offset:5120
	ds_read_b128 v[216:219], v162 offset:6144
	ds_read_b128 v[220:223], v162 offset:7168
	global_load_lds_dwordx4 v[154:155], off
	v_lshl_add_u64 v[154:155], s[22:23], 0, v[140:141]
	s_add_i32 m0, s31, 0xe000
	s_nop 0
	global_load_lds_dwordx4 v[154:155], off
	s_setprio 1
	s_waitcnt vmcnt(8)
	s_waitcnt lgkmcnt(0)
	s_barrier
	v_mfma_f32_16x16x32_bf16 v[124:127], v[146:149], v[192:195], 0
	v_mfma_f32_16x16x32_bf16 v[120:123], v[164:167], v[192:195], 0
	v_mfma_f32_16x16x32_bf16 v[108:111], v[146:149], v[200:203], 0
	v_mfma_f32_16x16x32_bf16 v[104:107], v[164:167], v[200:203], 0
	v_mfma_f32_16x16x32_bf16 v[92:95], v[146:149], v[208:211], 0
	v_mfma_f32_16x16x32_bf16 v[88:91], v[164:167], v[208:211], 0
	v_mfma_f32_16x16x32_bf16 v[76:79], v[146:149], v[216:219], 0
	v_mfma_f32_16x16x32_bf16 v[72:75], v[164:167], v[216:219], 0
	v_mfma_f32_16x16x32_bf16 v[124:127], v[150:153], v[196:199], v[124:127]
	v_mfma_f32_16x16x32_bf16 v[120:123], v[168:171], v[196:199], v[120:123]
	v_mfma_f32_16x16x32_bf16 v[108:111], v[150:153], v[204:207], v[108:111]
	v_mfma_f32_16x16x32_bf16 v[104:107], v[168:171], v[204:207], v[104:107]
	v_mfma_f32_16x16x32_bf16 v[92:95], v[150:153], v[212:215], v[92:95]
	v_mfma_f32_16x16x32_bf16 v[88:91], v[168:171], v[212:215], v[88:91]
	v_mfma_f32_16x16x32_bf16 v[76:79], v[150:153], v[220:223], v[76:79]
	v_mfma_f32_16x16x32_bf16 v[72:75], v[168:171], v[220:223], v[72:75]
	s_setprio 0
	s_setprio 1
	v_mfma_f32_16x16x32_bf16 v[116:119], v[172:175], v[192:195], 0
	v_mfma_f32_16x16x32_bf16 v[112:115], v[180:183], v[192:195], 0
	v_mfma_f32_16x16x32_bf16 v[100:103], v[172:175], v[200:203], 0
	v_mfma_f32_16x16x32_bf16 v[96:99], v[180:183], v[200:203], 0
	v_mfma_f32_16x16x32_bf16 v[84:87], v[172:175], v[208:211], 0
	v_mfma_f32_16x16x32_bf16 v[80:83], v[180:183], v[208:211], 0
	v_mfma_f32_16x16x32_bf16 v[68:71], v[172:175], v[216:219], 0
	v_mfma_f32_16x16x32_bf16 v[64:67], v[180:183], v[216:219], 0
	v_mfma_f32_16x16x32_bf16 v[116:119], v[176:179], v[196:199], v[116:119]
	v_mfma_f32_16x16x32_bf16 v[112:115], v[188:191], v[196:199], v[112:115]
	v_mfma_f32_16x16x32_bf16 v[100:103], v[176:179], v[204:207], v[100:103]
	v_mfma_f32_16x16x32_bf16 v[96:99], v[188:191], v[204:207], v[96:99]
	v_mfma_f32_16x16x32_bf16 v[84:87], v[176:179], v[212:215], v[84:87]
	v_mfma_f32_16x16x32_bf16 v[80:83], v[188:191], v[212:215], v[80:83]
	v_mfma_f32_16x16x32_bf16 v[68:71], v[176:179], v[220:223], v[68:71]
	s_setprio 2
	s_barrier
	v_mfma_f32_16x16x32_bf16 v[64:67], v[188:191], v[220:223], v[64:67]
	s_setprio 0
	s_add_i32 s47, s39, s28
	v_lshl_add_u64 v[154:155], s[24:25], 0, v[130:131]
	s_mov_b32 m0, s47
	ds_read_b128 v[192:195], v162 offset:16384
	ds_read_b128 v[196:199], v162 offset:17408
	ds_read_b128 v[200:203], v162 offset:18432
	ds_read_b128 v[204:207], v162 offset:19456
	ds_read_b128 v[208:211], v162 offset:20480
	ds_read_b128 v[212:215], v162 offset:21504
	ds_read_b128 v[216:219], v162 offset:22528
	ds_read_b128 v[220:223], v162 offset:23552
	global_load_lds_dwordx4 v[154:155], off
	s_add_i32 m0, s47, 0x2000
	s_add_u32 s48, s24, 0x40000
	v_lshl_add_u64 v[184:185], s[24:25], 0, v[134:135]
	s_addc_u32 s49, s25, 0
	s_add_i32 s47, s40, s28
	global_load_lds_dwordx4 v[184:185], off
	v_lshl_add_u64 v[224:225], s[48:49], 0, v[130:131]
	s_mov_b32 m0, s47
	v_lshl_add_u64 v[226:227], s[26:27], 0, v[132:133]
	global_load_lds_dwordx4 v[224:225], off
	v_lshl_add_u64 v[224:225], s[48:49], 0, v[134:135]
	s_add_i32 m0, s47, 0x2000
	s_nop 0
	global_load_lds_dwordx4 v[224:225], off
	v_lshl_add_u64 v[224:225], s[26:27], 0, v[128:129]
	s_mov_b32 m0, s31
	s_nop 0
	global_load_lds_dwordx4 v[224:225], off
	s_mov_b32 m0, s33
	s_nop 0
	global_load_lds_dwordx4 v[226:227], off
	s_setprio 1
	s_waitcnt vmcnt(8)
	s_waitcnt lgkmcnt(0)
	s_barrier
; #define PG8_STAGE(bufoff, gbase, voff) do { _Pragma("unroll") for (int _i = 0; _i < 2; ++_i) \
;         __builtin_amdgcn_global_load_lds((const unsigned*)((const char*)(gbase) + (voff)[_i]), (PG8_LAS unsigned*)(lds + (bufoff) + ldsw + _i * 8192), 16, 0, 0); } while (0)
; #define PG8_LDA(dst, b, h) do { _Pragma("unroll") for (int m = 0; m < 4; ++m) _Pragma("unroll") for (int k = 0; k < 2; ++k) dst[m][k] = *(const PG8_LAS bf16x8*)(lds + PG8_SA(b, h) + aoff + m * 2048 + k * 1024); } while (0)
; #define PG8_LDB(dst, b, h) do { _Pragma("unroll") for (int n = 0; n < 2; ++n) _Pragma("unroll") for (int k = 0; k < 2; ++k) dst[n][k] = *(const PG8_LAS bf16x8*)(lds + PG8_SB(b, h) + boff + n * 2048 + k * 1024); } while (0)
; #define PG8_MMA(ai, bj, At, Bt) do { __builtin_amdgcn_s_setprio(1); _Pragma("unroll") for (int m = 0; m < 4; ++m) _Pragma("unroll") for (int n = 0; n < 2; ++n) _Pragma("unroll") for (int k = 0; k < 2; ++k) \
;         acc[ai][bj][m][n] = __builtin_amdgcn_mfma_f32_16x16x32_bf16(Bt[n][k], At[m][k], acc[ai][bj][m][n], 0, 0, 0); __builtin_amdgcn_s_setprio(0); } while (0)
; #define PG8_WAIT_V(n) asm volatile("s_waitcnt vmcnt(" #n ")" ::: "memory")
; template <class Epi, class Sched, bool ALIGN_EPI = false, bool SP2 = false>
; __device__ __forceinline__ void gemm_phase(PG8_LAS unsigned char* lds, const Gemm g, const Sched& S, const Epi& E) {
;     ...
;             PG8_LDB(B0, 0, 0); PG8_LDB(B1, 0, 1); PG8_SCHED; PG8_LDA(At, 0, 0); PG8_STAGE(PG8_SA(1, 1), a1 + hstep, voffA);
;             PG8_WAIT_V(8); PG8_WAIT_L(0); PG8_BAR; PG8_MMA(0, 0, At, B0); PG8_MMA(0, 1, At, B1); PG8_BAR; PG8_SCHED;
;             PG8_LDA(At, 0, 1); PG8_STAGE(PG8_SB(0, 0), b2, voffB); PG8_STAGE(PG8_SB(0, 1), b2 + hstep, voffB); PG8_STAGE(PG8_SA(0, 0), a2, voffA);
;             PG8_WAIT_V(8); PG8_WAIT_L(0); PG8_BAR; PG8_MMA(1, 0, At, B0); PG8_MMA(1, 1, At, B1); PG8_BAR; PG8_SCHED;
;             PG8_LDB(B0, 1, 0); PG8_LDB(B1, 1, 1); PG8_SCHED; PG8_LDA(At, 1, 0); PG8_STAGE(PG8_SA(0, 1), a2 + hstep, voffA);
;             PG8_WAIT_V(8); PG8_WAIT_L(0); PG8_BAR; PG8_MMA(0, 0, At, B0); PG8_MMA(0, 1, At, B1); PG8_BAR; PG8_SCHED;
;             PG8_LDA(At, 1, 1); PG8_STAGE(PG8_SB(1, 0), b3, voffB); PG8_STAGE(PG8_SB(1, 1), b3 + hstep, voffB); PG8_STAGE(PG8_SA(1, 0), a3, voffA);
;             PG8_WAIT_V(8); PG8_WAIT_L(0); PG8_BAR; PG8_MMA(1, 0, At, B0); PG8_MMA(1, 1, At, B1); PG8_BAR; PG8_SCHED;
	v_mfma_f32_16x16x32_bf16 v[60:63], v[146:149], v[192:195], 0
	v_mfma_f32_16x16x32_bf16 v[56:59], v[164:167], v[192:195], 0
	v_mfma_f32_16x16x32_bf16 v[44:47], v[146:149], v[200:203], 0
	v_mfma_f32_16x16x32_bf16 v[40:43], v[164:167], v[200:203], 0
	v_mfma_f32_16x16x32_bf16 v[28:31], v[146:149], v[208:211], 0
	v_mfma_f32_16x16x32_bf16 v[24:27], v[164:167], v[208:211], 0
	v_mfma_f32_16x16x32_bf16 v[12:15], v[146:149], v[216:219], 0
	v_mfma_f32_16x16x32_bf16 v[8:11], v[164:167], v[216:219], 0
	v_mfma_f32_16x16x32_bf16 v[60:63], v[150:153], v[196:199], v[60:63]
	v_mfma_f32_16x16x32_bf16 v[56:59], v[168:171], v[196:199], v[56:59]
	v_mfma_f32_16x16x32_bf16 v[44:47], v[150:153], v[204:207], v[44:47]
	v_mfma_f32_16x16x32_bf16 v[40:43], v[168:171], v[204:207], v[40:43]
	v_mfma_f32_16x16x32_bf16 v[28:31], v[150:153], v[212:215], v[28:31]
	v_mfma_f32_16x16x32_bf16 v[24:27], v[168:171], v[212:215], v[24:27]
	v_mfma_f32_16x16x32_bf16 v[12:15], v[150:153], v[220:223], v[12:15]
	v_mfma_f32_16x16x32_bf16 v[8:11], v[168:171], v[220:223], v[8:11]
	s_setprio 0
	s_setprio 1
	v_mfma_f32_16x16x32_bf16 v[52:55], v[172:175], v[192:195], 0
	v_mfma_f32_16x16x32_bf16 v[48:51], v[180:183], v[192:195], 0
	v_mfma_f32_16x16x32_bf16 v[36:39], v[172:175], v[200:203], 0
	v_mfma_f32_16x16x32_bf16 v[32:35], v[180:183], v[200:203], 0
	v_mfma_f32_16x16x32_bf16 v[20:23], v[172:175], v[208:211], 0
	v_mfma_f32_16x16x32_bf16 v[16:19], v[180:183], v[208:211], 0
	v_mfma_f32_16x16x32_bf16 v[4:7], v[172:175], v[216:219], 0
	v_mfma_f32_16x16x32_bf16 v[0:3], v[180:183], v[216:219], 0
	v_mfma_f32_16x16x32_bf16 v[52:55], v[176:179], v[196:199], v[52:55]
	v_mfma_f32_16x16x32_bf16 v[48:51], v[188:191], v[196:199], v[48:51]
	v_mfma_f32_16x16x32_bf16 v[36:39], v[176:179], v[204:207], v[36:39]
	v_mfma_f32_16x16x32_bf16 v[32:35], v[188:191], v[204:207], v[32:35]
	v_mfma_f32_16x16x32_bf16 v[20:23], v[176:179], v[212:215], v[20:23]
	v_mfma_f32_16x16x32_bf16 v[16:19], v[188:191], v[212:215], v[16:19]
	v_mfma_f32_16x16x32_bf16 v[4:7], v[176:179], v[220:223], v[4:7]
	s_setprio 2
	s_barrier
	v_mfma_f32_16x16x32_bf16 v[0:3], v[188:191], v[220:223], v[0:3]
	s_setprio 0
	s_add_i32 s47, 0, 0x18000
	v_add_u32_e32 v136, s47, v157
	s_add_i32 s48, 0, 0x1c000
	ds_read_b128 v[146:149], v136
	ds_read_b128 v[150:153], v136 offset:1024
	ds_read_b128 v[164:167], v136 offset:2048
	ds_read_b128 v[168:171], v136 offset:3072
	v_add_u32_e32 v136, s48, v157
	ds_read_b128 v[172:175], v136
	ds_read_b128 v[176:179], v136 offset:1024
	ds_read_b128 v[180:183], v136 offset:2048
	ds_read_b128 v[188:191], v136 offset:3072
	s_add_u32 s26, s26, 0x40000
	s_addc_u32 s27, s27, 0
	s_mov_b32 m0, s34
	v_lshl_add_u64 v[228:229], s[26:27], 0, v[128:129]
	ds_read_b128 v[192:195], v162 offset:32768
	ds_read_b128 v[196:199], v162 offset:33792
	ds_read_b128 v[200:203], v162 offset:34816
	ds_read_b128 v[204:207], v162 offset:35840
	ds_read_b128 v[208:211], v162 offset:36864
	ds_read_b128 v[212:215], v162 offset:37888
	ds_read_b128 v[216:219], v162 offset:38912
	ds_read_b128 v[220:223], v162 offset:39936
	global_load_lds_dwordx4 v[228:229], off
	v_lshl_add_u64 v[228:229], s[26:27], 0, v[132:133]
	s_mov_b32 m0, s35
	s_nop 0
	global_load_lds_dwordx4 v[228:229], off
	s_setprio 1
	s_waitcnt vmcnt(8)
	s_waitcnt lgkmcnt(0)
	s_barrier
	v_mfma_f32_16x16x32_bf16 v[124:127], v[146:149], v[192:195], v[124:127]
	v_mfma_f32_16x16x32_bf16 v[120:123], v[164:167], v[192:195], v[120:123]
	v_mfma_f32_16x16x32_bf16 v[108:111], v[146:149], v[200:203], v[108:111]
	v_mfma_f32_16x16x32_bf16 v[104:107], v[164:167], v[200:203], v[104:107]
	v_mfma_f32_16x16x32_bf16 v[92:95], v[146:149], v[208:211], v[92:95]
	v_mfma_f32_16x16x32_bf16 v[88:91], v[164:167], v[208:211], v[88:91]
	v_mfma_f32_16x16x32_bf16 v[76:79], v[146:149], v[216:219], v[76:79]
	v_mfma_f32_16x16x32_bf16 v[72:75], v[164:167], v[216:219], v[72:75]
	v_mfma_f32_16x16x32_bf16 v[124:127], v[150:153], v[196:199], v[124:127]
	v_mfma_f32_16x16x32_bf16 v[120:123], v[168:171], v[196:199], v[120:123]
	v_mfma_f32_16x16x32_bf16 v[108:111], v[150:153], v[204:207], v[108:111]
	v_mfma_f32_16x16x32_bf16 v[104:107], v[168:171], v[204:207], v[104:107]
	v_mfma_f32_16x16x32_bf16 v[92:95], v[150:153], v[212:215], v[92:95]
	v_mfma_f32_16x16x32_bf16 v[88:91], v[168:171], v[212:215], v[88:91]
	v_mfma_f32_16x16x32_bf16 v[76:79], v[150:153], v[220:223], v[76:79]
	v_mfma_f32_16x16x32_bf16 v[72:75], v[168:171], v[220:223], v[72:75]
	s_setprio 0
	s_setprio 1
	v_mfma_f32_16x16x32_bf16 v[116:119], v[172:175], v[192:195], v[116:119]
	v_mfma_f32_16x16x32_bf16 v[112:115], v[180:183], v[192:195], v[112:115]
	v_mfma_f32_16x16x32_bf16 v[100:103], v[172:175], v[200:203], v[100:103]
	v_mfma_f32_16x16x32_bf16 v[96:99], v[180:183], v[200:203], v[96:99]
	v_mfma_f32_16x16x32_bf16 v[84:87], v[172:175], v[208:211], v[84:87]
	v_mfma_f32_16x16x32_bf16 v[80:83], v[180:183], v[208:211], v[80:83]
	v_mfma_f32_16x16x32_bf16 v[68:71], v[172:175], v[216:219], v[68:71]
	v_mfma_f32_16x16x32_bf16 v[64:67], v[180:183], v[216:219], v[64:67]
	v_mfma_f32_16x16x32_bf16 v[116:119], v[176:179], v[196:199], v[116:119]
	v_mfma_f32_16x16x32_bf16 v[112:115], v[188:191], v[196:199], v[112:115]
	v_mfma_f32_16x16x32_bf16 v[100:103], v[176:179], v[204:207], v[100:103]
	v_mfma_f32_16x16x32_bf16 v[96:99], v[188:191], v[204:207], v[96:99]
	v_mfma_f32_16x16x32_bf16 v[84:87], v[176:179], v[212:215], v[84:87]
	v_mfma_f32_16x16x32_bf16 v[80:83], v[188:191], v[212:215], v[80:83]
	v_mfma_f32_16x16x32_bf16 v[68:71], v[176:179], v[220:223], v[68:71]
	s_setprio 2
	s_barrier
; #define PG8_STAGE(bufoff, gbase, voff) do { _Pragma("unroll") for (int _i = 0; _i < 2; ++_i) \
;         __builtin_amdgcn_global_load_lds((const unsigned*)((const char*)(gbase) + (voff)[_i]), (PG8_LAS unsigned*)(lds + (bufoff) + ldsw + _i * 8192), 16, 0, 0); } while (0)
; #define PG8_LDA(dst, b, h) do { _Pragma("unroll") for (int m = 0; m < 4; ++m) _Pragma("unroll") for (int k = 0; k < 2; ++k) dst[m][k] = *(const PG8_LAS bf16x8*)(lds + PG8_SA(b, h) + aoff + m * 2048 + k * 1024); } while (0)
; #define PG8_LDB(dst, b, h) do { _Pragma("unroll") for (int n = 0; n < 2; ++n) _Pragma("unroll") for (int k = 0; k < 2; ++k) dst[n][k] = *(const PG8_LAS bf16x8*)(lds + PG8_SB(b, h) + boff + n * 2048 + k * 1024); } while (0)
; #define PG8_MMA(ai, bj, At, Bt) do { __builtin_amdgcn_s_setprio(1); _Pragma("unroll") for (int m = 0; m < 4; ++m) _Pragma("unroll") for (int n = 0; n < 2; ++n) _Pragma("unroll") for (int k = 0; k < 2; ++k) \
;         acc[ai][bj][m][n] = __builtin_amdgcn_mfma_f32_16x16x32_bf16(Bt[n][k], At[m][k], acc[ai][bj][m][n], 0, 0, 0); __builtin_amdgcn_s_setprio(0); } while (0)
; #define PG8_WAIT_V(n) asm volatile("s_waitcnt vmcnt(" #n ")" ::: "memory")
; template <class Epi, class Sched, bool ALIGN_EPI = false, bool SP2 = false>
; __device__ __forceinline__ void gemm_phase(PG8_LAS unsigned char* lds, const Gemm g, const Sched& S, const Epi& E) {
;     ...
;             PG8_LDB(B0, 0, 0); PG8_LDB(B1, 0, 1); PG8_SCHED; PG8_LDA(At, 0, 0); PG8_STAGE(PG8_SA(1, 1), a1 + hstep, voffA);
;             PG8_WAIT_V(8); PG8_WAIT_L(0); PG8_BAR; PG8_MMA(0, 0, At, B0); PG8_MMA(0, 1, At, B1); PG8_BAR; PG8_SCHED;
;             PG8_LDA(At, 0, 1); PG8_STAGE(PG8_SB(0, 0), b2, voffB); PG8_STAGE(PG8_SB(0, 1), b2 + hstep, voffB); PG8_STAGE(PG8_SA(0, 0), a2, voffA);
;             PG8_WAIT_V(8); PG8_WAIT_L(0); PG8_BAR; PG8_MMA(1, 0, At, B0); PG8_MMA(1, 1, At, B1); PG8_BAR; PG8_SCHED;
;             PG8_LDB(B0, 1, 0); PG8_LDB(B1, 1, 1); PG8_SCHED; PG8_LDA(At, 1, 0); PG8_STAGE(PG8_SA(0, 1), a2 + hstep, voffA);
;             PG8_WAIT_V(8); PG8_WAIT_L(0); PG8_BAR; PG8_MMA(0, 0, At, B0); PG8_MMA(0, 1, At, B1); PG8_BAR; PG8_SCHED;
;             PG8_LDA(At, 1, 1); PG8_STAGE(PG8_SB(1, 0), b3, voffB); PG8_STAGE(PG8_SB(1, 1), b3 + hstep, voffB); PG8_STAGE(PG8_SA(1, 0), a3, voffA);
;             PG8_WAIT_V(8); PG8_WAIT_L(0); PG8_BAR; PG8_MMA(1, 0, At, B0); PG8_MMA(1, 1, At, B1); PG8_BAR; PG8_SCHED;
	v_mfma_f32_16x16x32_bf16 v[64:67], v[188:191], v[220:223], v[64:67]
	s_setprio 0
	s_add_i32 s26, s47, s28
	v_lshl_add_u64 v[154:155], v[154:155], 0, s[8:9]
	s_mov_b32 m0, s26
	ds_read_b128 v[192:195], v162 offset:49152
	ds_read_b128 v[196:199], v162 offset:50176
	ds_read_b128 v[200:203], v162 offset:51200
	ds_read_b128 v[204:207], v162 offset:52224
	ds_read_b128 v[208:211], v162 offset:53248
	ds_read_b128 v[212:215], v162 offset:54272
	ds_read_b128 v[216:219], v162 offset:55296
	ds_read_b128 v[220:223], v162 offset:56320
	global_load_lds_dwordx4 v[154:155], off
	s_add_i32 m0, s26, 0x2000
	s_add_u32 s24, s24, 0x40080
	v_lshl_add_u64 v[154:155], v[184:185], 0, s[8:9]
	s_addc_u32 s25, s25, 0
	s_add_i32 s26, s48, s28
	global_load_lds_dwordx4 v[154:155], off
	v_lshl_add_u64 v[154:155], s[24:25], 0, v[130:131]
	s_mov_b32 m0, s26
	s_nop 0
	global_load_lds_dwordx4 v[154:155], off
	v_lshl_add_u64 v[154:155], s[24:25], 0, v[134:135]
	s_add_i32 m0, s26, 0x2000
	s_nop 0
	global_load_lds_dwordx4 v[154:155], off
	v_lshl_add_u64 v[154:155], v[224:225], 0, s[8:9]
	s_mov_b32 m0, s36
	s_nop 0
	global_load_lds_dwordx4 v[154:155], off
	v_lshl_add_u64 v[154:155], v[226:227], 0, s[8:9]
	s_mov_b32 m0, s37
	s_nop 0
	global_load_lds_dwordx4 v[154:155], off
	s_setprio 1
	s_waitcnt vmcnt(8)
	s_waitcnt lgkmcnt(0)
	s_barrier
	v_mfma_f32_16x16x32_bf16 v[60:63], v[146:149], v[192:195], v[60:63]
	v_mfma_f32_16x16x32_bf16 v[56:59], v[164:167], v[192:195], v[56:59]
	v_mfma_f32_16x16x32_bf16 v[44:47], v[146:149], v[200:203], v[44:47]
	v_mfma_f32_16x16x32_bf16 v[40:43], v[164:167], v[200:203], v[40:43]
	v_mfma_f32_16x16x32_bf16 v[28:31], v[146:149], v[208:211], v[28:31]
	v_mfma_f32_16x16x32_bf16 v[24:27], v[164:167], v[208:211], v[24:27]
	v_mfma_f32_16x16x32_bf16 v[12:15], v[146:149], v[216:219], v[12:15]
	v_mfma_f32_16x16x32_bf16 v[8:11], v[164:167], v[216:219], v[8:11]
	v_mfma_f32_16x16x32_bf16 v[60:63], v[150:153], v[196:199], v[60:63]
	v_mfma_f32_16x16x32_bf16 v[56:59], v[168:171], v[196:199], v[56:59]
	v_mfma_f32_16x16x32_bf16 v[44:47], v[150:153], v[204:207], v[44:47]
	v_mfma_f32_16x16x32_bf16 v[40:43], v[168:171], v[204:207], v[40:43]
	v_mfma_f32_16x16x32_bf16 v[28:31], v[150:153], v[212:215], v[28:31]
	v_mfma_f32_16x16x32_bf16 v[24:27], v[168:171], v[212:215], v[24:27]
	v_mfma_f32_16x16x32_bf16 v[12:15], v[150:153], v[220:223], v[12:15]
	v_mfma_f32_16x16x32_bf16 v[8:11], v[168:171], v[220:223], v[8:11]
	s_setprio 0
	s_setprio 1
	v_mfma_f32_16x16x32_bf16 v[52:55], v[172:175], v[192:195], v[52:55]
	v_mfma_f32_16x16x32_bf16 v[48:51], v[180:183], v[192:195], v[48:51]
	v_mfma_f32_16x16x32_bf16 v[36:39], v[172:175], v[200:203], v[36:39]
	v_mfma_f32_16x16x32_bf16 v[32:35], v[180:183], v[200:203], v[32:35]
	v_mfma_f32_16x16x32_bf16 v[20:23], v[172:175], v[208:211], v[20:23]
	v_mfma_f32_16x16x32_bf16 v[16:19], v[180:183], v[208:211], v[16:19]
	v_mfma_f32_16x16x32_bf16 v[4:7], v[172:175], v[216:219], v[4:7]
	v_mfma_f32_16x16x32_bf16 v[0:3], v[180:183], v[216:219], v[0:3]
	v_mfma_f32_16x16x32_bf16 v[52:55], v[176:179], v[196:199], v[52:55]
	v_mfma_f32_16x16x32_bf16 v[48:51], v[188:191], v[196:199], v[48:51]
	v_mfma_f32_16x16x32_bf16 v[36:39], v[176:179], v[204:207], v[36:39]
	v_mfma_f32_16x16x32_bf16 v[32:35], v[188:191], v[204:207], v[32:35]
	v_mfma_f32_16x16x32_bf16 v[20:23], v[176:179], v[212:215], v[20:23]
	v_mfma_f32_16x16x32_bf16 v[16:19], v[188:191], v[212:215], v[16:19]
	v_mfma_f32_16x16x32_bf16 v[4:7], v[176:179], v[220:223], v[4:7]
	s_setprio 2
	s_barrier
	v_mfma_f32_16x16x32_bf16 v[0:3], v[188:191], v[220:223], v[0:3]
	s_setprio 0
	s_add_i32 s46, s46, 2
	s_add_u32 s22, s22, 0x100
	s_addc_u32 s23, s23, 0
	s_add_u32 s44, s44, 0x100
	s_addc_u32 s45, s45, 0
	s_cmp_gt_u32 s46, 13
.LBB0_572:
	ds_read_b128 v[146:149], v159
	ds_read_b128 v[150:153], v159 offset:1024
	ds_read_b128 v[164:167], v159 offset:2048
	ds_read_b128 v[168:171], v159 offset:3072
	ds_read_b128 v[172:175], v161
	ds_read_b128 v[176:179], v161 offset:1024
	ds_read_b128 v[180:183], v161 offset:2048
	ds_read_b128 v[188:191], v161 offset:3072
	s_add_u32 s24, s22, 0xfffc0080
	s_addc_u32 s25, s23, -1
	s_cmp_eq_u32 s46, 12
	s_cselect_b32 s27, s7, s25
	s_cselect_b32 s26, s15, s24
	s_cselect_b32 s25, s13, s45
	s_cselect_b32 s24, s21, s44
	v_lshl_add_u64 v[154:155], s[22:23], 0, v[138:139]
	s_add_i32 m0, s31, 0xc000
	ds_read_b128 v[192:195], v162
	ds_read_b128 v[196:199], v162 offset:1024
	ds_read_b128 v[200:203], v162 offset:2048
	ds_read_b128 v[204:207], v162 offset:3072
	ds_read_b128 v[208:211], v162 offset:4096
	ds_read_b128 v[212:215], v162 offset:5120
	ds_read_b128 v[216:219], v162 offset:6144
	ds_read_b128 v[220:223], v162 offset:7168
	global_load_lds_dwordx4 v[154:155], off
	v_lshl_add_u64 v[154:155], s[22:23], 0, v[140:141]
	s_add_i32 m0, s31, 0xe000
	s_nop 0
	global_load_lds_dwordx4 v[154:155], off
	s_setprio 1
	s_waitcnt vmcnt(8)
	s_waitcnt lgkmcnt(0)
	s_barrier
; #define PG8_STAGE(bufoff, gbase, voff) do { _Pragma("unroll") for (int _i = 0; _i < 2; ++_i) \
;         __builtin_amdgcn_global_load_lds((const unsigned*)((const char*)(gbase) + (voff)[_i]), (PG8_LAS unsigned*)(lds + (bufoff) + ldsw + _i * 8192), 16, 0, 0); } while (0)
; #define PG8_LDA(dst, b, h) do { _Pragma("unroll") for (int m = 0; m < 4; ++m) _Pragma("unroll") for (int k = 0; k < 2; ++k) dst[m][k] = *(const PG8_LAS bf16x8*)(lds + PG8_SA(b, h) + aoff + m * 2048 + k * 1024); } while (0)
; #define PG8_LDB(dst, b, h) do { _Pragma("unroll") for (int n = 0; n < 2; ++n) _Pragma("unroll") for (int k = 0; k < 2; ++k) dst[n][k] = *(const PG8_LAS bf16x8*)(lds + PG8_SB(b, h) + boff + n * 2048 + k * 1024); } while (0)
; #define PG8_MMA(ai, bj, At, Bt) do { __builtin_amdgcn_s_setprio(1); _Pragma("unroll") for (int m = 0; m < 4; ++m) _Pragma("unroll") for (int n = 0; n < 2; ++n) _Pragma("unroll") for (int k = 0; k < 2; ++k) \
;         acc[ai][bj][m][n] = __builtin_amdgcn_mfma_f32_16x16x32_bf16(Bt[n][k], At[m][k], acc[ai][bj][m][n], 0, 0, 0); __builtin_amdgcn_s_setprio(0); } while (0)
; #define PG8_WAIT_V(n) asm volatile("s_waitcnt vmcnt(" #n ")" ::: "memory")
; template <class Epi, class Sched, bool ALIGN_EPI = false, bool SP2 = false>
; __device__ __forceinline__ void gemm_phase(PG8_LAS unsigned char* lds, const Gemm g, const Sched& S, const Epi& E) {
;     ...
;             PG8_LDB(B0, 0, 0); PG8_LDB(B1, 0, 1); PG8_SCHED; PG8_LDA(At, 0, 0); PG8_STAGE(PG8_SA(1, 1), a1 + hstep, voffA);
;             PG8_WAIT_V(8); PG8_WAIT_L(0); PG8_BAR; PG8_MMA(0, 0, At, B0); PG8_MMA(0, 1, At, B1); PG8_BAR; PG8_SCHED;
;             PG8_LDA(At, 0, 1); PG8_STAGE(PG8_SB(0, 0), b2, voffB); PG8_STAGE(PG8_SB(0, 1), b2 + hstep, voffB); PG8_STAGE(PG8_SA(0, 0), a2, voffA);
;             PG8_WAIT_V(8); PG8_WAIT_L(0); PG8_BAR; PG8_MMA(1, 0, At, B0); PG8_MMA(1, 1, At, B1); PG8_BAR; PG8_SCHED;
;             PG8_LDB(B0, 1, 0); PG8_LDB(B1, 1, 1); PG8_SCHED; PG8_LDA(At, 1, 0); PG8_STAGE(PG8_SA(0, 1), a2 + hstep, voffA);
;             PG8_WAIT_V(8); PG8_WAIT_L(0); PG8_BAR; PG8_MMA(0, 0, At, B0); PG8_MMA(0, 1, At, B1); PG8_BAR; PG8_SCHED;
;             PG8_LDA(At, 1, 1); PG8_STAGE(PG8_SB(1, 0), b3, voffB); PG8_STAGE(PG8_SB(1, 1), b3 + hstep, voffB); PG8_STAGE(PG8_SA(1, 0), a3, voffA);
;             PG8_WAIT_V(8); PG8_WAIT_L(0); PG8_BAR; PG8_MMA(1, 0, At, B0); PG8_MMA(1, 1, At, B1); PG8_BAR; PG8_SCHED;
	v_mfma_f32_16x16x32_bf16 v[124:127], v[146:149], v[192:195], v[124:127]
	v_mfma_f32_16x16x32_bf16 v[120:123], v[164:167], v[192:195], v[120:123]
	v_mfma_f32_16x16x32_bf16 v[108:111], v[146:149], v[200:203], v[108:111]
	v_mfma_f32_16x16x32_bf16 v[104:107], v[164:167], v[200:203], v[104:107]
	v_mfma_f32_16x16x32_bf16 v[92:95], v[146:149], v[208:211], v[92:95]
	v_mfma_f32_16x16x32_bf16 v[88:91], v[164:167], v[208:211], v[88:91]
	v_mfma_f32_16x16x32_bf16 v[76:79], v[146:149], v[216:219], v[76:79]
	v_mfma_f32_16x16x32_bf16 v[72:75], v[164:167], v[216:219], v[72:75]
	v_mfma_f32_16x16x32_bf16 v[124:127], v[150:153], v[196:199], v[124:127]
	v_mfma_f32_16x16x32_bf16 v[120:123], v[168:171], v[196:199], v[120:123]
	v_mfma_f32_16x16x32_bf16 v[108:111], v[150:153], v[204:207], v[108:111]
	v_mfma_f32_16x16x32_bf16 v[104:107], v[168:171], v[204:207], v[104:107]
	v_mfma_f32_16x16x32_bf16 v[92:95], v[150:153], v[212:215], v[92:95]
	v_mfma_f32_16x16x32_bf16 v[88:91], v[168:171], v[212:215], v[88:91]
	v_mfma_f32_16x16x32_bf16 v[76:79], v[150:153], v[220:223], v[76:79]
	v_mfma_f32_16x16x32_bf16 v[72:75], v[168:171], v[220:223], v[72:75]
	s_setprio 0
	s_setprio 1
	v_mfma_f32_16x16x32_bf16 v[116:119], v[172:175], v[192:195], v[116:119]
	v_mfma_f32_16x16x32_bf16 v[112:115], v[180:183], v[192:195], v[112:115]
	v_mfma_f32_16x16x32_bf16 v[100:103], v[172:175], v[200:203], v[100:103]
	v_mfma_f32_16x16x32_bf16 v[96:99], v[180:183], v[200:203], v[96:99]
	v_mfma_f32_16x16x32_bf16 v[84:87], v[172:175], v[208:211], v[84:87]
	v_mfma_f32_16x16x32_bf16 v[80:83], v[180:183], v[208:211], v[80:83]
	v_mfma_f32_16x16x32_bf16 v[68:71], v[172:175], v[216:219], v[68:71]
	v_mfma_f32_16x16x32_bf16 v[64:67], v[180:183], v[216:219], v[64:67]
	v_mfma_f32_16x16x32_bf16 v[116:119], v[176:179], v[196:199], v[116:119]
	v_mfma_f32_16x16x32_bf16 v[112:115], v[188:191], v[196:199], v[112:115]
	v_mfma_f32_16x16x32_bf16 v[100:103], v[176:179], v[204:207], v[100:103]
	v_mfma_f32_16x16x32_bf16 v[96:99], v[188:191], v[204:207], v[96:99]
	v_mfma_f32_16x16x32_bf16 v[84:87], v[176:179], v[212:215], v[84:87]
	v_mfma_f32_16x16x32_bf16 v[80:83], v[188:191], v[212:215], v[80:83]
	v_mfma_f32_16x16x32_bf16 v[68:71], v[176:179], v[220:223], v[68:71]
	s_setprio 2
	s_barrier
	v_mfma_f32_16x16x32_bf16 v[64:67], v[188:191], v[220:223], v[64:67]
	s_setprio 0
	s_add_i32 s47, s39, s28
	v_lshl_add_u64 v[154:155], s[24:25], 0, v[130:131]
	s_mov_b32 m0, s47
	ds_read_b128 v[192:195], v162 offset:16384
	ds_read_b128 v[196:199], v162 offset:17408
	ds_read_b128 v[200:203], v162 offset:18432
	ds_read_b128 v[204:207], v162 offset:19456
	ds_read_b128 v[208:211], v162 offset:20480
	ds_read_b128 v[212:215], v162 offset:21504
	ds_read_b128 v[216:219], v162 offset:22528
	ds_read_b128 v[220:223], v162 offset:23552
	global_load_lds_dwordx4 v[154:155], off
	s_add_i32 m0, s47, 0x2000
	s_add_u32 s48, s24, 0x40000
	v_lshl_add_u64 v[184:185], s[24:25], 0, v[134:135]
	s_addc_u32 s49, s25, 0
	s_add_i32 s47, s40, s28
	global_load_lds_dwordx4 v[184:185], off
	v_lshl_add_u64 v[224:225], s[48:49], 0, v[130:131]
	s_mov_b32 m0, s47
	v_lshl_add_u64 v[226:227], s[26:27], 0, v[132:133]
	global_load_lds_dwordx4 v[224:225], off
	v_lshl_add_u64 v[224:225], s[48:49], 0, v[134:135]
	s_add_i32 m0, s47, 0x2000
	s_nop 0
	global_load_lds_dwordx4 v[224:225], off
	v_lshl_add_u64 v[224:225], s[26:27], 0, v[128:129]
	s_mov_b32 m0, s31
	s_nop 0
	global_load_lds_dwordx4 v[224:225], off
	s_mov_b32 m0, s33
	s_nop 0
	global_load_lds_dwordx4 v[226:227], off
	s_setprio 1
	s_waitcnt vmcnt(8)
	s_waitcnt lgkmcnt(0)
	s_barrier
	v_mfma_f32_16x16x32_bf16 v[60:63], v[146:149], v[192:195], v[60:63]
	v_mfma_f32_16x16x32_bf16 v[56:59], v[164:167], v[192:195], v[56:59]
	v_mfma_f32_16x16x32_bf16 v[44:47], v[146:149], v[200:203], v[44:47]
	v_mfma_f32_16x16x32_bf16 v[40:43], v[164:167], v[200:203], v[40:43]
	v_mfma_f32_16x16x32_bf16 v[28:31], v[146:149], v[208:211], v[28:31]
	v_mfma_f32_16x16x32_bf16 v[24:27], v[164:167], v[208:211], v[24:27]
	v_mfma_f32_16x16x32_bf16 v[12:15], v[146:149], v[216:219], v[12:15]
	v_mfma_f32_16x16x32_bf16 v[8:11], v[164:167], v[216:219], v[8:11]
	v_mfma_f32_16x16x32_bf16 v[60:63], v[150:153], v[196:199], v[60:63]
	v_mfma_f32_16x16x32_bf16 v[56:59], v[168:171], v[196:199], v[56:59]
	v_mfma_f32_16x16x32_bf16 v[44:47], v[150:153], v[204:207], v[44:47]
	v_mfma_f32_16x16x32_bf16 v[40:43], v[168:171], v[204:207], v[40:43]
	v_mfma_f32_16x16x32_bf16 v[28:31], v[150:153], v[212:215], v[28:31]
	v_mfma_f32_16x16x32_bf16 v[24:27], v[168:171], v[212:215], v[24:27]
	v_mfma_f32_16x16x32_bf16 v[12:15], v[150:153], v[220:223], v[12:15]
	v_mfma_f32_16x16x32_bf16 v[8:11], v[168:171], v[220:223], v[8:11]
	s_setprio 0
	s_setprio 1
	v_mfma_f32_16x16x32_bf16 v[52:55], v[172:175], v[192:195], v[52:55]
	v_mfma_f32_16x16x32_bf16 v[48:51], v[180:183], v[192:195], v[48:51]
	v_mfma_f32_16x16x32_bf16 v[36:39], v[172:175], v[200:203], v[36:39]
	v_mfma_f32_16x16x32_bf16 v[32:35], v[180:183], v[200:203], v[32:35]
	v_mfma_f32_16x16x32_bf16 v[20:23], v[172:175], v[208:211], v[20:23]
	v_mfma_f32_16x16x32_bf16 v[16:19], v[180:183], v[208:211], v[16:19]
	v_mfma_f32_16x16x32_bf16 v[4:7], v[172:175], v[216:219], v[4:7]
	v_mfma_f32_16x16x32_bf16 v[0:3], v[180:183], v[216:219], v[0:3]
	v_mfma_f32_16x16x32_bf16 v[52:55], v[176:179], v[196:199], v[52:55]
	v_mfma_f32_16x16x32_bf16 v[48:51], v[188:191], v[196:199], v[48:51]
	v_mfma_f32_16x16x32_bf16 v[36:39], v[176:179], v[204:207], v[36:39]
	v_mfma_f32_16x16x32_bf16 v[32:35], v[188:191], v[204:207], v[32:35]
	v_mfma_f32_16x16x32_bf16 v[20:23], v[176:179], v[212:215], v[20:23]
	v_mfma_f32_16x16x32_bf16 v[16:19], v[188:191], v[212:215], v[16:19]
	v_mfma_f32_16x16x32_bf16 v[4:7], v[176:179], v[220:223], v[4:7]
	s_setprio 2
	s_barrier
; #define PG8_STAGE(bufoff, gbase, voff) do { _Pragma("unroll") for (int _i = 0; _i < 2; ++_i) \
;         __builtin_amdgcn_global_load_lds((const unsigned*)((const char*)(gbase) + (voff)[_i]), (PG8_LAS unsigned*)(lds + (bufoff) + ldsw + _i * 8192), 16, 0, 0); } while (0)
; #define PG8_LDA(dst, b, h) do { _Pragma("unroll") for (int m = 0; m < 4; ++m) _Pragma("unroll") for (int k = 0; k < 2; ++k) dst[m][k] = *(const PG8_LAS bf16x8*)(lds + PG8_SA(b, h) + aoff + m * 2048 + k * 1024); } while (0)
; #define PG8_LDB(dst, b, h) do { _Pragma("unroll") for (int n = 0; n < 2; ++n) _Pragma("unroll") for (int k = 0; k < 2; ++k) dst[n][k] = *(const PG8_LAS bf16x8*)(lds + PG8_SB(b, h) + boff + n * 2048 + k * 1024); } while (0)
; #define PG8_MMA(ai, bj, At, Bt) do { __builtin_amdgcn_s_setprio(1); _Pragma("unroll") for (int m = 0; m < 4; ++m) _Pragma("unroll") for (int n = 0; n < 2; ++n) _Pragma("unroll") for (int k = 0; k < 2; ++k) \
;         acc[ai][bj][m][n] = __builtin_amdgcn_mfma_f32_16x16x32_bf16(Bt[n][k], At[m][k], acc[ai][bj][m][n], 0, 0, 0); __builtin_amdgcn_s_setprio(0); } while (0)
; #define PG8_WAIT_V(n) asm volatile("s_waitcnt vmcnt(" #n ")" ::: "memory")
; template <class Epi, class Sched, bool ALIGN_EPI = false, bool SP2 = false>
; __device__ __forceinline__ void gemm_phase(PG8_LAS unsigned char* lds, const Gemm g, const Sched& S, const Epi& E) {
;     ...
;             PG8_LDB(B0, 0, 0); PG8_LDB(B1, 0, 1); PG8_SCHED; PG8_LDA(At, 0, 0); PG8_STAGE(PG8_SA(1, 1), a1 + hstep, voffA);
;             PG8_WAIT_V(8); PG8_WAIT_L(0); PG8_BAR; PG8_MMA(0, 0, At, B0); PG8_MMA(0, 1, At, B1); PG8_BAR; PG8_SCHED;
;             PG8_LDA(At, 0, 1); PG8_STAGE(PG8_SB(0, 0), b2, voffB); PG8_STAGE(PG8_SB(0, 1), b2 + hstep, voffB); PG8_STAGE(PG8_SA(0, 0), a2, voffA);
;             PG8_WAIT_V(8); PG8_WAIT_L(0); PG8_BAR; PG8_MMA(1, 0, At, B0); PG8_MMA(1, 1, At, B1); PG8_BAR; PG8_SCHED;
;             PG8_LDB(B0, 1, 0); PG8_LDB(B1, 1, 1); PG8_SCHED; PG8_LDA(At, 1, 0); PG8_STAGE(PG8_SA(0, 1), a2 + hstep, voffA);
;             PG8_WAIT_V(8); PG8_WAIT_L(0); PG8_BAR; PG8_MMA(0, 0, At, B0); PG8_MMA(0, 1, At, B1); PG8_BAR; PG8_SCHED;
;             PG8_LDA(At, 1, 1); PG8_STAGE(PG8_SB(1, 0), b3, voffB); PG8_STAGE(PG8_SB(1, 1), b3 + hstep, voffB); PG8_STAGE(PG8_SA(1, 0), a3, voffA);
;             PG8_WAIT_V(8); PG8_WAIT_L(0); PG8_BAR; PG8_MMA(1, 0, At, B0); PG8_MMA(1, 1, At, B1); PG8_BAR; PG8_SCHED;
	v_mfma_f32_16x16x32_bf16 v[0:3], v[188:191], v[220:223], v[0:3]
	s_setprio 0
	s_add_i32 s47, 0, 0x18000
	v_add_u32_e32 v136, s47, v157
	s_add_i32 s48, 0, 0x1c000
	ds_read_b128 v[146:149], v136
	ds_read_b128 v[150:153], v136 offset:1024
	ds_read_b128 v[164:167], v136 offset:2048
	ds_read_b128 v[168:171], v136 offset:3072
	v_add_u32_e32 v136, s48, v157
	ds_read_b128 v[172:175], v136
	ds_read_b128 v[176:179], v136 offset:1024
	ds_read_b128 v[180:183], v136 offset:2048
	ds_read_b128 v[188:191], v136 offset:3072
	s_add_u32 s26, s26, 0x40000
	s_addc_u32 s27, s27, 0
	s_mov_b32 m0, s34
	v_lshl_add_u64 v[228:229], s[26:27], 0, v[128:129]
	ds_read_b128 v[192:195], v162 offset:32768
	ds_read_b128 v[196:199], v162 offset:33792
	ds_read_b128 v[200:203], v162 offset:34816
	ds_read_b128 v[204:207], v162 offset:35840
	ds_read_b128 v[208:211], v162 offset:36864
	ds_read_b128 v[212:215], v162 offset:37888
	ds_read_b128 v[216:219], v162 offset:38912
	ds_read_b128 v[220:223], v162 offset:39936
	global_load_lds_dwordx4 v[228:229], off
	v_lshl_add_u64 v[228:229], s[26:27], 0, v[132:133]
	s_mov_b32 m0, s35
	s_nop 0
	global_load_lds_dwordx4 v[228:229], off
	s_setprio 1
	s_waitcnt vmcnt(8)
	s_waitcnt lgkmcnt(0)
	s_barrier
	v_mfma_f32_16x16x32_bf16 v[124:127], v[146:149], v[192:195], v[124:127]
	v_mfma_f32_16x16x32_bf16 v[120:123], v[164:167], v[192:195], v[120:123]
	v_mfma_f32_16x16x32_bf16 v[108:111], v[146:149], v[200:203], v[108:111]
	v_mfma_f32_16x16x32_bf16 v[104:107], v[164:167], v[200:203], v[104:107]
	v_mfma_f32_16x16x32_bf16 v[92:95], v[146:149], v[208:211], v[92:95]
	v_mfma_f32_16x16x32_bf16 v[88:91], v[164:167], v[208:211], v[88:91]
	v_mfma_f32_16x16x32_bf16 v[76:79], v[146:149], v[216:219], v[76:79]
	v_mfma_f32_16x16x32_bf16 v[72:75], v[164:167], v[216:219], v[72:75]
	v_mfma_f32_16x16x32_bf16 v[124:127], v[150:153], v[196:199], v[124:127]
	v_mfma_f32_16x16x32_bf16 v[120:123], v[168:171], v[196:199], v[120:123]
	v_mfma_f32_16x16x32_bf16 v[108:111], v[150:153], v[204:207], v[108:111]
	v_mfma_f32_16x16x32_bf16 v[104:107], v[168:171], v[204:207], v[104:107]
	v_mfma_f32_16x16x32_bf16 v[92:95], v[150:153], v[212:215], v[92:95]
	v_mfma_f32_16x16x32_bf16 v[88:91], v[168:171], v[212:215], v[88:91]
	v_mfma_f32_16x16x32_bf16 v[76:79], v[150:153], v[220:223], v[76:79]
	v_mfma_f32_16x16x32_bf16 v[72:75], v[168:171], v[220:223], v[72:75]
	s_setprio 0
	s_setprio 1
	v_mfma_f32_16x16x32_bf16 v[116:119], v[172:175], v[192:195], v[116:119]
	v_mfma_f32_16x16x32_bf16 v[112:115], v[180:183], v[192:195], v[112:115]
	v_mfma_f32_16x16x32_bf16 v[100:103], v[172:175], v[200:203], v[100:103]
	v_mfma_f32_16x16x32_bf16 v[96:99], v[180:183], v[200:203], v[96:99]
	v_mfma_f32_16x16x32_bf16 v[84:87], v[172:175], v[208:211], v[84:87]
	v_mfma_f32_16x16x32_bf16 v[80:83], v[180:183], v[208:211], v[80:83]
	v_mfma_f32_16x16x32_bf16 v[68:71], v[172:175], v[216:219], v[68:71]
	v_mfma_f32_16x16x32_bf16 v[64:67], v[180:183], v[216:219], v[64:67]
	v_mfma_f32_16x16x32_bf16 v[116:119], v[176:179], v[196:199], v[116:119]
	v_mfma_f32_16x16x32_bf16 v[112:115], v[188:191], v[196:199], v[112:115]
	v_mfma_f32_16x16x32_bf16 v[100:103], v[176:179], v[204:207], v[100:103]
	v_mfma_f32_16x16x32_bf16 v[96:99], v[188:191], v[204:207], v[96:99]
	v_mfma_f32_16x16x32_bf16 v[84:87], v[176:179], v[212:215], v[84:87]
	v_mfma_f32_16x16x32_bf16 v[80:83], v[188:191], v[212:215], v[80:83]
	v_mfma_f32_16x16x32_bf16 v[68:71], v[176:179], v[220:223], v[68:71]
	s_setprio 2
	s_barrier
; #define PG8_STAGE(bufoff, gbase, voff) do { _Pragma("unroll") for (int _i = 0; _i < 2; ++_i) \
;         __builtin_amdgcn_global_load_lds((const unsigned*)((const char*)(gbase) + (voff)[_i]), (PG8_LAS unsigned*)(lds + (bufoff) + ldsw + _i * 8192), 16, 0, 0); } while (0)
; #define PG8_LDA(dst, b, h) do { _Pragma("unroll") for (int m = 0; m < 4; ++m) _Pragma("unroll") for (int k = 0; k < 2; ++k) dst[m][k] = *(const PG8_LAS bf16x8*)(lds + PG8_SA(b, h) + aoff + m * 2048 + k * 1024); } while (0)
; #define PG8_LDB(dst, b, h) do { _Pragma("unroll") for (int n = 0; n < 2; ++n) _Pragma("unroll") for (int k = 0; k < 2; ++k) dst[n][k] = *(const PG8_LAS bf16x8*)(lds + PG8_SB(b, h) + boff + n * 2048 + k * 1024); } while (0)
; #define PG8_MMA(ai, bj, At, Bt) do { __builtin_amdgcn_s_setprio(1); _Pragma("unroll") for (int m = 0; m < 4; ++m) _Pragma("unroll") for (int n = 0; n < 2; ++n) _Pragma("unroll") for (int k = 0; k < 2; ++k) \
;         acc[ai][bj][m][n] = __builtin_amdgcn_mfma_f32_16x16x32_bf16(Bt[n][k], At[m][k], acc[ai][bj][m][n], 0, 0, 0); __builtin_amdgcn_s_setprio(0); } while (0)
; template <class Epi, class Sched, bool ALIGN_EPI = false, bool SP2 = false>
; __device__ __forceinline__ void gemm_phase(PG8_LAS unsigned char* lds, const Gemm g, const Sched& S, const Epi& E) {
;     ...
;             PG8_LDB(B0, 0, 0); PG8_LDB(B1, 0, 1); PG8_SCHED; PG8_LDA(At, 0, 0); PG8_STAGE(PG8_SA(1, 1), a1 + hstep, voffA);
;             PG8_WAIT_V(8); PG8_WAIT_L(0); PG8_BAR; PG8_MMA(0, 0, At, B0); PG8_MMA(0, 1, At, B1); PG8_BAR; PG8_SCHED;
;             PG8_LDA(At, 0, 1); PG8_STAGE(PG8_SB(0, 0), b2, voffB); PG8_STAGE(PG8_SB(0, 1), b2 + hstep, voffB); PG8_STAGE(PG8_SA(0, 0), a2, voffA);
;             PG8_WAIT_V(8); PG8_WAIT_L(0); PG8_BAR; PG8_MMA(1, 0, At, B0); PG8_MMA(1, 1, At, B1); PG8_BAR; PG8_SCHED;
;             PG8_LDB(B0, 1, 0); PG8_LDB(B1, 1, 1); PG8_SCHED; PG8_LDA(At, 1, 0); PG8_STAGE(PG8_SA(0, 1), a2 + hstep, voffA);
;             PG8_WAIT_V(8); PG8_WAIT_L(0); PG8_BAR; PG8_MMA(0, 0, At, B0); PG8_MMA(0, 1, At, B1); PG8_BAR; PG8_SCHED;
;             PG8_LDA(At, 1, 1); PG8_STAGE(PG8_SB(1, 0), b3, voffB); PG8_STAGE(PG8_SB(1, 1), b3 + hstep, voffB); PG8_STAGE(PG8_SA(1, 0), a3, voffA);
;             PG8_WAIT_V(8); PG8_WAIT_L(0); PG8_BAR; PG8_MMA(1, 0, At, B0); PG8_MMA(1, 1, At, B1); PG8_BAR; PG8_SCHED;
;     ...
;         if constexpr (ALIGN_EPI) { if (wr == 0) PG8_BAR; }
	v_mfma_f32_16x16x32_bf16 v[64:67], v[188:191], v[220:223], v[64:67]
	s_setprio 0
	s_add_i32 s26, s47, s28
	v_lshl_add_u64 v[154:155], v[154:155], 0, s[8:9]
	s_mov_b32 m0, s26
	ds_read_b128 v[192:195], v162 offset:49152
	ds_read_b128 v[196:199], v162 offset:50176
	ds_read_b128 v[200:203], v162 offset:51200
	ds_read_b128 v[204:207], v162 offset:52224
	ds_read_b128 v[208:211], v162 offset:53248
	ds_read_b128 v[212:215], v162 offset:54272
	ds_read_b128 v[216:219], v162 offset:55296
	ds_read_b128 v[220:223], v162 offset:56320
	global_load_lds_dwordx4 v[154:155], off
	s_add_i32 m0, s26, 0x2000
	s_add_u32 s24, s24, 0x40080
	v_lshl_add_u64 v[154:155], v[184:185], 0, s[8:9]
	s_addc_u32 s25, s25, 0
	s_add_i32 s26, s48, s28
	global_load_lds_dwordx4 v[154:155], off
	v_lshl_add_u64 v[154:155], s[24:25], 0, v[130:131]
	s_mov_b32 m0, s26
	s_nop 0
	global_load_lds_dwordx4 v[154:155], off
	v_lshl_add_u64 v[154:155], s[24:25], 0, v[134:135]
	s_add_i32 m0, s26, 0x2000
	s_nop 0
	global_load_lds_dwordx4 v[154:155], off
	v_lshl_add_u64 v[154:155], v[224:225], 0, s[8:9]
	s_mov_b32 m0, s36
	s_nop 0
	global_load_lds_dwordx4 v[154:155], off
	v_lshl_add_u64 v[154:155], v[226:227], 0, s[8:9]
	s_mov_b32 m0, s37
	s_nop 0
	global_load_lds_dwordx4 v[154:155], off
	s_setprio 1
	s_waitcnt vmcnt(8)
	s_waitcnt lgkmcnt(0)
	s_barrier
	v_mfma_f32_16x16x32_bf16 v[60:63], v[146:149], v[192:195], v[60:63]
	v_mfma_f32_16x16x32_bf16 v[56:59], v[164:167], v[192:195], v[56:59]
	v_mfma_f32_16x16x32_bf16 v[44:47], v[146:149], v[200:203], v[44:47]
	v_mfma_f32_16x16x32_bf16 v[40:43], v[164:167], v[200:203], v[40:43]
	v_mfma_f32_16x16x32_bf16 v[28:31], v[146:149], v[208:211], v[28:31]
	v_mfma_f32_16x16x32_bf16 v[24:27], v[164:167], v[208:211], v[24:27]
	v_mfma_f32_16x16x32_bf16 v[12:15], v[146:149], v[216:219], v[12:15]
	v_mfma_f32_16x16x32_bf16 v[8:11], v[164:167], v[216:219], v[8:11]
	v_mfma_f32_16x16x32_bf16 v[60:63], v[150:153], v[196:199], v[60:63]
	v_mfma_f32_16x16x32_bf16 v[56:59], v[168:171], v[196:199], v[56:59]
	v_mfma_f32_16x16x32_bf16 v[44:47], v[150:153], v[204:207], v[44:47]
	v_mfma_f32_16x16x32_bf16 v[40:43], v[168:171], v[204:207], v[40:43]
	v_mfma_f32_16x16x32_bf16 v[28:31], v[150:153], v[212:215], v[28:31]
	v_mfma_f32_16x16x32_bf16 v[24:27], v[168:171], v[212:215], v[24:27]
	v_mfma_f32_16x16x32_bf16 v[12:15], v[150:153], v[220:223], v[12:15]
	v_mfma_f32_16x16x32_bf16 v[8:11], v[168:171], v[220:223], v[8:11]
	s_setprio 0
	s_setprio 1
	v_mfma_f32_16x16x32_bf16 v[52:55], v[172:175], v[192:195], v[52:55]
	v_mfma_f32_16x16x32_bf16 v[48:51], v[180:183], v[192:195], v[48:51]
	v_mfma_f32_16x16x32_bf16 v[36:39], v[172:175], v[200:203], v[36:39]
	v_mfma_f32_16x16x32_bf16 v[32:35], v[180:183], v[200:203], v[32:35]
	v_mfma_f32_16x16x32_bf16 v[20:23], v[172:175], v[208:211], v[20:23]
	v_mfma_f32_16x16x32_bf16 v[16:19], v[180:183], v[208:211], v[16:19]
	v_mfma_f32_16x16x32_bf16 v[4:7], v[172:175], v[216:219], v[4:7]
	v_mfma_f32_16x16x32_bf16 v[0:3], v[180:183], v[216:219], v[0:3]
	v_mfma_f32_16x16x32_bf16 v[52:55], v[176:179], v[196:199], v[52:55]
	v_mfma_f32_16x16x32_bf16 v[48:51], v[188:191], v[196:199], v[48:51]
	v_mfma_f32_16x16x32_bf16 v[36:39], v[176:179], v[204:207], v[36:39]
	v_mfma_f32_16x16x32_bf16 v[32:35], v[188:191], v[204:207], v[32:35]
	v_mfma_f32_16x16x32_bf16 v[20:23], v[176:179], v[212:215], v[20:23]
	v_mfma_f32_16x16x32_bf16 v[16:19], v[188:191], v[212:215], v[16:19]
	v_mfma_f32_16x16x32_bf16 v[4:7], v[176:179], v[220:223], v[4:7]
	s_setprio 2
	s_barrier
	v_mfma_f32_16x16x32_bf16 v[0:3], v[188:191], v[220:223], v[0:3]
	s_setprio 0
	s_add_i32 s46, s46, 2
	s_add_u32 s22, s22, 0x100
	s_addc_u32 s23, s23, 0
	s_add_u32 s44, s44, 0x100
	s_addc_u32 s45, s45, 0
	s_cmp_gt_u32 s46, 13
	s_cbranch_scc0 .LBB0_572
	s_and_b64 vcc, exec, s[10:11]
	s_cbranch_vccz .LBB0_575
	s_barrier

;     __device__ __forceinline__ bool next(int i, Unit& u) const { if (!base.next(i >> 1, u)) return false; if (i & 1) { u.pm += 64; u.pn += 8; } return true; }
; #define PG8_STAGE(bufoff, gbase, voff) do { _Pragma("unroll") for (int _i = 0; _i < 2; ++_i) \
;         __builtin_amdgcn_global_load_lds((const unsigned*)((const char*)(gbase) + (voff)[_i]), (PG8_LAS unsigned*)(lds + (bufoff) + ldsw + _i * 8192), 16, 0, 0); } while (0)
; #define PG8_WAIT_V(n) asm volatile("s_waitcnt vmcnt(" #n ")" ::: "memory")
; template <class Epi, class Sched, bool ALIGN_EPI = false, bool SP2 = false>
; __device__ __forceinline__ void gemm_phase(PG8_LAS unsigned char* lds, const Gemm g, const Sched& S, const Epi& E) {
;     ...
;         const bool has_next = S.next(ui + 1, nxt);
;         const char* nA = has_next ? (const char*)g.A + (size_t)nxt.pm * tstep : cA; const char* nB = has_next ? (const char*)g.Bt + (size_t)nxt.pn * tstep : cB;
;         for (int t = 0; t < nt; t += 2) {
;             const bool last = (t == nt - 2);
;             const char* a1 = cA + (size_t)(t + 1) * kstep;
;             const char* a2 = last ? nA : cA + (size_t)(t + 2) * kstep; const char* b2 = last ? nB : cB + (size_t)(t + 2) * kstep;
;             const char* a3 = a2 + kstep; const char* b3 = b2 + kstep;
;             if (last && has_next) S.a_ready(nxt);
;             if constexpr (SP2) {
;             PG8_LDB(B0, 0, 0); PG8_LDB(B1, 0, 1); PG8_SCHED; PG8_LDA(At, 0, 0); PG8_STAGE(PG8_SA(1, 1), a1 + hstep, voffA);
;             PG8_WAIT_V(8); PG8_WAIT_L(0); PG8_BAR; PG8_MMA(0, 0, At, B0); PG8_MMA(0, 1, At, B1); PG8_BAR; PG8_SCHED;
;             PG8_LDA(At, 0, 1); PG8_STAGE(PG8_SB(0, 0), b2, voffB); PG8_STAGE(PG8_SB(0, 1), b2 + hstep, voffB); PG8_STAGE(PG8_SA(0, 0), a2, voffA);
;             PG8_WAIT_V(8); PG8_WAIT_L(0); PG8_BAR; PG8_MMA(1, 0, At, B0); PG8_MMA(1, 1, At, B1); PG8_BAR; PG8_SCHED;
;             PG8_LDB(B0, 1, 0); PG8_LDB(B1, 1, 1); PG8_SCHED; PG8_LDA(At, 1, 0); PG8_STAGE(PG8_SA(0, 1), a2 + hstep, voffA);
;             PG8_WAIT_V(8); PG8_WAIT_L(0); PG8_BAR; PG8_MMA(0, 0, At, B0); PG8_MMA(0, 1, At, B1); PG8_BAR; PG8_SCHED;
;             PG8_LDA(At, 1, 1); PG8_STAGE(PG8_SB(1, 0), b3, voffB); PG8_STAGE(PG8_SB(1, 1), b3 + hstep, voffB); PG8_STAGE(PG8_SA(1, 0), a3, voffA);
;             PG8_WAIT_V(8); PG8_WAIT_L(0); PG8_BAR; PG8_MMA(1, 0, At, B0); PG8_MMA(1, 1, At, B1); PG8_BAR; PG8_SCHED;
.LBB0_893:
	s_ashr_i32 s25, s24, 31
	s_lshl_b64 s[28:29], s[24:25], 20
	v_readlane_b32 s30, v236, 50
	v_readlane_b32 s31, v236, 51
	s_add_u32 s28, s30, s28
	s_addc_u32 s29, s31, s29
	s_and_b64 s[30:31], s[6:7], exec
	s_cselect_b32 s25, s29, s39
	s_cselect_b32 s35, s28, s38
	s_ashr_i32 s27, s26, 31
	s_lshl_b64 s[30:31], s[26:27], 20
	v_readlane_b32 s42, v236, 43
	v_readlane_b32 s43, v236, 44
	s_add_u32 s30, s42, s30
	s_addc_u32 s31, s43, s31
	s_and_b64 s[42:43], s[6:7], exec
	s_cselect_b32 s27, s31, s41
	s_cselect_b32 s55, s30, s40
	s_add_u32 s38, s38, 0x80080
	s_addc_u32 s39, s39, 0
	s_add_u32 s56, s40, 0x100
	s_addc_u32 s57, s41, 0
	s_mov_b32 s58, -2
	s_waitcnt lgkmcnt(0)
	ds_read_b128 v[72:75], v169
	ds_read_b128 v[84:87], v169 offset:1024
	ds_read_b128 v[92:95], v169 offset:2048
	ds_read_b128 v[96:99], v169 offset:3072
	ds_read_b128 v[156:159], v170
	ds_read_b128 v[160:163], v170 offset:1024
	ds_read_b128 v[174:177], v170 offset:2048
	ds_read_b128 v[178:181], v170 offset:3072
	s_add_u32 s40, s38, 0xfff80080
	s_addc_u32 s41, s39, -1
	s_cmp_eq_u32 s58, 28
	s_cselect_b32 s43, s25, s41
	s_cselect_b32 s42, s35, s40
	s_cselect_b32 s41, s27, s57
	s_cselect_b32 s40, s55, s56
	v_lshl_add_u64 v[164:165], s[38:39], 0, v[148:149]
	s_add_i32 m0, s37, 0xc000
	ds_read_b128 v[182:185], v171
	ds_read_b128 v[188:191], v171 offset:1024
	ds_read_b128 v[192:195], v171 offset:2048
	ds_read_b128 v[196:199], v171 offset:3072
	ds_read_b128 v[200:203], v171 offset:4096
	ds_read_b128 v[204:207], v171 offset:5120
	ds_read_b128 v[208:211], v171 offset:6144
	ds_read_b128 v[212:215], v171 offset:7168
	global_load_lds_dwordx4 v[164:165], off
	v_lshl_add_u64 v[164:165], s[38:39], 0, v[150:151]
	s_add_i32 m0, s37, 0xe000
	s_nop 0
	global_load_lds_dwordx4 v[164:165], off
	s_setprio 1
	s_waitcnt vmcnt(8)
	s_waitcnt lgkmcnt(0)
	s_barrier
	v_mfma_f32_16x16x32_bf16 v[140:143], v[72:75], v[182:185], 0
	v_mfma_f32_16x16x32_bf16 v[136:139], v[92:95], v[182:185], 0
	v_mfma_f32_16x16x32_bf16 v[124:127], v[72:75], v[192:195], 0
	v_mfma_f32_16x16x32_bf16 v[120:123], v[92:95], v[192:195], 0
	v_mfma_f32_16x16x32_bf16 v[108:111], v[72:75], v[200:203], 0
	v_mfma_f32_16x16x32_bf16 v[104:107], v[92:95], v[200:203], 0
	v_mfma_f32_16x16x32_bf16 v[80:83], v[72:75], v[208:211], 0
	v_mfma_f32_16x16x32_bf16 v[76:79], v[92:95], v[208:211], 0
	v_mfma_f32_16x16x32_bf16 v[140:143], v[84:87], v[188:191], v[140:143]
	v_mfma_f32_16x16x32_bf16 v[136:139], v[96:99], v[188:191], v[136:139]
	v_mfma_f32_16x16x32_bf16 v[124:127], v[84:87], v[196:199], v[124:127]
	v_mfma_f32_16x16x32_bf16 v[120:123], v[96:99], v[196:199], v[120:123]
	v_mfma_f32_16x16x32_bf16 v[108:111], v[84:87], v[204:207], v[108:111]
	v_mfma_f32_16x16x32_bf16 v[104:107], v[96:99], v[204:207], v[104:107]
	v_mfma_f32_16x16x32_bf16 v[80:83], v[84:87], v[212:215], v[80:83]
	v_mfma_f32_16x16x32_bf16 v[76:79], v[96:99], v[212:215], v[76:79]
	s_setprio 0
	s_setprio 1
	v_mfma_f32_16x16x32_bf16 v[132:135], v[156:159], v[182:185], 0
	v_mfma_f32_16x16x32_bf16 v[128:131], v[174:177], v[182:185], 0
	v_mfma_f32_16x16x32_bf16 v[116:119], v[156:159], v[192:195], 0
	v_mfma_f32_16x16x32_bf16 v[112:115], v[174:177], v[192:195], 0
	v_mfma_f32_16x16x32_bf16 v[100:103], v[156:159], v[200:203], 0
	v_mfma_f32_16x16x32_bf16 v[88:91], v[174:177], v[200:203], 0
	v_mfma_f32_16x16x32_bf16 v[68:71], v[156:159], v[208:211], 0
	v_mfma_f32_16x16x32_bf16 v[64:67], v[174:177], v[208:211], 0
	v_mfma_f32_16x16x32_bf16 v[132:135], v[160:163], v[188:191], v[132:135]
	v_mfma_f32_16x16x32_bf16 v[128:131], v[178:181], v[188:191], v[128:131]
	v_mfma_f32_16x16x32_bf16 v[116:119], v[160:163], v[196:199], v[116:119]
	v_mfma_f32_16x16x32_bf16 v[112:115], v[178:181], v[196:199], v[112:115]
	v_mfma_f32_16x16x32_bf16 v[100:103], v[160:163], v[204:207], v[100:103]
	v_mfma_f32_16x16x32_bf16 v[88:91], v[178:181], v[204:207], v[88:91]
	v_mfma_f32_16x16x32_bf16 v[68:71], v[160:163], v[212:215], v[68:71]
	s_setprio 2
	s_barrier
	v_mfma_f32_16x16x32_bf16 v[64:67], v[178:181], v[212:215], v[64:67]
	s_setprio 0
	s_add_i32 s59, s53, s33
	v_lshl_add_u64 v[164:165], s[40:41], 0, v[144:145]
	s_mov_b32 m0, s59
	ds_read_b128 v[182:185], v171 offset:16384
	ds_read_b128 v[188:191], v171 offset:17408
	ds_read_b128 v[192:195], v171 offset:18432
	ds_read_b128 v[196:199], v171 offset:19456
	ds_read_b128 v[200:203], v171 offset:20480
	ds_read_b128 v[204:207], v171 offset:21504
	ds_read_b128 v[208:211], v171 offset:22528
	ds_read_b128 v[212:215], v171 offset:23552
	global_load_lds_dwordx4 v[164:165], off
	s_add_i32 m0, s59, 0x2000
	s_add_u32 s60, s40, 0x80000
	v_lshl_add_u64 v[216:217], s[40:41], 0, v[146:147]
	s_addc_u32 s61, s41, 0
	s_add_i32 s59, s54, s33
	global_load_lds_dwordx4 v[216:217], off
	v_lshl_add_u64 v[218:219], s[60:61], 0, v[144:145]
	s_mov_b32 m0, s59
	v_lshl_add_u64 v[220:221], s[42:43], 0, v[146:147]
	global_load_lds_dwordx4 v[218:219], off
	v_lshl_add_u64 v[218:219], s[60:61], 0, v[146:147]
	s_add_i32 m0, s59, 0x2000
	s_nop 0
	global_load_lds_dwordx4 v[218:219], off
	v_lshl_add_u64 v[218:219], s[42:43], 0, v[144:145]
	s_mov_b32 m0, s37
	s_nop 0
	global_load_lds_dwordx4 v[218:219], off
	s_mov_b32 m0, s44
	s_nop 0
	global_load_lds_dwordx4 v[220:221], off
	s_setprio 1
	s_waitcnt vmcnt(8)
	s_waitcnt lgkmcnt(0)
	s_barrier
; #define PG8_STAGE(bufoff, gbase, voff) do { _Pragma("unroll") for (int _i = 0; _i < 2; ++_i) \
;         __builtin_amdgcn_global_load_lds((const unsigned*)((const char*)(gbase) + (voff)[_i]), (PG8_LAS unsigned*)(lds + (bufoff) + ldsw + _i * 8192), 16, 0, 0); } while (0)
; #define PG8_LDA(dst, b, h) do { _Pragma("unroll") for (int m = 0; m < 4; ++m) _Pragma("unroll") for (int k = 0; k < 2; ++k) dst[m][k] = *(const PG8_LAS bf16x8*)(lds + PG8_SA(b, h) + aoff + m * 2048 + k * 1024); } while (0)
; #define PG8_LDB(dst, b, h) do { _Pragma("unroll") for (int n = 0; n < 2; ++n) _Pragma("unroll") for (int k = 0; k < 2; ++k) dst[n][k] = *(const PG8_LAS bf16x8*)(lds + PG8_SB(b, h) + boff + n * 2048 + k * 1024); } while (0)
; #define PG8_MMA(ai, bj, At, Bt) do { __builtin_amdgcn_s_setprio(1); _Pragma("unroll") for (int m = 0; m < 4; ++m) _Pragma("unroll") for (int n = 0; n < 2; ++n) _Pragma("unroll") for (int k = 0; k < 2; ++k) \
;         acc[ai][bj][m][n] = __builtin_amdgcn_mfma_f32_16x16x32_bf16(Bt[n][k], At[m][k], acc[ai][bj][m][n], 0, 0, 0); __builtin_amdgcn_s_setprio(0); } while (0)
; #define PG8_WAIT_V(n) asm volatile("s_waitcnt vmcnt(" #n ")" ::: "memory")
; template <class Epi, class Sched, bool ALIGN_EPI = false, bool SP2 = false>
; __device__ __forceinline__ void gemm_phase(PG8_LAS unsigned char* lds, const Gemm g, const Sched& S, const Epi& E) {
;     ...
;             PG8_LDB(B0, 0, 0); PG8_LDB(B1, 0, 1); PG8_SCHED; PG8_LDA(At, 0, 0); PG8_STAGE(PG8_SA(1, 1), a1 + hstep, voffA);
;             PG8_WAIT_V(8); PG8_WAIT_L(0); PG8_BAR; PG8_MMA(0, 0, At, B0); PG8_MMA(0, 1, At, B1); PG8_BAR; PG8_SCHED;
;             PG8_LDA(At, 0, 1); PG8_STAGE(PG8_SB(0, 0), b2, voffB); PG8_STAGE(PG8_SB(0, 1), b2 + hstep, voffB); PG8_STAGE(PG8_SA(0, 0), a2, voffA);
;             PG8_WAIT_V(8); PG8_WAIT_L(0); PG8_BAR; PG8_MMA(1, 0, At, B0); PG8_MMA(1, 1, At, B1); PG8_BAR; PG8_SCHED;
;             PG8_LDB(B0, 1, 0); PG8_LDB(B1, 1, 1); PG8_SCHED; PG8_LDA(At, 1, 0); PG8_STAGE(PG8_SA(0, 1), a2 + hstep, voffA);
;             PG8_WAIT_V(8); PG8_WAIT_L(0); PG8_BAR; PG8_MMA(0, 0, At, B0); PG8_MMA(0, 1, At, B1); PG8_BAR; PG8_SCHED;
;             PG8_LDA(At, 1, 1); PG8_STAGE(PG8_SB(1, 0), b3, voffB); PG8_STAGE(PG8_SB(1, 1), b3 + hstep, voffB); PG8_STAGE(PG8_SA(1, 0), a3, voffA);
;             PG8_WAIT_V(8); PG8_WAIT_L(0); PG8_BAR; PG8_MMA(1, 0, At, B0); PG8_MMA(1, 1, At, B1); PG8_BAR; PG8_SCHED;
	v_mfma_f32_16x16x32_bf16 v[60:63], v[72:75], v[182:185], 0
	v_mfma_f32_16x16x32_bf16 v[56:59], v[92:95], v[182:185], 0
	v_mfma_f32_16x16x32_bf16 v[44:47], v[72:75], v[192:195], 0
	v_mfma_f32_16x16x32_bf16 v[40:43], v[92:95], v[192:195], 0
	v_mfma_f32_16x16x32_bf16 v[28:31], v[72:75], v[200:203], 0
	v_mfma_f32_16x16x32_bf16 v[24:27], v[92:95], v[200:203], 0
	v_mfma_f32_16x16x32_bf16 v[12:15], v[72:75], v[208:211], 0
	v_mfma_f32_16x16x32_bf16 v[8:11], v[92:95], v[208:211], 0
	v_mfma_f32_16x16x32_bf16 v[60:63], v[84:87], v[188:191], v[60:63]
	v_mfma_f32_16x16x32_bf16 v[56:59], v[96:99], v[188:191], v[56:59]
	v_mfma_f32_16x16x32_bf16 v[44:47], v[84:87], v[196:199], v[44:47]
	v_mfma_f32_16x16x32_bf16 v[40:43], v[96:99], v[196:199], v[40:43]
	v_mfma_f32_16x16x32_bf16 v[28:31], v[84:87], v[204:207], v[28:31]
	v_mfma_f32_16x16x32_bf16 v[24:27], v[96:99], v[204:207], v[24:27]
	v_mfma_f32_16x16x32_bf16 v[12:15], v[84:87], v[212:215], v[12:15]
	v_mfma_f32_16x16x32_bf16 v[8:11], v[96:99], v[212:215], v[8:11]
	s_setprio 0
	s_setprio 1
	v_mfma_f32_16x16x32_bf16 v[52:55], v[156:159], v[182:185], 0
	v_mfma_f32_16x16x32_bf16 v[48:51], v[174:177], v[182:185], 0
	v_mfma_f32_16x16x32_bf16 v[36:39], v[156:159], v[192:195], 0
	v_mfma_f32_16x16x32_bf16 v[32:35], v[174:177], v[192:195], 0
	v_mfma_f32_16x16x32_bf16 v[20:23], v[156:159], v[200:203], 0
	v_mfma_f32_16x16x32_bf16 v[16:19], v[174:177], v[200:203], 0
	v_mfma_f32_16x16x32_bf16 v[4:7], v[156:159], v[208:211], 0
	v_mfma_f32_16x16x32_bf16 v[0:3], v[174:177], v[208:211], 0
	v_mfma_f32_16x16x32_bf16 v[52:55], v[160:163], v[188:191], v[52:55]
	v_mfma_f32_16x16x32_bf16 v[48:51], v[178:181], v[188:191], v[48:51]
	v_mfma_f32_16x16x32_bf16 v[36:39], v[160:163], v[196:199], v[36:39]
	v_mfma_f32_16x16x32_bf16 v[32:35], v[178:181], v[196:199], v[32:35]
	v_mfma_f32_16x16x32_bf16 v[20:23], v[160:163], v[204:207], v[20:23]
	v_mfma_f32_16x16x32_bf16 v[16:19], v[178:181], v[204:207], v[16:19]
	v_mfma_f32_16x16x32_bf16 v[4:7], v[160:163], v[212:215], v[4:7]
	s_setprio 2
	s_barrier
	v_mfma_f32_16x16x32_bf16 v[0:3], v[178:181], v[212:215], v[0:3]
	s_setprio 0
	s_add_i32 s59, 0, 0x18000
	s_add_i32 s60, 0, 0x1c000
	v_add_u32_e32 v96, s59, v167
	v_add_u32_e32 v173, s60, v167
	ds_read_b128 v[72:75], v96
	ds_read_b128 v[84:87], v96 offset:1024
	ds_read_b128 v[92:95], v96 offset:2048
	ds_read_b128 v[96:99], v96 offset:3072
	ds_read_b128 v[156:159], v173
	ds_read_b128 v[160:163], v173 offset:1024
	ds_read_b128 v[174:177], v173 offset:2048
	ds_read_b128 v[178:181], v173 offset:3072
	s_add_u32 s42, s42, 0x80000
	s_addc_u32 s43, s43, 0
	s_mov_b32 m0, s45
	v_lshl_add_u64 v[222:223], s[42:43], 0, v[144:145]
	ds_read_b128 v[182:185], v171 offset:32768
	ds_read_b128 v[188:191], v171 offset:33792
	ds_read_b128 v[192:195], v171 offset:34816
	ds_read_b128 v[196:199], v171 offset:35840
	ds_read_b128 v[200:203], v171 offset:36864
	ds_read_b128 v[204:207], v171 offset:37888
	ds_read_b128 v[208:211], v171 offset:38912
	ds_read_b128 v[212:215], v171 offset:39936
	global_load_lds_dwordx4 v[222:223], off
	v_lshl_add_u64 v[222:223], s[42:43], 0, v[146:147]
	s_mov_b32 m0, s46
	s_nop 0
	global_load_lds_dwordx4 v[222:223], off
	s_setprio 1
	s_waitcnt vmcnt(8)
	s_waitcnt lgkmcnt(0)
	s_barrier
	v_mfma_f32_16x16x32_bf16 v[140:143], v[72:75], v[182:185], v[140:143]
	v_mfma_f32_16x16x32_bf16 v[136:139], v[92:95], v[182:185], v[136:139]
	v_mfma_f32_16x16x32_bf16 v[124:127], v[72:75], v[192:195], v[124:127]
	v_mfma_f32_16x16x32_bf16 v[120:123], v[92:95], v[192:195], v[120:123]
	v_mfma_f32_16x16x32_bf16 v[108:111], v[72:75], v[200:203], v[108:111]
	v_mfma_f32_16x16x32_bf16 v[104:107], v[92:95], v[200:203], v[104:107]
	v_mfma_f32_16x16x32_bf16 v[80:83], v[72:75], v[208:211], v[80:83]
	v_mfma_f32_16x16x32_bf16 v[76:79], v[92:95], v[208:211], v[76:79]
	v_mfma_f32_16x16x32_bf16 v[140:143], v[84:87], v[188:191], v[140:143]
	v_mfma_f32_16x16x32_bf16 v[136:139], v[96:99], v[188:191], v[136:139]
	v_mfma_f32_16x16x32_bf16 v[124:127], v[84:87], v[196:199], v[124:127]
	v_mfma_f32_16x16x32_bf16 v[120:123], v[96:99], v[196:199], v[120:123]
	v_mfma_f32_16x16x32_bf16 v[108:111], v[84:87], v[204:207], v[108:111]
	v_mfma_f32_16x16x32_bf16 v[104:107], v[96:99], v[204:207], v[104:107]
	v_mfma_f32_16x16x32_bf16 v[80:83], v[84:87], v[212:215], v[80:83]
	v_mfma_f32_16x16x32_bf16 v[76:79], v[96:99], v[212:215], v[76:79]
	s_setprio 0
	s_setprio 1
	v_mfma_f32_16x16x32_bf16 v[132:135], v[156:159], v[182:185], v[132:135]
	v_mfma_f32_16x16x32_bf16 v[128:131], v[174:177], v[182:185], v[128:131]
	v_mfma_f32_16x16x32_bf16 v[116:119], v[156:159], v[192:195], v[116:119]
	v_mfma_f32_16x16x32_bf16 v[112:115], v[174:177], v[192:195], v[112:115]
	v_mfma_f32_16x16x32_bf16 v[100:103], v[156:159], v[200:203], v[100:103]
	v_mfma_f32_16x16x32_bf16 v[88:91], v[174:177], v[200:203], v[88:91]
	v_mfma_f32_16x16x32_bf16 v[68:71], v[156:159], v[208:211], v[68:71]
	v_mfma_f32_16x16x32_bf16 v[64:67], v[174:177], v[208:211], v[64:67]
	v_mfma_f32_16x16x32_bf16 v[132:135], v[160:163], v[188:191], v[132:135]
	v_mfma_f32_16x16x32_bf16 v[128:131], v[178:181], v[188:191], v[128:131]
	v_mfma_f32_16x16x32_bf16 v[116:119], v[160:163], v[196:199], v[116:119]
	v_mfma_f32_16x16x32_bf16 v[112:115], v[178:181], v[196:199], v[112:115]
	v_mfma_f32_16x16x32_bf16 v[100:103], v[160:163], v[204:207], v[100:103]
	v_mfma_f32_16x16x32_bf16 v[88:91], v[178:181], v[204:207], v[88:91]
	v_mfma_f32_16x16x32_bf16 v[68:71], v[160:163], v[212:215], v[68:71]
	s_setprio 2
	s_barrier
; #define PG8_STAGE(bufoff, gbase, voff) do { _Pragma("unroll") for (int _i = 0; _i < 2; ++_i) \
;         __builtin_amdgcn_global_load_lds((const unsigned*)((const char*)(gbase) + (voff)[_i]), (PG8_LAS unsigned*)(lds + (bufoff) + ldsw + _i * 8192), 16, 0, 0); } while (0)
; #define PG8_LDA(dst, b, h) do { _Pragma("unroll") for (int m = 0; m < 4; ++m) _Pragma("unroll") for (int k = 0; k < 2; ++k) dst[m][k] = *(const PG8_LAS bf16x8*)(lds + PG8_SA(b, h) + aoff + m * 2048 + k * 1024); } while (0)
; #define PG8_LDB(dst, b, h) do { _Pragma("unroll") for (int n = 0; n < 2; ++n) _Pragma("unroll") for (int k = 0; k < 2; ++k) dst[n][k] = *(const PG8_LAS bf16x8*)(lds + PG8_SB(b, h) + boff + n * 2048 + k * 1024); } while (0)
; #define PG8_MMA(ai, bj, At, Bt) do { __builtin_amdgcn_s_setprio(1); _Pragma("unroll") for (int m = 0; m < 4; ++m) _Pragma("unroll") for (int n = 0; n < 2; ++n) _Pragma("unroll") for (int k = 0; k < 2; ++k) \
;         acc[ai][bj][m][n] = __builtin_amdgcn_mfma_f32_16x16x32_bf16(Bt[n][k], At[m][k], acc[ai][bj][m][n], 0, 0, 0); __builtin_amdgcn_s_setprio(0); } while (0)
; #define PG8_WAIT_V(n) asm volatile("s_waitcnt vmcnt(" #n ")" ::: "memory")
; template <class Epi, class Sched, bool ALIGN_EPI = false, bool SP2 = false>
; __device__ __forceinline__ void gemm_phase(PG8_LAS unsigned char* lds, const Gemm g, const Sched& S, const Epi& E) {
;     ...
;             PG8_LDB(B0, 0, 0); PG8_LDB(B1, 0, 1); PG8_SCHED; PG8_LDA(At, 0, 0); PG8_STAGE(PG8_SA(1, 1), a1 + hstep, voffA);
;             PG8_WAIT_V(8); PG8_WAIT_L(0); PG8_BAR; PG8_MMA(0, 0, At, B0); PG8_MMA(0, 1, At, B1); PG8_BAR; PG8_SCHED;
;             PG8_LDA(At, 0, 1); PG8_STAGE(PG8_SB(0, 0), b2, voffB); PG8_STAGE(PG8_SB(0, 1), b2 + hstep, voffB); PG8_STAGE(PG8_SA(0, 0), a2, voffA);
;             PG8_WAIT_V(8); PG8_WAIT_L(0); PG8_BAR; PG8_MMA(1, 0, At, B0); PG8_MMA(1, 1, At, B1); PG8_BAR; PG8_SCHED;
;             PG8_LDB(B0, 1, 0); PG8_LDB(B1, 1, 1); PG8_SCHED; PG8_LDA(At, 1, 0); PG8_STAGE(PG8_SA(0, 1), a2 + hstep, voffA);
;             PG8_WAIT_V(8); PG8_WAIT_L(0); PG8_BAR; PG8_MMA(0, 0, At, B0); PG8_MMA(0, 1, At, B1); PG8_BAR; PG8_SCHED;
;             PG8_LDA(At, 1, 1); PG8_STAGE(PG8_SB(1, 0), b3, voffB); PG8_STAGE(PG8_SB(1, 1), b3 + hstep, voffB); PG8_STAGE(PG8_SA(1, 0), a3, voffA);
;             PG8_WAIT_V(8); PG8_WAIT_L(0); PG8_BAR; PG8_MMA(1, 0, At, B0); PG8_MMA(1, 1, At, B1); PG8_BAR; PG8_SCHED;
	v_mfma_f32_16x16x32_bf16 v[64:67], v[178:181], v[212:215], v[64:67]
	s_setprio 0
	s_add_i32 s42, s59, s33
	v_lshl_add_u64 v[164:165], v[164:165], 0, s[12:13]
	s_mov_b32 m0, s42
	ds_read_b128 v[182:185], v171 offset:49152
	ds_read_b128 v[188:191], v171 offset:50176
	ds_read_b128 v[192:195], v171 offset:51200
	ds_read_b128 v[196:199], v171 offset:52224
	ds_read_b128 v[200:203], v171 offset:53248
	ds_read_b128 v[204:207], v171 offset:54272
	ds_read_b128 v[208:211], v171 offset:55296
	ds_read_b128 v[212:215], v171 offset:56320
	global_load_lds_dwordx4 v[164:165], off
	s_add_i32 m0, s42, 0x2000
	s_add_u32 s40, s40, 0x80080
	v_lshl_add_u64 v[164:165], v[216:217], 0, s[12:13]
	s_addc_u32 s41, s41, 0
	s_add_i32 s42, s60, s33
	global_load_lds_dwordx4 v[164:165], off
	v_lshl_add_u64 v[164:165], s[40:41], 0, v[144:145]
	s_mov_b32 m0, s42
	s_nop 0
	global_load_lds_dwordx4 v[164:165], off
	v_lshl_add_u64 v[164:165], s[40:41], 0, v[146:147]
	s_add_i32 m0, s42, 0x2000
	s_nop 0
	global_load_lds_dwordx4 v[164:165], off
	v_lshl_add_u64 v[164:165], v[218:219], 0, s[12:13]
	s_mov_b32 m0, s50
	s_nop 0
	global_load_lds_dwordx4 v[164:165], off
	v_lshl_add_u64 v[164:165], v[220:221], 0, s[12:13]
	s_mov_b32 m0, s51
	s_nop 0
	global_load_lds_dwordx4 v[164:165], off
	s_setprio 1
	s_waitcnt vmcnt(8)
	s_waitcnt lgkmcnt(0)
	s_barrier
	v_mfma_f32_16x16x32_bf16 v[60:63], v[72:75], v[182:185], v[60:63]
	v_mfma_f32_16x16x32_bf16 v[56:59], v[92:95], v[182:185], v[56:59]
	v_mfma_f32_16x16x32_bf16 v[44:47], v[72:75], v[192:195], v[44:47]
	v_mfma_f32_16x16x32_bf16 v[40:43], v[92:95], v[192:195], v[40:43]
	v_mfma_f32_16x16x32_bf16 v[28:31], v[72:75], v[200:203], v[28:31]
	v_mfma_f32_16x16x32_bf16 v[24:27], v[92:95], v[200:203], v[24:27]
	v_mfma_f32_16x16x32_bf16 v[12:15], v[72:75], v[208:211], v[12:15]
	v_mfma_f32_16x16x32_bf16 v[8:11], v[92:95], v[208:211], v[8:11]
	v_mfma_f32_16x16x32_bf16 v[60:63], v[84:87], v[188:191], v[60:63]
	v_mfma_f32_16x16x32_bf16 v[56:59], v[96:99], v[188:191], v[56:59]
	v_mfma_f32_16x16x32_bf16 v[44:47], v[84:87], v[196:199], v[44:47]
	v_mfma_f32_16x16x32_bf16 v[40:43], v[96:99], v[196:199], v[40:43]
	v_mfma_f32_16x16x32_bf16 v[28:31], v[84:87], v[204:207], v[28:31]
	v_mfma_f32_16x16x32_bf16 v[24:27], v[96:99], v[204:207], v[24:27]
	v_mfma_f32_16x16x32_bf16 v[12:15], v[84:87], v[212:215], v[12:15]
	v_mfma_f32_16x16x32_bf16 v[8:11], v[96:99], v[212:215], v[8:11]
	s_setprio 0
	s_setprio 1
	v_mfma_f32_16x16x32_bf16 v[52:55], v[156:159], v[182:185], v[52:55]
	v_mfma_f32_16x16x32_bf16 v[48:51], v[174:177], v[182:185], v[48:51]
	v_mfma_f32_16x16x32_bf16 v[36:39], v[156:159], v[192:195], v[36:39]
	v_mfma_f32_16x16x32_bf16 v[32:35], v[174:177], v[192:195], v[32:35]
	v_mfma_f32_16x16x32_bf16 v[20:23], v[156:159], v[200:203], v[20:23]
	v_mfma_f32_16x16x32_bf16 v[16:19], v[174:177], v[200:203], v[16:19]
	v_mfma_f32_16x16x32_bf16 v[4:7], v[156:159], v[208:211], v[4:7]
	v_mfma_f32_16x16x32_bf16 v[0:3], v[174:177], v[208:211], v[0:3]
	v_mfma_f32_16x16x32_bf16 v[52:55], v[160:163], v[188:191], v[52:55]
	v_mfma_f32_16x16x32_bf16 v[48:51], v[178:181], v[188:191], v[48:51]
	v_mfma_f32_16x16x32_bf16 v[36:39], v[160:163], v[196:199], v[36:39]
	v_mfma_f32_16x16x32_bf16 v[32:35], v[178:181], v[196:199], v[32:35]
	v_mfma_f32_16x16x32_bf16 v[20:23], v[160:163], v[204:207], v[20:23]
	v_mfma_f32_16x16x32_bf16 v[16:19], v[178:181], v[204:207], v[16:19]
	v_mfma_f32_16x16x32_bf16 v[4:7], v[160:163], v[212:215], v[4:7]
	s_setprio 2
	s_barrier
	v_mfma_f32_16x16x32_bf16 v[0:3], v[178:181], v[212:215], v[0:3]
	s_setprio 0
	s_add_i32 s58, s58, 2
	s_add_u32 s38, s38, 0x100
	s_addc_u32 s39, s39, 0
	s_add_u32 s56, s56, 0x100
	s_addc_u32 s57, s57, 0
	s_cmp_gt_u32 s58, 29
.LBB0_894:
	ds_read_b128 v[72:75], v169
	ds_read_b128 v[84:87], v169 offset:1024
	ds_read_b128 v[92:95], v169 offset:2048
	ds_read_b128 v[96:99], v169 offset:3072
	ds_read_b128 v[156:159], v170
	ds_read_b128 v[160:163], v170 offset:1024
	ds_read_b128 v[174:177], v170 offset:2048
	ds_read_b128 v[178:181], v170 offset:3072
	s_add_u32 s40, s38, 0xfff80080
	s_addc_u32 s41, s39, -1
	s_cmp_eq_u32 s58, 28
	s_cselect_b32 s43, s25, s41
	s_cselect_b32 s42, s35, s40
	s_cselect_b32 s41, s27, s57
	s_cselect_b32 s40, s55, s56
	v_lshl_add_u64 v[164:165], s[38:39], 0, v[148:149]
	s_add_i32 m0, s37, 0xc000
	ds_read_b128 v[182:185], v171
	ds_read_b128 v[188:191], v171 offset:1024
	ds_read_b128 v[192:195], v171 offset:2048
	ds_read_b128 v[196:199], v171 offset:3072
	ds_read_b128 v[200:203], v171 offset:4096
	ds_read_b128 v[204:207], v171 offset:5120
	ds_read_b128 v[208:211], v171 offset:6144
	ds_read_b128 v[212:215], v171 offset:7168
	global_load_lds_dwordx4 v[164:165], off
	v_lshl_add_u64 v[164:165], s[38:39], 0, v[150:151]
	s_add_i32 m0, s37, 0xe000
	s_nop 0
	global_load_lds_dwordx4 v[164:165], off
	s_setprio 1
	s_waitcnt vmcnt(8)
	s_waitcnt lgkmcnt(0)
	s_barrier
; #define PG8_STAGE(bufoff, gbase, voff) do { _Pragma("unroll") for (int _i = 0; _i < 2; ++_i) \
;         __builtin_amdgcn_global_load_lds((const unsigned*)((const char*)(gbase) + (voff)[_i]), (PG8_LAS unsigned*)(lds + (bufoff) + ldsw + _i * 8192), 16, 0, 0); } while (0)
; #define PG8_LDA(dst, b, h) do { _Pragma("unroll") for (int m = 0; m < 4; ++m) _Pragma("unroll") for (int k = 0; k < 2; ++k) dst[m][k] = *(const PG8_LAS bf16x8*)(lds + PG8_SA(b, h) + aoff + m * 2048 + k * 1024); } while (0)
; #define PG8_LDB(dst, b, h) do { _Pragma("unroll") for (int n = 0; n < 2; ++n) _Pragma("unroll") for (int k = 0; k < 2; ++k) dst[n][k] = *(const PG8_LAS bf16x8*)(lds + PG8_SB(b, h) + boff + n * 2048 + k * 1024); } while (0)
; #define PG8_MMA(ai, bj, At, Bt) do { __builtin_amdgcn_s_setprio(1); _Pragma("unroll") for (int m = 0; m < 4; ++m) _Pragma("unroll") for (int n = 0; n < 2; ++n) _Pragma("unroll") for (int k = 0; k < 2; ++k) \
;         acc[ai][bj][m][n] = __builtin_amdgcn_mfma_f32_16x16x32_bf16(Bt[n][k], At[m][k], acc[ai][bj][m][n], 0, 0, 0); __builtin_amdgcn_s_setprio(0); } while (0)
; #define PG8_WAIT_V(n) asm volatile("s_waitcnt vmcnt(" #n ")" ::: "memory")
; template <class Epi, class Sched, bool ALIGN_EPI = false, bool SP2 = false>
; __device__ __forceinline__ void gemm_phase(PG8_LAS unsigned char* lds, const Gemm g, const Sched& S, const Epi& E) {
;     ...
;             PG8_LDB(B0, 0, 0); PG8_LDB(B1, 0, 1); PG8_SCHED; PG8_LDA(At, 0, 0); PG8_STAGE(PG8_SA(1, 1), a1 + hstep, voffA);
;             PG8_WAIT_V(8); PG8_WAIT_L(0); PG8_BAR; PG8_MMA(0, 0, At, B0); PG8_MMA(0, 1, At, B1); PG8_BAR; PG8_SCHED;
;             PG8_LDA(At, 0, 1); PG8_STAGE(PG8_SB(0, 0), b2, voffB); PG8_STAGE(PG8_SB(0, 1), b2 + hstep, voffB); PG8_STAGE(PG8_SA(0, 0), a2, voffA);
;             PG8_WAIT_V(8); PG8_WAIT_L(0); PG8_BAR; PG8_MMA(1, 0, At, B0); PG8_MMA(1, 1, At, B1); PG8_BAR; PG8_SCHED;
;             PG8_LDB(B0, 1, 0); PG8_LDB(B1, 1, 1); PG8_SCHED; PG8_LDA(At, 1, 0); PG8_STAGE(PG8_SA(0, 1), a2 + hstep, voffA);
;             PG8_WAIT_V(8); PG8_WAIT_L(0); PG8_BAR; PG8_MMA(0, 0, At, B0); PG8_MMA(0, 1, At, B1); PG8_BAR; PG8_SCHED;
;             PG8_LDA(At, 1, 1); PG8_STAGE(PG8_SB(1, 0), b3, voffB); PG8_STAGE(PG8_SB(1, 1), b3 + hstep, voffB); PG8_STAGE(PG8_SA(1, 0), a3, voffA);
;             PG8_WAIT_V(8); PG8_WAIT_L(0); PG8_BAR; PG8_MMA(1, 0, At, B0); PG8_MMA(1, 1, At, B1); PG8_BAR; PG8_SCHED;
	v_mfma_f32_16x16x32_bf16 v[140:143], v[72:75], v[182:185], v[140:143]
	v_mfma_f32_16x16x32_bf16 v[136:139], v[92:95], v[182:185], v[136:139]
	v_mfma_f32_16x16x32_bf16 v[124:127], v[72:75], v[192:195], v[124:127]
	v_mfma_f32_16x16x32_bf16 v[120:123], v[92:95], v[192:195], v[120:123]
	v_mfma_f32_16x16x32_bf16 v[108:111], v[72:75], v[200:203], v[108:111]
	v_mfma_f32_16x16x32_bf16 v[104:107], v[92:95], v[200:203], v[104:107]
	v_mfma_f32_16x16x32_bf16 v[80:83], v[72:75], v[208:211], v[80:83]
	v_mfma_f32_16x16x32_bf16 v[76:79], v[92:95], v[208:211], v[76:79]
	v_mfma_f32_16x16x32_bf16 v[140:143], v[84:87], v[188:191], v[140:143]
	v_mfma_f32_16x16x32_bf16 v[136:139], v[96:99], v[188:191], v[136:139]
	v_mfma_f32_16x16x32_bf16 v[124:127], v[84:87], v[196:199], v[124:127]
	v_mfma_f32_16x16x32_bf16 v[120:123], v[96:99], v[196:199], v[120:123]
	v_mfma_f32_16x16x32_bf16 v[108:111], v[84:87], v[204:207], v[108:111]
	v_mfma_f32_16x16x32_bf16 v[104:107], v[96:99], v[204:207], v[104:107]
	v_mfma_f32_16x16x32_bf16 v[80:83], v[84:87], v[212:215], v[80:83]
	v_mfma_f32_16x16x32_bf16 v[76:79], v[96:99], v[212:215], v[76:79]
	s_setprio 0
	s_setprio 1
	v_mfma_f32_16x16x32_bf16 v[132:135], v[156:159], v[182:185], v[132:135]
	v_mfma_f32_16x16x32_bf16 v[128:131], v[174:177], v[182:185], v[128:131]
	v_mfma_f32_16x16x32_bf16 v[116:119], v[156:159], v[192:195], v[116:119]
	v_mfma_f32_16x16x32_bf16 v[112:115], v[174:177], v[192:195], v[112:115]
	v_mfma_f32_16x16x32_bf16 v[100:103], v[156:159], v[200:203], v[100:103]
	v_mfma_f32_16x16x32_bf16 v[88:91], v[174:177], v[200:203], v[88:91]
	v_mfma_f32_16x16x32_bf16 v[68:71], v[156:159], v[208:211], v[68:71]
	v_mfma_f32_16x16x32_bf16 v[64:67], v[174:177], v[208:211], v[64:67]
	v_mfma_f32_16x16x32_bf16 v[132:135], v[160:163], v[188:191], v[132:135]
	v_mfma_f32_16x16x32_bf16 v[128:131], v[178:181], v[188:191], v[128:131]
	v_mfma_f32_16x16x32_bf16 v[116:119], v[160:163], v[196:199], v[116:119]
	v_mfma_f32_16x16x32_bf16 v[112:115], v[178:181], v[196:199], v[112:115]
	v_mfma_f32_16x16x32_bf16 v[100:103], v[160:163], v[204:207], v[100:103]
	v_mfma_f32_16x16x32_bf16 v[88:91], v[178:181], v[204:207], v[88:91]
	v_mfma_f32_16x16x32_bf16 v[68:71], v[160:163], v[212:215], v[68:71]
	s_setprio 2
	s_barrier
	v_mfma_f32_16x16x32_bf16 v[64:67], v[178:181], v[212:215], v[64:67]
	s_setprio 0
	s_add_i32 s59, s53, s33
	v_lshl_add_u64 v[164:165], s[40:41], 0, v[144:145]
	s_mov_b32 m0, s59
	ds_read_b128 v[182:185], v171 offset:16384
	ds_read_b128 v[188:191], v171 offset:17408
	ds_read_b128 v[192:195], v171 offset:18432
	ds_read_b128 v[196:199], v171 offset:19456
	ds_read_b128 v[200:203], v171 offset:20480
	ds_read_b128 v[204:207], v171 offset:21504
	ds_read_b128 v[208:211], v171 offset:22528
	ds_read_b128 v[212:215], v171 offset:23552
	global_load_lds_dwordx4 v[164:165], off
	s_add_i32 m0, s59, 0x2000
	s_add_u32 s60, s40, 0x80000
	v_lshl_add_u64 v[216:217], s[40:41], 0, v[146:147]
	s_addc_u32 s61, s41, 0
	s_add_i32 s59, s54, s33
	global_load_lds_dwordx4 v[216:217], off
	v_lshl_add_u64 v[218:219], s[60:61], 0, v[144:145]
	s_mov_b32 m0, s59
	v_lshl_add_u64 v[220:221], s[42:43], 0, v[146:147]
	global_load_lds_dwordx4 v[218:219], off
	v_lshl_add_u64 v[218:219], s[60:61], 0, v[146:147]
	s_add_i32 m0, s59, 0x2000
	s_nop 0
	global_load_lds_dwordx4 v[218:219], off
	v_lshl_add_u64 v[218:219], s[42:43], 0, v[144:145]
	s_mov_b32 m0, s37
	s_nop 0
	global_load_lds_dwordx4 v[218:219], off
	s_mov_b32 m0, s44
	s_nop 0
	global_load_lds_dwordx4 v[220:221], off
	s_setprio 1
	s_waitcnt vmcnt(8)
	s_waitcnt lgkmcnt(0)
	s_barrier
	v_mfma_f32_16x16x32_bf16 v[60:63], v[72:75], v[182:185], v[60:63]
	v_mfma_f32_16x16x32_bf16 v[56:59], v[92:95], v[182:185], v[56:59]
	v_mfma_f32_16x16x32_bf16 v[44:47], v[72:75], v[192:195], v[44:47]
	v_mfma_f32_16x16x32_bf16 v[40:43], v[92:95], v[192:195], v[40:43]
	v_mfma_f32_16x16x32_bf16 v[28:31], v[72:75], v[200:203], v[28:31]
	v_mfma_f32_16x16x32_bf16 v[24:27], v[92:95], v[200:203], v[24:27]
	v_mfma_f32_16x16x32_bf16 v[12:15], v[72:75], v[208:211], v[12:15]
	v_mfma_f32_16x16x32_bf16 v[8:11], v[92:95], v[208:211], v[8:11]
	v_mfma_f32_16x16x32_bf16 v[60:63], v[84:87], v[188:191], v[60:63]
	v_mfma_f32_16x16x32_bf16 v[56:59], v[96:99], v[188:191], v[56:59]
	v_mfma_f32_16x16x32_bf16 v[44:47], v[84:87], v[196:199], v[44:47]
	v_mfma_f32_16x16x32_bf16 v[40:43], v[96:99], v[196:199], v[40:43]
	v_mfma_f32_16x16x32_bf16 v[28:31], v[84:87], v[204:207], v[28:31]
	v_mfma_f32_16x16x32_bf16 v[24:27], v[96:99], v[204:207], v[24:27]
	v_mfma_f32_16x16x32_bf16 v[12:15], v[84:87], v[212:215], v[12:15]
	v_mfma_f32_16x16x32_bf16 v[8:11], v[96:99], v[212:215], v[8:11]
	s_setprio 0
	s_setprio 1
	v_mfma_f32_16x16x32_bf16 v[52:55], v[156:159], v[182:185], v[52:55]
	v_mfma_f32_16x16x32_bf16 v[48:51], v[174:177], v[182:185], v[48:51]
	v_mfma_f32_16x16x32_bf16 v[36:39], v[156:159], v[192:195], v[36:39]
	v_mfma_f32_16x16x32_bf16 v[32:35], v[174:177], v[192:195], v[32:35]
	v_mfma_f32_16x16x32_bf16 v[20:23], v[156:159], v[200:203], v[20:23]
	v_mfma_f32_16x16x32_bf16 v[16:19], v[174:177], v[200:203], v[16:19]
	v_mfma_f32_16x16x32_bf16 v[4:7], v[156:159], v[208:211], v[4:7]
	v_mfma_f32_16x16x32_bf16 v[0:3], v[174:177], v[208:211], v[0:3]
	v_mfma_f32_16x16x32_bf16 v[52:55], v[160:163], v[188:191], v[52:55]
	v_mfma_f32_16x16x32_bf16 v[48:51], v[178:181], v[188:191], v[48:51]
	v_mfma_f32_16x16x32_bf16 v[36:39], v[160:163], v[196:199], v[36:39]
	v_mfma_f32_16x16x32_bf16 v[32:35], v[178:181], v[196:199], v[32:35]
	v_mfma_f32_16x16x32_bf16 v[20:23], v[160:163], v[204:207], v[20:23]
	v_mfma_f32_16x16x32_bf16 v[16:19], v[178:181], v[204:207], v[16:19]
	v_mfma_f32_16x16x32_bf16 v[4:7], v[160:163], v[212:215], v[4:7]
	s_setprio 2
	s_barrier
; #define PG8_STAGE(bufoff, gbase, voff) do { _Pragma("unroll") for (int _i = 0; _i < 2; ++_i) \
;         __builtin_amdgcn_global_load_lds((const unsigned*)((const char*)(gbase) + (voff)[_i]), (PG8_LAS unsigned*)(lds + (bufoff) + ldsw + _i * 8192), 16, 0, 0); } while (0)
; #define PG8_LDA(dst, b, h) do { _Pragma("unroll") for (int m = 0; m < 4; ++m) _Pragma("unroll") for (int k = 0; k < 2; ++k) dst[m][k] = *(const PG8_LAS bf16x8*)(lds + PG8_SA(b, h) + aoff + m * 2048 + k * 1024); } while (0)
; #define PG8_LDB(dst, b, h) do { _Pragma("unroll") for (int n = 0; n < 2; ++n) _Pragma("unroll") for (int k = 0; k < 2; ++k) dst[n][k] = *(const PG8_LAS bf16x8*)(lds + PG8_SB(b, h) + boff + n * 2048 + k * 1024); } while (0)
; #define PG8_MMA(ai, bj, At, Bt) do { __builtin_amdgcn_s_setprio(1); _Pragma("unroll") for (int m = 0; m < 4; ++m) _Pragma("unroll") for (int n = 0; n < 2; ++n) _Pragma("unroll") for (int k = 0; k < 2; ++k) \
;         acc[ai][bj][m][n] = __builtin_amdgcn_mfma_f32_16x16x32_bf16(Bt[n][k], At[m][k], acc[ai][bj][m][n], 0, 0, 0); __builtin_amdgcn_s_setprio(0); } while (0)
; #define PG8_WAIT_V(n) asm volatile("s_waitcnt vmcnt(" #n ")" ::: "memory")
; template <class Epi, class Sched, bool ALIGN_EPI = false, bool SP2 = false>
; __device__ __forceinline__ void gemm_phase(PG8_LAS unsigned char* lds, const Gemm g, const Sched& S, const Epi& E) {
;     ...
;             PG8_LDB(B0, 0, 0); PG8_LDB(B1, 0, 1); PG8_SCHED; PG8_LDA(At, 0, 0); PG8_STAGE(PG8_SA(1, 1), a1 + hstep, voffA);
;             PG8_WAIT_V(8); PG8_WAIT_L(0); PG8_BAR; PG8_MMA(0, 0, At, B0); PG8_MMA(0, 1, At, B1); PG8_BAR; PG8_SCHED;
;             PG8_LDA(At, 0, 1); PG8_STAGE(PG8_SB(0, 0), b2, voffB); PG8_STAGE(PG8_SB(0, 1), b2 + hstep, voffB); PG8_STAGE(PG8_SA(0, 0), a2, voffA);
;             PG8_WAIT_V(8); PG8_WAIT_L(0); PG8_BAR; PG8_MMA(1, 0, At, B0); PG8_MMA(1, 1, At, B1); PG8_BAR; PG8_SCHED;
;             PG8_LDB(B0, 1, 0); PG8_LDB(B1, 1, 1); PG8_SCHED; PG8_LDA(At, 1, 0); PG8_STAGE(PG8_SA(0, 1), a2 + hstep, voffA);
;             PG8_WAIT_V(8); PG8_WAIT_L(0); PG8_BAR; PG8_MMA(0, 0, At, B0); PG8_MMA(0, 1, At, B1); PG8_BAR; PG8_SCHED;
;             PG8_LDA(At, 1, 1); PG8_STAGE(PG8_SB(1, 0), b3, voffB); PG8_STAGE(PG8_SB(1, 1), b3 + hstep, voffB); PG8_STAGE(PG8_SA(1, 0), a3, voffA);
;             PG8_WAIT_V(8); PG8_WAIT_L(0); PG8_BAR; PG8_MMA(1, 0, At, B0); PG8_MMA(1, 1, At, B1); PG8_BAR; PG8_SCHED;
	v_mfma_f32_16x16x32_bf16 v[0:3], v[178:181], v[212:215], v[0:3]
	s_setprio 0
	s_add_i32 s59, 0, 0x18000
	s_add_i32 s60, 0, 0x1c000
	v_add_u32_e32 v96, s59, v167
	v_add_u32_e32 v173, s60, v167
	ds_read_b128 v[72:75], v96
	ds_read_b128 v[84:87], v96 offset:1024
	ds_read_b128 v[92:95], v96 offset:2048
	ds_read_b128 v[96:99], v96 offset:3072
	ds_read_b128 v[156:159], v173
	ds_read_b128 v[160:163], v173 offset:1024
	ds_read_b128 v[174:177], v173 offset:2048
	ds_read_b128 v[178:181], v173 offset:3072
	s_add_u32 s42, s42, 0x80000
	s_addc_u32 s43, s43, 0
	s_mov_b32 m0, s45
	v_lshl_add_u64 v[222:223], s[42:43], 0, v[144:145]
	ds_read_b128 v[182:185], v171 offset:32768
	ds_read_b128 v[188:191], v171 offset:33792
	ds_read_b128 v[192:195], v171 offset:34816
	ds_read_b128 v[196:199], v171 offset:35840
	ds_read_b128 v[200:203], v171 offset:36864
	ds_read_b128 v[204:207], v171 offset:37888
	ds_read_b128 v[208:211], v171 offset:38912
	ds_read_b128 v[212:215], v171 offset:39936
	global_load_lds_dwordx4 v[222:223], off
	v_lshl_add_u64 v[222:223], s[42:43], 0, v[146:147]
	s_mov_b32 m0, s46
	s_nop 0
	global_load_lds_dwordx4 v[222:223], off
	s_setprio 1
	s_waitcnt vmcnt(8)
	s_waitcnt lgkmcnt(0)
	s_barrier
	v_mfma_f32_16x16x32_bf16 v[140:143], v[72:75], v[182:185], v[140:143]
	v_mfma_f32_16x16x32_bf16 v[136:139], v[92:95], v[182:185], v[136:139]
	v_mfma_f32_16x16x32_bf16 v[124:127], v[72:75], v[192:195], v[124:127]
	v_mfma_f32_16x16x32_bf16 v[120:123], v[92:95], v[192:195], v[120:123]
	v_mfma_f32_16x16x32_bf16 v[108:111], v[72:75], v[200:203], v[108:111]
	v_mfma_f32_16x16x32_bf16 v[104:107], v[92:95], v[200:203], v[104:107]
	v_mfma_f32_16x16x32_bf16 v[80:83], v[72:75], v[208:211], v[80:83]
	v_mfma_f32_16x16x32_bf16 v[76:79], v[92:95], v[208:211], v[76:79]
	v_mfma_f32_16x16x32_bf16 v[140:143], v[84:87], v[188:191], v[140:143]
	v_mfma_f32_16x16x32_bf16 v[136:139], v[96:99], v[188:191], v[136:139]
	v_mfma_f32_16x16x32_bf16 v[124:127], v[84:87], v[196:199], v[124:127]
	v_mfma_f32_16x16x32_bf16 v[120:123], v[96:99], v[196:199], v[120:123]
	v_mfma_f32_16x16x32_bf16 v[108:111], v[84:87], v[204:207], v[108:111]
	v_mfma_f32_16x16x32_bf16 v[104:107], v[96:99], v[204:207], v[104:107]
	v_mfma_f32_16x16x32_bf16 v[80:83], v[84:87], v[212:215], v[80:83]
	v_mfma_f32_16x16x32_bf16 v[76:79], v[96:99], v[212:215], v[76:79]
	s_setprio 0
	s_setprio 1
	v_mfma_f32_16x16x32_bf16 v[132:135], v[156:159], v[182:185], v[132:135]
	v_mfma_f32_16x16x32_bf16 v[128:131], v[174:177], v[182:185], v[128:131]
	v_mfma_f32_16x16x32_bf16 v[116:119], v[156:159], v[192:195], v[116:119]
	v_mfma_f32_16x16x32_bf16 v[112:115], v[174:177], v[192:195], v[112:115]
	v_mfma_f32_16x16x32_bf16 v[100:103], v[156:159], v[200:203], v[100:103]
	v_mfma_f32_16x16x32_bf16 v[88:91], v[174:177], v[200:203], v[88:91]
	v_mfma_f32_16x16x32_bf16 v[68:71], v[156:159], v[208:211], v[68:71]
	v_mfma_f32_16x16x32_bf16 v[64:67], v[174:177], v[208:211], v[64:67]
	v_mfma_f32_16x16x32_bf16 v[132:135], v[160:163], v[188:191], v[132:135]
	v_mfma_f32_16x16x32_bf16 v[128:131], v[178:181], v[188:191], v[128:131]
	v_mfma_f32_16x16x32_bf16 v[116:119], v[160:163], v[196:199], v[116:119]
	v_mfma_f32_16x16x32_bf16 v[112:115], v[178:181], v[196:199], v[112:115]
	v_mfma_f32_16x16x32_bf16 v[100:103], v[160:163], v[204:207], v[100:103]
	v_mfma_f32_16x16x32_bf16 v[88:91], v[178:181], v[204:207], v[88:91]
	v_mfma_f32_16x16x32_bf16 v[68:71], v[160:163], v[212:215], v[68:71]
	s_setprio 2
	s_barrier
; #define PG8_STAGE(bufoff, gbase, voff) do { _Pragma("unroll") for (int _i = 0; _i < 2; ++_i) \
;         __builtin_amdgcn_global_load_lds((const unsigned*)((const char*)(gbase) + (voff)[_i]), (PG8_LAS unsigned*)(lds + (bufoff) + ldsw + _i * 8192), 16, 0, 0); } while (0)
; #define PG8_LDA(dst, b, h) do { _Pragma("unroll") for (int m = 0; m < 4; ++m) _Pragma("unroll") for (int k = 0; k < 2; ++k) dst[m][k] = *(const PG8_LAS bf16x8*)(lds + PG8_SA(b, h) + aoff + m * 2048 + k * 1024); } while (0)
; #define PG8_LDB(dst, b, h) do { _Pragma("unroll") for (int n = 0; n < 2; ++n) _Pragma("unroll") for (int k = 0; k < 2; ++k) dst[n][k] = *(const PG8_LAS bf16x8*)(lds + PG8_SB(b, h) + boff + n * 2048 + k * 1024); } while (0)
; #define PG8_MMA(ai, bj, At, Bt) do { __builtin_amdgcn_s_setprio(1); _Pragma("unroll") for (int m = 0; m < 4; ++m) _Pragma("unroll") for (int n = 0; n < 2; ++n) _Pragma("unroll") for (int k = 0; k < 2; ++k) \
;         acc[ai][bj][m][n] = __builtin_amdgcn_mfma_f32_16x16x32_bf16(Bt[n][k], At[m][k], acc[ai][bj][m][n], 0, 0, 0); __builtin_amdgcn_s_setprio(0); } while (0)
; template <class Epi, class Sched, bool ALIGN_EPI = false, bool SP2 = false>
; __device__ __forceinline__ void gemm_phase(PG8_LAS unsigned char* lds, const Gemm g, const Sched& S, const Epi& E) {
;     ...
;             PG8_LDB(B0, 0, 0); PG8_LDB(B1, 0, 1); PG8_SCHED; PG8_LDA(At, 0, 0); PG8_STAGE(PG8_SA(1, 1), a1 + hstep, voffA);
;             PG8_WAIT_V(8); PG8_WAIT_L(0); PG8_BAR; PG8_MMA(0, 0, At, B0); PG8_MMA(0, 1, At, B1); PG8_BAR; PG8_SCHED;
;             PG8_LDA(At, 0, 1); PG8_STAGE(PG8_SB(0, 0), b2, voffB); PG8_STAGE(PG8_SB(0, 1), b2 + hstep, voffB); PG8_STAGE(PG8_SA(0, 0), a2, voffA);
;             PG8_WAIT_V(8); PG8_WAIT_L(0); PG8_BAR; PG8_MMA(1, 0, At, B0); PG8_MMA(1, 1, At, B1); PG8_BAR; PG8_SCHED;
;             PG8_LDB(B0, 1, 0); PG8_LDB(B1, 1, 1); PG8_SCHED; PG8_LDA(At, 1, 0); PG8_STAGE(PG8_SA(0, 1), a2 + hstep, voffA);
;             PG8_WAIT_V(8); PG8_WAIT_L(0); PG8_BAR; PG8_MMA(0, 0, At, B0); PG8_MMA(0, 1, At, B1); PG8_BAR; PG8_SCHED;
;             PG8_LDA(At, 1, 1); PG8_STAGE(PG8_SB(1, 0), b3, voffB); PG8_STAGE(PG8_SB(1, 1), b3 + hstep, voffB); PG8_STAGE(PG8_SA(1, 0), a3, voffA);
;             PG8_WAIT_V(8); PG8_WAIT_L(0); PG8_BAR; PG8_MMA(1, 0, At, B0); PG8_MMA(1, 1, At, B1); PG8_BAR; PG8_SCHED;
;     ...
;         if constexpr (ALIGN_EPI) { if (wr == 0) PG8_BAR; }
	v_mfma_f32_16x16x32_bf16 v[64:67], v[178:181], v[212:215], v[64:67]
	s_setprio 0
	s_add_i32 s42, s59, s33
	v_lshl_add_u64 v[164:165], v[164:165], 0, s[12:13]
	s_mov_b32 m0, s42
	ds_read_b128 v[182:185], v171 offset:49152
	ds_read_b128 v[188:191], v171 offset:50176
	ds_read_b128 v[192:195], v171 offset:51200
	ds_read_b128 v[196:199], v171 offset:52224
	ds_read_b128 v[200:203], v171 offset:53248
	ds_read_b128 v[204:207], v171 offset:54272
	ds_read_b128 v[208:211], v171 offset:55296
	ds_read_b128 v[212:215], v171 offset:56320
	global_load_lds_dwordx4 v[164:165], off
	s_add_i32 m0, s42, 0x2000
	s_add_u32 s40, s40, 0x80080
	v_lshl_add_u64 v[164:165], v[216:217], 0, s[12:13]
	s_addc_u32 s41, s41, 0
	s_add_i32 s42, s60, s33
	global_load_lds_dwordx4 v[164:165], off
	v_lshl_add_u64 v[164:165], s[40:41], 0, v[144:145]
	s_mov_b32 m0, s42
	s_nop 0
	global_load_lds_dwordx4 v[164:165], off
	v_lshl_add_u64 v[164:165], s[40:41], 0, v[146:147]
	s_add_i32 m0, s42, 0x2000
	s_nop 0
	global_load_lds_dwordx4 v[164:165], off
	v_lshl_add_u64 v[164:165], v[218:219], 0, s[12:13]
	s_mov_b32 m0, s50
	s_nop 0
	global_load_lds_dwordx4 v[164:165], off
	v_lshl_add_u64 v[164:165], v[220:221], 0, s[12:13]
	s_mov_b32 m0, s51
	s_nop 0
	global_load_lds_dwordx4 v[164:165], off
	s_setprio 1
	s_waitcnt vmcnt(8)
	s_waitcnt lgkmcnt(0)
	s_barrier
	v_mfma_f32_16x16x32_bf16 v[60:63], v[72:75], v[182:185], v[60:63]
	v_mfma_f32_16x16x32_bf16 v[56:59], v[92:95], v[182:185], v[56:59]
	v_mfma_f32_16x16x32_bf16 v[44:47], v[72:75], v[192:195], v[44:47]
	v_mfma_f32_16x16x32_bf16 v[40:43], v[92:95], v[192:195], v[40:43]
	v_mfma_f32_16x16x32_bf16 v[28:31], v[72:75], v[200:203], v[28:31]
	v_mfma_f32_16x16x32_bf16 v[24:27], v[92:95], v[200:203], v[24:27]
	v_mfma_f32_16x16x32_bf16 v[12:15], v[72:75], v[208:211], v[12:15]
	v_mfma_f32_16x16x32_bf16 v[8:11], v[92:95], v[208:211], v[8:11]
	v_mfma_f32_16x16x32_bf16 v[60:63], v[84:87], v[188:191], v[60:63]
	v_mfma_f32_16x16x32_bf16 v[56:59], v[96:99], v[188:191], v[56:59]
	v_mfma_f32_16x16x32_bf16 v[44:47], v[84:87], v[196:199], v[44:47]
	v_mfma_f32_16x16x32_bf16 v[40:43], v[96:99], v[196:199], v[40:43]
	v_mfma_f32_16x16x32_bf16 v[28:31], v[84:87], v[204:207], v[28:31]
	v_mfma_f32_16x16x32_bf16 v[24:27], v[96:99], v[204:207], v[24:27]
	v_mfma_f32_16x16x32_bf16 v[12:15], v[84:87], v[212:215], v[12:15]
	v_mfma_f32_16x16x32_bf16 v[8:11], v[96:99], v[212:215], v[8:11]
	s_setprio 0
	s_setprio 1
	v_mfma_f32_16x16x32_bf16 v[52:55], v[156:159], v[182:185], v[52:55]
	v_mfma_f32_16x16x32_bf16 v[48:51], v[174:177], v[182:185], v[48:51]
	v_mfma_f32_16x16x32_bf16 v[36:39], v[156:159], v[192:195], v[36:39]
	v_mfma_f32_16x16x32_bf16 v[32:35], v[174:177], v[192:195], v[32:35]
	v_mfma_f32_16x16x32_bf16 v[20:23], v[156:159], v[200:203], v[20:23]
	v_mfma_f32_16x16x32_bf16 v[16:19], v[174:177], v[200:203], v[16:19]
	v_mfma_f32_16x16x32_bf16 v[4:7], v[156:159], v[208:211], v[4:7]
	v_mfma_f32_16x16x32_bf16 v[0:3], v[174:177], v[208:211], v[0:3]
	v_mfma_f32_16x16x32_bf16 v[52:55], v[160:163], v[188:191], v[52:55]
	v_mfma_f32_16x16x32_bf16 v[48:51], v[178:181], v[188:191], v[48:51]
	v_mfma_f32_16x16x32_bf16 v[36:39], v[160:163], v[196:199], v[36:39]
	v_mfma_f32_16x16x32_bf16 v[32:35], v[178:181], v[196:199], v[32:35]
	v_mfma_f32_16x16x32_bf16 v[20:23], v[160:163], v[204:207], v[20:23]
	v_mfma_f32_16x16x32_bf16 v[16:19], v[178:181], v[204:207], v[16:19]
	v_mfma_f32_16x16x32_bf16 v[4:7], v[160:163], v[212:215], v[4:7]
	s_setprio 2
	s_barrier
	v_mfma_f32_16x16x32_bf16 v[0:3], v[178:181], v[212:215], v[0:3]
	s_setprio 0
	s_add_i32 s58, s58, 2
	s_add_u32 s38, s38, 0x100
	s_addc_u32 s39, s39, 0
	s_add_u32 s56, s56, 0x100
	s_addc_u32 s57, s57, 0
	s_cmp_gt_u32 s58, 29
	s_cbranch_scc0 .LBB0_894
	s_and_b64 vcc, exec, s[14:15]
	s_cbranch_vccz .LBB0_897
	s_barrier

;     __device__ __forceinline__ bool next(int i, Unit& u) const { if (!base.next(i >> 1, u)) return false; if (i & 1) { u.pm += 64; u.pn += 8; } return true; }
; #define PG8_STAGE(bufoff, gbase, voff) do { _Pragma("unroll") for (int _i = 0; _i < 2; ++_i) \
;         __builtin_amdgcn_global_load_lds((const unsigned*)((const char*)(gbase) + (voff)[_i]), (PG8_LAS unsigned*)(lds + (bufoff) + ldsw + _i * 8192), 16, 0, 0); } while (0)
; #define PG8_WAIT_V(n) asm volatile("s_waitcnt vmcnt(" #n ")" ::: "memory")
; template <class Epi, class Sched, bool ALIGN_EPI = false, bool SP2 = false>
; __device__ __forceinline__ void gemm_phase(PG8_LAS unsigned char* lds, const Gemm g, const Sched& S, const Epi& E) {
;     ...
;         const bool has_next = S.next(ui + 1, nxt);
;         const char* nA = has_next ? (const char*)g.A + (size_t)nxt.pm * tstep : cA; const char* nB = has_next ? (const char*)g.Bt + (size_t)nxt.pn * tstep : cB;
;         for (int t = 0; t < nt; t += 2) {
;             const bool last = (t == nt - 2);
;             const char* a1 = cA + (size_t)(t + 1) * kstep;
;             const char* a2 = last ? nA : cA + (size_t)(t + 2) * kstep; const char* b2 = last ? nB : cB + (size_t)(t + 2) * kstep;
;             const char* a3 = a2 + kstep; const char* b3 = b2 + kstep;
;             if (last && has_next) S.a_ready(nxt);
;             if constexpr (SP2) {
;             PG8_LDB(B0, 0, 0); PG8_LDB(B1, 0, 1); PG8_SCHED; PG8_LDA(At, 0, 0); PG8_STAGE(PG8_SA(1, 1), a1 + hstep, voffA);
;             PG8_WAIT_V(8); PG8_WAIT_L(0); PG8_BAR; PG8_MMA(0, 0, At, B0); PG8_MMA(0, 1, At, B1); PG8_BAR; PG8_SCHED;
;             PG8_LDA(At, 0, 1); PG8_STAGE(PG8_SB(0, 0), b2, voffB); PG8_STAGE(PG8_SB(0, 1), b2 + hstep, voffB); PG8_STAGE(PG8_SA(0, 0), a2, voffA);
;             PG8_WAIT_V(8); PG8_WAIT_L(0); PG8_BAR; PG8_MMA(1, 0, At, B0); PG8_MMA(1, 1, At, B1); PG8_BAR; PG8_SCHED;
;             PG8_LDB(B0, 1, 0); PG8_LDB(B1, 1, 1); PG8_SCHED; PG8_LDA(At, 1, 0); PG8_STAGE(PG8_SA(0, 1), a2 + hstep, voffA);
;             PG8_WAIT_V(8); PG8_WAIT_L(0); PG8_BAR; PG8_MMA(0, 0, At, B0); PG8_MMA(0, 1, At, B1); PG8_BAR; PG8_SCHED;
;             PG8_LDA(At, 1, 1); PG8_STAGE(PG8_SB(1, 0), b3, voffB); PG8_STAGE(PG8_SB(1, 1), b3 + hstep, voffB); PG8_STAGE(PG8_SA(1, 0), a3, voffA);
;             PG8_WAIT_V(8); PG8_WAIT_L(0); PG8_BAR; PG8_MMA(1, 0, At, B0); PG8_MMA(1, 1, At, B1); PG8_BAR; PG8_SCHED;
.LBB0_993:
	s_ashr_i32 s15, s14, 31
	s_lshl_b64 s[18:19], s[14:15], 20
	s_add_u32 s18, s8, s18
	s_addc_u32 s19, s9, s19
	s_and_b64 s[20:21], s[4:5], exec
	s_cselect_b32 s15, s19, s25
	s_cselect_b32 s43, s18, s24
	s_ashr_i32 s17, s16, 31
	s_lshl_b64 s[20:21], s[16:17], 20
	v_readlane_b32 s28, v236, 52
	v_readlane_b32 s29, v236, 53
	s_add_u32 s20, s28, s20
	s_addc_u32 s21, s29, s21
	s_and_b64 s[28:29], s[4:5], exec
	s_cselect_b32 s17, s21, s27
	s_cselect_b32 s44, s20, s26
	s_add_u32 s24, s24, 0x80080
	s_addc_u32 s25, s25, 0
	s_add_u32 s45, s26, 0x100
	s_addc_u32 s46, s27, 0
	s_mov_b32 s47, -2
	ds_read_b128 v[128:131], v173
	ds_read_b128 v[132:135], v173 offset:1024
	ds_read_b128 v[136:139], v173 offset:2048
	ds_read_b128 v[140:143], v173 offset:3072
	ds_read_b128 v[176:179], v174
	ds_read_b128 v[180:183], v174 offset:1024
	ds_read_b128 v[188:191], v174 offset:2048
	ds_read_b128 v[192:195], v174 offset:3072
	s_add_u32 s26, s24, 0xfff80080
	s_addc_u32 s27, s25, -1
	s_cmp_eq_u32 s47, 28
	s_cselect_b32 s29, s15, s27
	s_cselect_b32 s28, s43, s26
	s_cselect_b32 s27, s17, s46
	s_cselect_b32 s26, s44, s45
	v_lshl_add_u64 v[160:161], s[24:25], 0, v[152:153]
	s_add_i32 m0, s23, 0xc000
	ds_read_b128 v[196:199], v175
	ds_read_b128 v[200:203], v175 offset:1024
	ds_read_b128 v[204:207], v175 offset:2048
	ds_read_b128 v[208:211], v175 offset:3072
	ds_read_b128 v[212:215], v175 offset:4096
	ds_read_b128 v[216:219], v175 offset:5120
	ds_read_b128 v[220:223], v175 offset:6144
	ds_read_b128 v[224:227], v175 offset:7168
	global_load_lds_dwordx4 v[160:161], off
	v_lshl_add_u64 v[160:161], s[24:25], 0, v[154:155]
	s_add_i32 m0, s23, 0xe000
	s_nop 0
	global_load_lds_dwordx4 v[160:161], off
	s_setprio 1
	s_waitcnt vmcnt(8)
	s_waitcnt lgkmcnt(0)
	s_barrier
	v_mfma_f32_16x16x32_bf16 v[124:127], v[128:131], v[196:199], 0
	v_mfma_f32_16x16x32_bf16 v[120:123], v[136:139], v[196:199], 0
	v_mfma_f32_16x16x32_bf16 v[108:111], v[128:131], v[204:207], 0
	v_mfma_f32_16x16x32_bf16 v[104:107], v[136:139], v[204:207], 0
	v_mfma_f32_16x16x32_bf16 v[92:95], v[128:131], v[212:215], 0
	v_mfma_f32_16x16x32_bf16 v[88:91], v[136:139], v[212:215], 0
	v_mfma_f32_16x16x32_bf16 v[76:79], v[128:131], v[220:223], 0
	v_mfma_f32_16x16x32_bf16 v[72:75], v[136:139], v[220:223], 0
	v_mfma_f32_16x16x32_bf16 v[124:127], v[132:135], v[200:203], v[124:127]
	v_mfma_f32_16x16x32_bf16 v[120:123], v[140:143], v[200:203], v[120:123]
	v_mfma_f32_16x16x32_bf16 v[108:111], v[132:135], v[208:211], v[108:111]
	v_mfma_f32_16x16x32_bf16 v[104:107], v[140:143], v[208:211], v[104:107]
	v_mfma_f32_16x16x32_bf16 v[92:95], v[132:135], v[216:219], v[92:95]
	v_mfma_f32_16x16x32_bf16 v[88:91], v[140:143], v[216:219], v[88:91]
	v_mfma_f32_16x16x32_bf16 v[76:79], v[132:135], v[224:227], v[76:79]
	v_mfma_f32_16x16x32_bf16 v[72:75], v[140:143], v[224:227], v[72:75]
	s_setprio 0
	s_setprio 1
	v_mfma_f32_16x16x32_bf16 v[116:119], v[176:179], v[196:199], 0
	v_mfma_f32_16x16x32_bf16 v[112:115], v[188:191], v[196:199], 0
	v_mfma_f32_16x16x32_bf16 v[100:103], v[176:179], v[204:207], 0
	v_mfma_f32_16x16x32_bf16 v[96:99], v[188:191], v[204:207], 0
	v_mfma_f32_16x16x32_bf16 v[84:87], v[176:179], v[212:215], 0
	v_mfma_f32_16x16x32_bf16 v[80:83], v[188:191], v[212:215], 0
	v_mfma_f32_16x16x32_bf16 v[68:71], v[176:179], v[220:223], 0
	v_mfma_f32_16x16x32_bf16 v[64:67], v[188:191], v[220:223], 0
	v_mfma_f32_16x16x32_bf16 v[116:119], v[180:183], v[200:203], v[116:119]
	v_mfma_f32_16x16x32_bf16 v[112:115], v[192:195], v[200:203], v[112:115]
	v_mfma_f32_16x16x32_bf16 v[100:103], v[180:183], v[208:211], v[100:103]
	v_mfma_f32_16x16x32_bf16 v[96:99], v[192:195], v[208:211], v[96:99]
	v_mfma_f32_16x16x32_bf16 v[84:87], v[180:183], v[216:219], v[84:87]
	v_mfma_f32_16x16x32_bf16 v[80:83], v[192:195], v[216:219], v[80:83]
	v_mfma_f32_16x16x32_bf16 v[68:71], v[180:183], v[224:227], v[68:71]
	s_setprio 2
	s_barrier
	v_mfma_f32_16x16x32_bf16 v[64:67], v[192:195], v[224:227], v[64:67]
	s_setprio 0
	s_add_i32 s48, s40, s31
	v_lshl_add_u64 v[160:161], s[26:27], 0, v[146:147]
	s_mov_b32 m0, s48
	ds_read_b128 v[196:199], v175 offset:16384
	ds_read_b128 v[200:203], v175 offset:17408
	ds_read_b128 v[204:207], v175 offset:18432
	ds_read_b128 v[208:211], v175 offset:19456
	ds_read_b128 v[212:215], v175 offset:20480
	ds_read_b128 v[216:219], v175 offset:21504
	ds_read_b128 v[220:223], v175 offset:22528
	ds_read_b128 v[224:227], v175 offset:23552
	global_load_lds_dwordx4 v[160:161], off
	s_add_i32 m0, s48, 0x2000
	s_add_u32 s48, s26, 0x80000
	v_lshl_add_u64 v[184:185], s[26:27], 0, v[150:151]
	s_addc_u32 s49, s27, 0
	s_add_i32 s50, s41, s31
	global_load_lds_dwordx4 v[184:185], off
	v_lshl_add_u64 v[228:229], s[48:49], 0, v[146:147]
	s_mov_b32 m0, s50
	v_lshl_add_u64 v[230:231], s[28:29], 0, v[148:149]
	global_load_lds_dwordx4 v[228:229], off
	v_lshl_add_u64 v[228:229], s[48:49], 0, v[150:151]
	s_add_i32 m0, s50, 0x2000
	s_nop 0
	global_load_lds_dwordx4 v[228:229], off
	v_lshl_add_u64 v[228:229], s[28:29], 0, v[144:145]
	s_mov_b32 m0, s23
	s_nop 0
	global_load_lds_dwordx4 v[228:229], off
	s_mov_b32 m0, s33
	s_nop 0
	global_load_lds_dwordx4 v[230:231], off
	s_setprio 1
	s_waitcnt vmcnt(8)
	s_waitcnt lgkmcnt(0)
	s_barrier
; #define PG8_STAGE(bufoff, gbase, voff) do { _Pragma("unroll") for (int _i = 0; _i < 2; ++_i) \
;         __builtin_amdgcn_global_load_lds((const unsigned*)((const char*)(gbase) + (voff)[_i]), (PG8_LAS unsigned*)(lds + (bufoff) + ldsw + _i * 8192), 16, 0, 0); } while (0)
; #define PG8_LDA(dst, b, h) do { _Pragma("unroll") for (int m = 0; m < 4; ++m) _Pragma("unroll") for (int k = 0; k < 2; ++k) dst[m][k] = *(const PG8_LAS bf16x8*)(lds + PG8_SA(b, h) + aoff + m * 2048 + k * 1024); } while (0)
; #define PG8_LDB(dst, b, h) do { _Pragma("unroll") for (int n = 0; n < 2; ++n) _Pragma("unroll") for (int k = 0; k < 2; ++k) dst[n][k] = *(const PG8_LAS bf16x8*)(lds + PG8_SB(b, h) + boff + n * 2048 + k * 1024); } while (0)
; #define PG8_MMA(ai, bj, At, Bt) do { __builtin_amdgcn_s_setprio(1); _Pragma("unroll") for (int m = 0; m < 4; ++m) _Pragma("unroll") for (int n = 0; n < 2; ++n) _Pragma("unroll") for (int k = 0; k < 2; ++k) \
;         acc[ai][bj][m][n] = __builtin_amdgcn_mfma_f32_16x16x32_bf16(Bt[n][k], At[m][k], acc[ai][bj][m][n], 0, 0, 0); __builtin_amdgcn_s_setprio(0); } while (0)
; #define PG8_WAIT_V(n) asm volatile("s_waitcnt vmcnt(" #n ")" ::: "memory")
; template <class Epi, class Sched, bool ALIGN_EPI = false, bool SP2 = false>
; __device__ __forceinline__ void gemm_phase(PG8_LAS unsigned char* lds, const Gemm g, const Sched& S, const Epi& E) {
;     ...
;             PG8_LDB(B0, 0, 0); PG8_LDB(B1, 0, 1); PG8_SCHED; PG8_LDA(At, 0, 0); PG8_STAGE(PG8_SA(1, 1), a1 + hstep, voffA);
;             PG8_WAIT_V(8); PG8_WAIT_L(0); PG8_BAR; PG8_MMA(0, 0, At, B0); PG8_MMA(0, 1, At, B1); PG8_BAR; PG8_SCHED;
;             PG8_LDA(At, 0, 1); PG8_STAGE(PG8_SB(0, 0), b2, voffB); PG8_STAGE(PG8_SB(0, 1), b2 + hstep, voffB); PG8_STAGE(PG8_SA(0, 0), a2, voffA);
;             PG8_WAIT_V(8); PG8_WAIT_L(0); PG8_BAR; PG8_MMA(1, 0, At, B0); PG8_MMA(1, 1, At, B1); PG8_BAR; PG8_SCHED;
;             PG8_LDB(B0, 1, 0); PG8_LDB(B1, 1, 1); PG8_SCHED; PG8_LDA(At, 1, 0); PG8_STAGE(PG8_SA(0, 1), a2 + hstep, voffA);
;             PG8_WAIT_V(8); PG8_WAIT_L(0); PG8_BAR; PG8_MMA(0, 0, At, B0); PG8_MMA(0, 1, At, B1); PG8_BAR; PG8_SCHED;
;             PG8_LDA(At, 1, 1); PG8_STAGE(PG8_SB(1, 0), b3, voffB); PG8_STAGE(PG8_SB(1, 1), b3 + hstep, voffB); PG8_STAGE(PG8_SA(1, 0), a3, voffA);
;             PG8_WAIT_V(8); PG8_WAIT_L(0); PG8_BAR; PG8_MMA(1, 0, At, B0); PG8_MMA(1, 1, At, B1); PG8_BAR; PG8_SCHED;
	v_mfma_f32_16x16x32_bf16 v[60:63], v[128:131], v[196:199], 0
	v_mfma_f32_16x16x32_bf16 v[56:59], v[136:139], v[196:199], 0
	v_mfma_f32_16x16x32_bf16 v[44:47], v[128:131], v[204:207], 0
	v_mfma_f32_16x16x32_bf16 v[40:43], v[136:139], v[204:207], 0
	v_mfma_f32_16x16x32_bf16 v[28:31], v[128:131], v[212:215], 0
	v_mfma_f32_16x16x32_bf16 v[24:27], v[136:139], v[212:215], 0
	v_mfma_f32_16x16x32_bf16 v[12:15], v[128:131], v[220:223], 0
	v_mfma_f32_16x16x32_bf16 v[8:11], v[136:139], v[220:223], 0
	v_mfma_f32_16x16x32_bf16 v[60:63], v[132:135], v[200:203], v[60:63]
	v_mfma_f32_16x16x32_bf16 v[56:59], v[140:143], v[200:203], v[56:59]
	v_mfma_f32_16x16x32_bf16 v[44:47], v[132:135], v[208:211], v[44:47]
	v_mfma_f32_16x16x32_bf16 v[40:43], v[140:143], v[208:211], v[40:43]
	v_mfma_f32_16x16x32_bf16 v[28:31], v[132:135], v[216:219], v[28:31]
	v_mfma_f32_16x16x32_bf16 v[24:27], v[140:143], v[216:219], v[24:27]
	v_mfma_f32_16x16x32_bf16 v[12:15], v[132:135], v[224:227], v[12:15]
	v_mfma_f32_16x16x32_bf16 v[8:11], v[140:143], v[224:227], v[8:11]
	s_setprio 0
	s_setprio 1
	v_mfma_f32_16x16x32_bf16 v[52:55], v[176:179], v[196:199], 0
	v_mfma_f32_16x16x32_bf16 v[48:51], v[188:191], v[196:199], 0
	v_mfma_f32_16x16x32_bf16 v[36:39], v[176:179], v[204:207], 0
	v_mfma_f32_16x16x32_bf16 v[32:35], v[188:191], v[204:207], 0
	v_mfma_f32_16x16x32_bf16 v[20:23], v[176:179], v[212:215], 0
	v_mfma_f32_16x16x32_bf16 v[16:19], v[188:191], v[212:215], 0
	v_mfma_f32_16x16x32_bf16 v[4:7], v[176:179], v[220:223], 0
	v_mfma_f32_16x16x32_bf16 v[0:3], v[188:191], v[220:223], 0
	v_mfma_f32_16x16x32_bf16 v[52:55], v[180:183], v[200:203], v[52:55]
	v_mfma_f32_16x16x32_bf16 v[48:51], v[192:195], v[200:203], v[48:51]
	v_mfma_f32_16x16x32_bf16 v[36:39], v[180:183], v[208:211], v[36:39]
	v_mfma_f32_16x16x32_bf16 v[32:35], v[192:195], v[208:211], v[32:35]
	v_mfma_f32_16x16x32_bf16 v[20:23], v[180:183], v[216:219], v[20:23]
	v_mfma_f32_16x16x32_bf16 v[16:19], v[192:195], v[216:219], v[16:19]
	v_mfma_f32_16x16x32_bf16 v[4:7], v[180:183], v[224:227], v[4:7]
	s_setprio 2
	s_barrier
	v_mfma_f32_16x16x32_bf16 v[0:3], v[192:195], v[224:227], v[0:3]
	s_setprio 0
	s_add_i32 s48, 0, 0x18000
	s_add_i32 s49, 0, 0x1c000
	v_add_u32_e32 v140, s48, v163
	v_add_u32_e32 v187, s49, v163
	ds_read_b128 v[128:131], v140
	ds_read_b128 v[132:135], v140 offset:1024
	ds_read_b128 v[136:139], v140 offset:2048
	ds_read_b128 v[140:143], v140 offset:3072
	ds_read_b128 v[176:179], v187
	ds_read_b128 v[180:183], v187 offset:1024
	ds_read_b128 v[188:191], v187 offset:2048
	ds_read_b128 v[192:195], v187 offset:3072
	s_add_u32 s28, s28, 0x80000
	s_addc_u32 s29, s29, 0
	s_mov_b32 m0, s34
	v_lshl_add_u64 v[232:233], s[28:29], 0, v[144:145]
	ds_read_b128 v[196:199], v175 offset:32768
	ds_read_b128 v[200:203], v175 offset:33792
	ds_read_b128 v[204:207], v175 offset:34816
	ds_read_b128 v[208:211], v175 offset:35840
	ds_read_b128 v[212:215], v175 offset:36864
	ds_read_b128 v[216:219], v175 offset:37888
	ds_read_b128 v[220:223], v175 offset:38912
	ds_read_b128 v[224:227], v175 offset:39936
	global_load_lds_dwordx4 v[232:233], off
	v_lshl_add_u64 v[232:233], s[28:29], 0, v[148:149]
	s_mov_b32 m0, s35
	s_nop 0
	global_load_lds_dwordx4 v[232:233], off
	s_setprio 1
	s_waitcnt vmcnt(8)
	s_waitcnt lgkmcnt(0)
	s_barrier
	v_mfma_f32_16x16x32_bf16 v[124:127], v[128:131], v[196:199], v[124:127]
	v_mfma_f32_16x16x32_bf16 v[120:123], v[136:139], v[196:199], v[120:123]
	v_mfma_f32_16x16x32_bf16 v[108:111], v[128:131], v[204:207], v[108:111]
	v_mfma_f32_16x16x32_bf16 v[104:107], v[136:139], v[204:207], v[104:107]
	v_mfma_f32_16x16x32_bf16 v[92:95], v[128:131], v[212:215], v[92:95]
	v_mfma_f32_16x16x32_bf16 v[88:91], v[136:139], v[212:215], v[88:91]
	v_mfma_f32_16x16x32_bf16 v[76:79], v[128:131], v[220:223], v[76:79]
	v_mfma_f32_16x16x32_bf16 v[72:75], v[136:139], v[220:223], v[72:75]
	v_mfma_f32_16x16x32_bf16 v[124:127], v[132:135], v[200:203], v[124:127]
	v_mfma_f32_16x16x32_bf16 v[120:123], v[140:143], v[200:203], v[120:123]
	v_mfma_f32_16x16x32_bf16 v[108:111], v[132:135], v[208:211], v[108:111]
	v_mfma_f32_16x16x32_bf16 v[104:107], v[140:143], v[208:211], v[104:107]
	v_mfma_f32_16x16x32_bf16 v[92:95], v[132:135], v[216:219], v[92:95]
	v_mfma_f32_16x16x32_bf16 v[88:91], v[140:143], v[216:219], v[88:91]
	v_mfma_f32_16x16x32_bf16 v[76:79], v[132:135], v[224:227], v[76:79]
	v_mfma_f32_16x16x32_bf16 v[72:75], v[140:143], v[224:227], v[72:75]
	s_setprio 0
	s_setprio 1
	v_mfma_f32_16x16x32_bf16 v[116:119], v[176:179], v[196:199], v[116:119]
	v_mfma_f32_16x16x32_bf16 v[112:115], v[188:191], v[196:199], v[112:115]
	v_mfma_f32_16x16x32_bf16 v[100:103], v[176:179], v[204:207], v[100:103]
	v_mfma_f32_16x16x32_bf16 v[96:99], v[188:191], v[204:207], v[96:99]
	v_mfma_f32_16x16x32_bf16 v[84:87], v[176:179], v[212:215], v[84:87]
	v_mfma_f32_16x16x32_bf16 v[80:83], v[188:191], v[212:215], v[80:83]
	v_mfma_f32_16x16x32_bf16 v[68:71], v[176:179], v[220:223], v[68:71]
	v_mfma_f32_16x16x32_bf16 v[64:67], v[188:191], v[220:223], v[64:67]
	v_mfma_f32_16x16x32_bf16 v[116:119], v[180:183], v[200:203], v[116:119]
	v_mfma_f32_16x16x32_bf16 v[112:115], v[192:195], v[200:203], v[112:115]
	v_mfma_f32_16x16x32_bf16 v[100:103], v[180:183], v[208:211], v[100:103]
	v_mfma_f32_16x16x32_bf16 v[96:99], v[192:195], v[208:211], v[96:99]
	v_mfma_f32_16x16x32_bf16 v[84:87], v[180:183], v[216:219], v[84:87]
	v_mfma_f32_16x16x32_bf16 v[80:83], v[192:195], v[216:219], v[80:83]
	v_mfma_f32_16x16x32_bf16 v[68:71], v[180:183], v[224:227], v[68:71]
	s_setprio 2
	s_barrier
; #define PG8_STAGE(bufoff, gbase, voff) do { _Pragma("unroll") for (int _i = 0; _i < 2; ++_i) \
;         __builtin_amdgcn_global_load_lds((const unsigned*)((const char*)(gbase) + (voff)[_i]), (PG8_LAS unsigned*)(lds + (bufoff) + ldsw + _i * 8192), 16, 0, 0); } while (0)
; #define PG8_LDA(dst, b, h) do { _Pragma("unroll") for (int m = 0; m < 4; ++m) _Pragma("unroll") for (int k = 0; k < 2; ++k) dst[m][k] = *(const PG8_LAS bf16x8*)(lds + PG8_SA(b, h) + aoff + m * 2048 + k * 1024); } while (0)
; #define PG8_LDB(dst, b, h) do { _Pragma("unroll") for (int n = 0; n < 2; ++n) _Pragma("unroll") for (int k = 0; k < 2; ++k) dst[n][k] = *(const PG8_LAS bf16x8*)(lds + PG8_SB(b, h) + boff + n * 2048 + k * 1024); } while (0)
; #define PG8_MMA(ai, bj, At, Bt) do { __builtin_amdgcn_s_setprio(1); _Pragma("unroll") for (int m = 0; m < 4; ++m) _Pragma("unroll") for (int n = 0; n < 2; ++n) _Pragma("unroll") for (int k = 0; k < 2; ++k) \
;         acc[ai][bj][m][n] = __builtin_amdgcn_mfma_f32_16x16x32_bf16(Bt[n][k], At[m][k], acc[ai][bj][m][n], 0, 0, 0); __builtin_amdgcn_s_setprio(0); } while (0)
; #define PG8_WAIT_V(n) asm volatile("s_waitcnt vmcnt(" #n ")" ::: "memory")
; template <class Epi, class Sched, bool ALIGN_EPI = false, bool SP2 = false>
; __device__ __forceinline__ void gemm_phase(PG8_LAS unsigned char* lds, const Gemm g, const Sched& S, const Epi& E) {
;     ...
;             PG8_LDB(B0, 0, 0); PG8_LDB(B1, 0, 1); PG8_SCHED; PG8_LDA(At, 0, 0); PG8_STAGE(PG8_SA(1, 1), a1 + hstep, voffA);
;             PG8_WAIT_V(8); PG8_WAIT_L(0); PG8_BAR; PG8_MMA(0, 0, At, B0); PG8_MMA(0, 1, At, B1); PG8_BAR; PG8_SCHED;
;             PG8_LDA(At, 0, 1); PG8_STAGE(PG8_SB(0, 0), b2, voffB); PG8_STAGE(PG8_SB(0, 1), b2 + hstep, voffB); PG8_STAGE(PG8_SA(0, 0), a2, voffA);
;             PG8_WAIT_V(8); PG8_WAIT_L(0); PG8_BAR; PG8_MMA(1, 0, At, B0); PG8_MMA(1, 1, At, B1); PG8_BAR; PG8_SCHED;
;             PG8_LDB(B0, 1, 0); PG8_LDB(B1, 1, 1); PG8_SCHED; PG8_LDA(At, 1, 0); PG8_STAGE(PG8_SA(0, 1), a2 + hstep, voffA);
;             PG8_WAIT_V(8); PG8_WAIT_L(0); PG8_BAR; PG8_MMA(0, 0, At, B0); PG8_MMA(0, 1, At, B1); PG8_BAR; PG8_SCHED;
;             PG8_LDA(At, 1, 1); PG8_STAGE(PG8_SB(1, 0), b3, voffB); PG8_STAGE(PG8_SB(1, 1), b3 + hstep, voffB); PG8_STAGE(PG8_SA(1, 0), a3, voffA);
;             PG8_WAIT_V(8); PG8_WAIT_L(0); PG8_BAR; PG8_MMA(1, 0, At, B0); PG8_MMA(1, 1, At, B1); PG8_BAR; PG8_SCHED;
	v_mfma_f32_16x16x32_bf16 v[64:67], v[192:195], v[224:227], v[64:67]
	s_setprio 0
	s_add_i32 s28, s48, s31
	v_lshl_add_u64 v[160:161], v[160:161], 0, s[10:11]
	s_mov_b32 m0, s28
	ds_read_b128 v[196:199], v175 offset:49152
	ds_read_b128 v[200:203], v175 offset:50176
	ds_read_b128 v[204:207], v175 offset:51200
	ds_read_b128 v[208:211], v175 offset:52224
	ds_read_b128 v[212:215], v175 offset:53248
	ds_read_b128 v[216:219], v175 offset:54272
	ds_read_b128 v[220:223], v175 offset:55296
	ds_read_b128 v[224:227], v175 offset:56320
	global_load_lds_dwordx4 v[160:161], off
	s_add_i32 m0, s28, 0x2000
	s_add_u32 s26, s26, 0x80080
	v_lshl_add_u64 v[160:161], v[184:185], 0, s[10:11]
	s_addc_u32 s27, s27, 0
	s_add_i32 s28, s49, s31
	global_load_lds_dwordx4 v[160:161], off
	v_lshl_add_u64 v[160:161], s[26:27], 0, v[146:147]
	s_mov_b32 m0, s28
	s_nop 0
	global_load_lds_dwordx4 v[160:161], off
	v_lshl_add_u64 v[160:161], s[26:27], 0, v[150:151]
	s_add_i32 m0, s28, 0x2000
	s_nop 0
	global_load_lds_dwordx4 v[160:161], off
	v_lshl_add_u64 v[160:161], v[228:229], 0, s[10:11]
	s_mov_b32 m0, s38
	s_nop 0
	global_load_lds_dwordx4 v[160:161], off
	v_lshl_add_u64 v[160:161], v[230:231], 0, s[10:11]
	s_mov_b32 m0, s39
	s_nop 0
	global_load_lds_dwordx4 v[160:161], off
	s_setprio 1
	s_waitcnt vmcnt(8)
	s_waitcnt lgkmcnt(0)
	s_barrier
	v_mfma_f32_16x16x32_bf16 v[60:63], v[128:131], v[196:199], v[60:63]
	v_mfma_f32_16x16x32_bf16 v[56:59], v[136:139], v[196:199], v[56:59]
	v_mfma_f32_16x16x32_bf16 v[44:47], v[128:131], v[204:207], v[44:47]
	v_mfma_f32_16x16x32_bf16 v[40:43], v[136:139], v[204:207], v[40:43]
	v_mfma_f32_16x16x32_bf16 v[28:31], v[128:131], v[212:215], v[28:31]
	v_mfma_f32_16x16x32_bf16 v[24:27], v[136:139], v[212:215], v[24:27]
	v_mfma_f32_16x16x32_bf16 v[12:15], v[128:131], v[220:223], v[12:15]
	v_mfma_f32_16x16x32_bf16 v[8:11], v[136:139], v[220:223], v[8:11]
	v_mfma_f32_16x16x32_bf16 v[60:63], v[132:135], v[200:203], v[60:63]
	v_mfma_f32_16x16x32_bf16 v[56:59], v[140:143], v[200:203], v[56:59]
	v_mfma_f32_16x16x32_bf16 v[44:47], v[132:135], v[208:211], v[44:47]
	v_mfma_f32_16x16x32_bf16 v[40:43], v[140:143], v[208:211], v[40:43]
	v_mfma_f32_16x16x32_bf16 v[28:31], v[132:135], v[216:219], v[28:31]
	v_mfma_f32_16x16x32_bf16 v[24:27], v[140:143], v[216:219], v[24:27]
	v_mfma_f32_16x16x32_bf16 v[12:15], v[132:135], v[224:227], v[12:15]
	v_mfma_f32_16x16x32_bf16 v[8:11], v[140:143], v[224:227], v[8:11]
	s_setprio 0
	s_setprio 1
	v_mfma_f32_16x16x32_bf16 v[52:55], v[176:179], v[196:199], v[52:55]
	v_mfma_f32_16x16x32_bf16 v[48:51], v[188:191], v[196:199], v[48:51]
	v_mfma_f32_16x16x32_bf16 v[36:39], v[176:179], v[204:207], v[36:39]
	v_mfma_f32_16x16x32_bf16 v[32:35], v[188:191], v[204:207], v[32:35]
	v_mfma_f32_16x16x32_bf16 v[20:23], v[176:179], v[212:215], v[20:23]
	v_mfma_f32_16x16x32_bf16 v[16:19], v[188:191], v[212:215], v[16:19]
	v_mfma_f32_16x16x32_bf16 v[4:7], v[176:179], v[220:223], v[4:7]
	v_mfma_f32_16x16x32_bf16 v[0:3], v[188:191], v[220:223], v[0:3]
	v_mfma_f32_16x16x32_bf16 v[52:55], v[180:183], v[200:203], v[52:55]
	v_mfma_f32_16x16x32_bf16 v[48:51], v[192:195], v[200:203], v[48:51]
	v_mfma_f32_16x16x32_bf16 v[36:39], v[180:183], v[208:211], v[36:39]
	v_mfma_f32_16x16x32_bf16 v[32:35], v[192:195], v[208:211], v[32:35]
	v_mfma_f32_16x16x32_bf16 v[20:23], v[180:183], v[216:219], v[20:23]
	v_mfma_f32_16x16x32_bf16 v[16:19], v[192:195], v[216:219], v[16:19]
	v_mfma_f32_16x16x32_bf16 v[4:7], v[180:183], v[224:227], v[4:7]
	s_setprio 2
	s_barrier
	v_mfma_f32_16x16x32_bf16 v[0:3], v[192:195], v[224:227], v[0:3]
	s_setprio 0
	s_add_i32 s47, s47, 2
	s_add_u32 s24, s24, 0x100
	s_addc_u32 s25, s25, 0
	s_add_u32 s45, s45, 0x100
	s_addc_u32 s46, s46, 0
	s_cmp_gt_u32 s47, 29
.LBB0_994:
	ds_read_b128 v[128:131], v173
	ds_read_b128 v[132:135], v173 offset:1024
	ds_read_b128 v[136:139], v173 offset:2048
	ds_read_b128 v[140:143], v173 offset:3072
	ds_read_b128 v[176:179], v174
	ds_read_b128 v[180:183], v174 offset:1024
	ds_read_b128 v[188:191], v174 offset:2048
	ds_read_b128 v[192:195], v174 offset:3072
	s_add_u32 s26, s24, 0xfff80080
	s_addc_u32 s27, s25, -1
	s_cmp_eq_u32 s47, 28
	s_cselect_b32 s29, s15, s27
	s_cselect_b32 s28, s43, s26
	s_cselect_b32 s27, s17, s46
	s_cselect_b32 s26, s44, s45
	v_lshl_add_u64 v[160:161], s[24:25], 0, v[152:153]
	s_add_i32 m0, s23, 0xc000
	ds_read_b128 v[196:199], v175
	ds_read_b128 v[200:203], v175 offset:1024
	ds_read_b128 v[204:207], v175 offset:2048
	ds_read_b128 v[208:211], v175 offset:3072
	ds_read_b128 v[212:215], v175 offset:4096
	ds_read_b128 v[216:219], v175 offset:5120
	ds_read_b128 v[220:223], v175 offset:6144
	ds_read_b128 v[224:227], v175 offset:7168
	global_load_lds_dwordx4 v[160:161], off
	v_lshl_add_u64 v[160:161], s[24:25], 0, v[154:155]
	s_add_i32 m0, s23, 0xe000
	s_nop 0
	global_load_lds_dwordx4 v[160:161], off
	s_setprio 1
	s_waitcnt vmcnt(8)
	s_waitcnt lgkmcnt(0)
	s_barrier
; #define PG8_STAGE(bufoff, gbase, voff) do { _Pragma("unroll") for (int _i = 0; _i < 2; ++_i) \
;         __builtin_amdgcn_global_load_lds((const unsigned*)((const char*)(gbase) + (voff)[_i]), (PG8_LAS unsigned*)(lds + (bufoff) + ldsw + _i * 8192), 16, 0, 0); } while (0)
; #define PG8_LDA(dst, b, h) do { _Pragma("unroll") for (int m = 0; m < 4; ++m) _Pragma("unroll") for (int k = 0; k < 2; ++k) dst[m][k] = *(const PG8_LAS bf16x8*)(lds + PG8_SA(b, h) + aoff + m * 2048 + k * 1024); } while (0)
; #define PG8_LDB(dst, b, h) do { _Pragma("unroll") for (int n = 0; n < 2; ++n) _Pragma("unroll") for (int k = 0; k < 2; ++k) dst[n][k] = *(const PG8_LAS bf16x8*)(lds + PG8_SB(b, h) + boff + n * 2048 + k * 1024); } while (0)
; #define PG8_MMA(ai, bj, At, Bt) do { __builtin_amdgcn_s_setprio(1); _Pragma("unroll") for (int m = 0; m < 4; ++m) _Pragma("unroll") for (int n = 0; n < 2; ++n) _Pragma("unroll") for (int k = 0; k < 2; ++k) \
;         acc[ai][bj][m][n] = __builtin_amdgcn_mfma_f32_16x16x32_bf16(Bt[n][k], At[m][k], acc[ai][bj][m][n], 0, 0, 0); __builtin_amdgcn_s_setprio(0); } while (0)
; #define PG8_WAIT_V(n) asm volatile("s_waitcnt vmcnt(" #n ")" ::: "memory")
; template <class Epi, class Sched, bool ALIGN_EPI = false, bool SP2 = false>
; __device__ __forceinline__ void gemm_phase(PG8_LAS unsigned char* lds, const Gemm g, const Sched& S, const Epi& E) {
;     ...
;             PG8_LDB(B0, 0, 0); PG8_LDB(B1, 0, 1); PG8_SCHED; PG8_LDA(At, 0, 0); PG8_STAGE(PG8_SA(1, 1), a1 + hstep, voffA);
;             PG8_WAIT_V(8); PG8_WAIT_L(0); PG8_BAR; PG8_MMA(0, 0, At, B0); PG8_MMA(0, 1, At, B1); PG8_BAR; PG8_SCHED;
;             PG8_LDA(At, 0, 1); PG8_STAGE(PG8_SB(0, 0), b2, voffB); PG8_STAGE(PG8_SB(0, 1), b2 + hstep, voffB); PG8_STAGE(PG8_SA(0, 0), a2, voffA);
;             PG8_WAIT_V(8); PG8_WAIT_L(0); PG8_BAR; PG8_MMA(1, 0, At, B0); PG8_MMA(1, 1, At, B1); PG8_BAR; PG8_SCHED;
;             PG8_LDB(B0, 1, 0); PG8_LDB(B1, 1, 1); PG8_SCHED; PG8_LDA(At, 1, 0); PG8_STAGE(PG8_SA(0, 1), a2 + hstep, voffA);
;             PG8_WAIT_V(8); PG8_WAIT_L(0); PG8_BAR; PG8_MMA(0, 0, At, B0); PG8_MMA(0, 1, At, B1); PG8_BAR; PG8_SCHED;
;             PG8_LDA(At, 1, 1); PG8_STAGE(PG8_SB(1, 0), b3, voffB); PG8_STAGE(PG8_SB(1, 1), b3 + hstep, voffB); PG8_STAGE(PG8_SA(1, 0), a3, voffA);
;             PG8_WAIT_V(8); PG8_WAIT_L(0); PG8_BAR; PG8_MMA(1, 0, At, B0); PG8_MMA(1, 1, At, B1); PG8_BAR; PG8_SCHED;
	v_mfma_f32_16x16x32_bf16 v[124:127], v[128:131], v[196:199], v[124:127]
	v_mfma_f32_16x16x32_bf16 v[120:123], v[136:139], v[196:199], v[120:123]
	v_mfma_f32_16x16x32_bf16 v[108:111], v[128:131], v[204:207], v[108:111]
	v_mfma_f32_16x16x32_bf16 v[104:107], v[136:139], v[204:207], v[104:107]
	v_mfma_f32_16x16x32_bf16 v[92:95], v[128:131], v[212:215], v[92:95]
	v_mfma_f32_16x16x32_bf16 v[88:91], v[136:139], v[212:215], v[88:91]
	v_mfma_f32_16x16x32_bf16 v[76:79], v[128:131], v[220:223], v[76:79]
	v_mfma_f32_16x16x32_bf16 v[72:75], v[136:139], v[220:223], v[72:75]
	v_mfma_f32_16x16x32_bf16 v[124:127], v[132:135], v[200:203], v[124:127]
	v_mfma_f32_16x16x32_bf16 v[120:123], v[140:143], v[200:203], v[120:123]
	v_mfma_f32_16x16x32_bf16 v[108:111], v[132:135], v[208:211], v[108:111]
	v_mfma_f32_16x16x32_bf16 v[104:107], v[140:143], v[208:211], v[104:107]
	v_mfma_f32_16x16x32_bf16 v[92:95], v[132:135], v[216:219], v[92:95]
	v_mfma_f32_16x16x32_bf16 v[88:91], v[140:143], v[216:219], v[88:91]
	v_mfma_f32_16x16x32_bf16 v[76:79], v[132:135], v[224:227], v[76:79]
	v_mfma_f32_16x16x32_bf16 v[72:75], v[140:143], v[224:227], v[72:75]
	s_setprio 0
	s_setprio 1
	v_mfma_f32_16x16x32_bf16 v[116:119], v[176:179], v[196:199], v[116:119]
	v_mfma_f32_16x16x32_bf16 v[112:115], v[188:191], v[196:199], v[112:115]
	v_mfma_f32_16x16x32_bf16 v[100:103], v[176:179], v[204:207], v[100:103]
	v_mfma_f32_16x16x32_bf16 v[96:99], v[188:191], v[204:207], v[96:99]
	v_mfma_f32_16x16x32_bf16 v[84:87], v[176:179], v[212:215], v[84:87]
	v_mfma_f32_16x16x32_bf16 v[80:83], v[188:191], v[212:215], v[80:83]
	v_mfma_f32_16x16x32_bf16 v[68:71], v[176:179], v[220:223], v[68:71]
	v_mfma_f32_16x16x32_bf16 v[64:67], v[188:191], v[220:223], v[64:67]
	v_mfma_f32_16x16x32_bf16 v[116:119], v[180:183], v[200:203], v[116:119]
	v_mfma_f32_16x16x32_bf16 v[112:115], v[192:195], v[200:203], v[112:115]
	v_mfma_f32_16x16x32_bf16 v[100:103], v[180:183], v[208:211], v[100:103]
	v_mfma_f32_16x16x32_bf16 v[96:99], v[192:195], v[208:211], v[96:99]
	v_mfma_f32_16x16x32_bf16 v[84:87], v[180:183], v[216:219], v[84:87]
	v_mfma_f32_16x16x32_bf16 v[80:83], v[192:195], v[216:219], v[80:83]
	v_mfma_f32_16x16x32_bf16 v[68:71], v[180:183], v[224:227], v[68:71]
	s_setprio 2
	s_barrier
	v_mfma_f32_16x16x32_bf16 v[64:67], v[192:195], v[224:227], v[64:67]
	s_setprio 0
	s_add_i32 s48, s40, s31
	v_lshl_add_u64 v[160:161], s[26:27], 0, v[146:147]
	s_mov_b32 m0, s48
	ds_read_b128 v[196:199], v175 offset:16384
	ds_read_b128 v[200:203], v175 offset:17408
	ds_read_b128 v[204:207], v175 offset:18432
	ds_read_b128 v[208:211], v175 offset:19456
	ds_read_b128 v[212:215], v175 offset:20480
	ds_read_b128 v[216:219], v175 offset:21504
	ds_read_b128 v[220:223], v175 offset:22528
	ds_read_b128 v[224:227], v175 offset:23552
	global_load_lds_dwordx4 v[160:161], off
	s_add_i32 m0, s48, 0x2000
	s_add_u32 s48, s26, 0x80000
	v_lshl_add_u64 v[184:185], s[26:27], 0, v[150:151]
	s_addc_u32 s49, s27, 0
	s_add_i32 s50, s41, s31
	global_load_lds_dwordx4 v[184:185], off
	v_lshl_add_u64 v[228:229], s[48:49], 0, v[146:147]
	s_mov_b32 m0, s50
	v_lshl_add_u64 v[230:231], s[28:29], 0, v[148:149]
	global_load_lds_dwordx4 v[228:229], off
	v_lshl_add_u64 v[228:229], s[48:49], 0, v[150:151]
	s_add_i32 m0, s50, 0x2000
	s_nop 0
	global_load_lds_dwordx4 v[228:229], off
	v_lshl_add_u64 v[228:229], s[28:29], 0, v[144:145]
	s_mov_b32 m0, s23
	s_nop 0
	global_load_lds_dwordx4 v[228:229], off
	s_mov_b32 m0, s33
	s_nop 0
	global_load_lds_dwordx4 v[230:231], off
	s_setprio 1
	s_waitcnt vmcnt(8)
	s_waitcnt lgkmcnt(0)
	s_barrier
	v_mfma_f32_16x16x32_bf16 v[60:63], v[128:131], v[196:199], v[60:63]
	v_mfma_f32_16x16x32_bf16 v[56:59], v[136:139], v[196:199], v[56:59]
	v_mfma_f32_16x16x32_bf16 v[44:47], v[128:131], v[204:207], v[44:47]
	v_mfma_f32_16x16x32_bf16 v[40:43], v[136:139], v[204:207], v[40:43]
	v_mfma_f32_16x16x32_bf16 v[28:31], v[128:131], v[212:215], v[28:31]
	v_mfma_f32_16x16x32_bf16 v[24:27], v[136:139], v[212:215], v[24:27]
	v_mfma_f32_16x16x32_bf16 v[12:15], v[128:131], v[220:223], v[12:15]
	v_mfma_f32_16x16x32_bf16 v[8:11], v[136:139], v[220:223], v[8:11]
	v_mfma_f32_16x16x32_bf16 v[60:63], v[132:135], v[200:203], v[60:63]
	v_mfma_f32_16x16x32_bf16 v[56:59], v[140:143], v[200:203], v[56:59]
	v_mfma_f32_16x16x32_bf16 v[44:47], v[132:135], v[208:211], v[44:47]
	v_mfma_f32_16x16x32_bf16 v[40:43], v[140:143], v[208:211], v[40:43]
	v_mfma_f32_16x16x32_bf16 v[28:31], v[132:135], v[216:219], v[28:31]
	v_mfma_f32_16x16x32_bf16 v[24:27], v[140:143], v[216:219], v[24:27]
	v_mfma_f32_16x16x32_bf16 v[12:15], v[132:135], v[224:227], v[12:15]
	v_mfma_f32_16x16x32_bf16 v[8:11], v[140:143], v[224:227], v[8:11]
	s_setprio 0
	s_setprio 1
	v_mfma_f32_16x16x32_bf16 v[52:55], v[176:179], v[196:199], v[52:55]
	v_mfma_f32_16x16x32_bf16 v[48:51], v[188:191], v[196:199], v[48:51]
	v_mfma_f32_16x16x32_bf16 v[36:39], v[176:179], v[204:207], v[36:39]
	v_mfma_f32_16x16x32_bf16 v[32:35], v[188:191], v[204:207], v[32:35]
	v_mfma_f32_16x16x32_bf16 v[20:23], v[176:179], v[212:215], v[20:23]
	v_mfma_f32_16x16x32_bf16 v[16:19], v[188:191], v[212:215], v[16:19]
	v_mfma_f32_16x16x32_bf16 v[4:7], v[176:179], v[220:223], v[4:7]
	v_mfma_f32_16x16x32_bf16 v[0:3], v[188:191], v[220:223], v[0:3]
	v_mfma_f32_16x16x32_bf16 v[52:55], v[180:183], v[200:203], v[52:55]
	v_mfma_f32_16x16x32_bf16 v[48:51], v[192:195], v[200:203], v[48:51]
	v_mfma_f32_16x16x32_bf16 v[36:39], v[180:183], v[208:211], v[36:39]
	v_mfma_f32_16x16x32_bf16 v[32:35], v[192:195], v[208:211], v[32:35]
	v_mfma_f32_16x16x32_bf16 v[20:23], v[180:183], v[216:219], v[20:23]
	v_mfma_f32_16x16x32_bf16 v[16:19], v[192:195], v[216:219], v[16:19]
	v_mfma_f32_16x16x32_bf16 v[4:7], v[180:183], v[224:227], v[4:7]
	s_setprio 2
	s_barrier
; #define PG8_STAGE(bufoff, gbase, voff) do { _Pragma("unroll") for (int _i = 0; _i < 2; ++_i) \
;         __builtin_amdgcn_global_load_lds((const unsigned*)((const char*)(gbase) + (voff)[_i]), (PG8_LAS unsigned*)(lds + (bufoff) + ldsw + _i * 8192), 16, 0, 0); } while (0)
; #define PG8_LDA(dst, b, h) do { _Pragma("unroll") for (int m = 0; m < 4; ++m) _Pragma("unroll") for (int k = 0; k < 2; ++k) dst[m][k] = *(const PG8_LAS bf16x8*)(lds + PG8_SA(b, h) + aoff + m * 2048 + k * 1024); } while (0)
; #define PG8_LDB(dst, b, h) do { _Pragma("unroll") for (int n = 0; n < 2; ++n) _Pragma("unroll") for (int k = 0; k < 2; ++k) dst[n][k] = *(const PG8_LAS bf16x8*)(lds + PG8_SB(b, h) + boff + n * 2048 + k * 1024); } while (0)
; #define PG8_MMA(ai, bj, At, Bt) do { __builtin_amdgcn_s_setprio(1); _Pragma("unroll") for (int m = 0; m < 4; ++m) _Pragma("unroll") for (int n = 0; n < 2; ++n) _Pragma("unroll") for (int k = 0; k < 2; ++k) \
;         acc[ai][bj][m][n] = __builtin_amdgcn_mfma_f32_16x16x32_bf16(Bt[n][k], At[m][k], acc[ai][bj][m][n], 0, 0, 0); __builtin_amdgcn_s_setprio(0); } while (0)
; #define PG8_WAIT_V(n) asm volatile("s_waitcnt vmcnt(" #n ")" ::: "memory")
; template <class Epi, class Sched, bool ALIGN_EPI = false, bool SP2 = false>
; __device__ __forceinline__ void gemm_phase(PG8_LAS unsigned char* lds, const Gemm g, const Sched& S, const Epi& E) {
;     ...
;             PG8_LDB(B0, 0, 0); PG8_LDB(B1, 0, 1); PG8_SCHED; PG8_LDA(At, 0, 0); PG8_STAGE(PG8_SA(1, 1), a1 + hstep, voffA);
;             PG8_WAIT_V(8); PG8_WAIT_L(0); PG8_BAR; PG8_MMA(0, 0, At, B0); PG8_MMA(0, 1, At, B1); PG8_BAR; PG8_SCHED;
;             PG8_LDA(At, 0, 1); PG8_STAGE(PG8_SB(0, 0), b2, voffB); PG8_STAGE(PG8_SB(0, 1), b2 + hstep, voffB); PG8_STAGE(PG8_SA(0, 0), a2, voffA);
;             PG8_WAIT_V(8); PG8_WAIT_L(0); PG8_BAR; PG8_MMA(1, 0, At, B0); PG8_MMA(1, 1, At, B1); PG8_BAR; PG8_SCHED;
;             PG8_LDB(B0, 1, 0); PG8_LDB(B1, 1, 1); PG8_SCHED; PG8_LDA(At, 1, 0); PG8_STAGE(PG8_SA(0, 1), a2 + hstep, voffA);
;             PG8_WAIT_V(8); PG8_WAIT_L(0); PG8_BAR; PG8_MMA(0, 0, At, B0); PG8_MMA(0, 1, At, B1); PG8_BAR; PG8_SCHED;
;             PG8_LDA(At, 1, 1); PG8_STAGE(PG8_SB(1, 0), b3, voffB); PG8_STAGE(PG8_SB(1, 1), b3 + hstep, voffB); PG8_STAGE(PG8_SA(1, 0), a3, voffA);
;             PG8_WAIT_V(8); PG8_WAIT_L(0); PG8_BAR; PG8_MMA(1, 0, At, B0); PG8_MMA(1, 1, At, B1); PG8_BAR; PG8_SCHED;
	v_mfma_f32_16x16x32_bf16 v[0:3], v[192:195], v[224:227], v[0:3]
	s_setprio 0
	s_add_i32 s48, 0, 0x18000
	s_add_i32 s49, 0, 0x1c000
	v_add_u32_e32 v140, s48, v163
	v_add_u32_e32 v187, s49, v163
	ds_read_b128 v[128:131], v140
	ds_read_b128 v[132:135], v140 offset:1024
	ds_read_b128 v[136:139], v140 offset:2048
	ds_read_b128 v[140:143], v140 offset:3072
	ds_read_b128 v[176:179], v187
	ds_read_b128 v[180:183], v187 offset:1024
	ds_read_b128 v[188:191], v187 offset:2048
	ds_read_b128 v[192:195], v187 offset:3072
	s_add_u32 s28, s28, 0x80000
	s_addc_u32 s29, s29, 0
	s_mov_b32 m0, s34
	v_lshl_add_u64 v[232:233], s[28:29], 0, v[144:145]
	ds_read_b128 v[196:199], v175 offset:32768
	ds_read_b128 v[200:203], v175 offset:33792
	ds_read_b128 v[204:207], v175 offset:34816
	ds_read_b128 v[208:211], v175 offset:35840
	ds_read_b128 v[212:215], v175 offset:36864
	ds_read_b128 v[216:219], v175 offset:37888
	ds_read_b128 v[220:223], v175 offset:38912
	ds_read_b128 v[224:227], v175 offset:39936
	global_load_lds_dwordx4 v[232:233], off
	v_lshl_add_u64 v[232:233], s[28:29], 0, v[148:149]
	s_mov_b32 m0, s35
	s_nop 0
	global_load_lds_dwordx4 v[232:233], off
	s_setprio 1
	s_waitcnt vmcnt(8)
	s_waitcnt lgkmcnt(0)
	s_barrier
	v_mfma_f32_16x16x32_bf16 v[124:127], v[128:131], v[196:199], v[124:127]
	v_mfma_f32_16x16x32_bf16 v[120:123], v[136:139], v[196:199], v[120:123]
	v_mfma_f32_16x16x32_bf16 v[108:111], v[128:131], v[204:207], v[108:111]
	v_mfma_f32_16x16x32_bf16 v[104:107], v[136:139], v[204:207], v[104:107]
	v_mfma_f32_16x16x32_bf16 v[92:95], v[128:131], v[212:215], v[92:95]
	v_mfma_f32_16x16x32_bf16 v[88:91], v[136:139], v[212:215], v[88:91]
	v_mfma_f32_16x16x32_bf16 v[76:79], v[128:131], v[220:223], v[76:79]
	v_mfma_f32_16x16x32_bf16 v[72:75], v[136:139], v[220:223], v[72:75]
	v_mfma_f32_16x16x32_bf16 v[124:127], v[132:135], v[200:203], v[124:127]
	v_mfma_f32_16x16x32_bf16 v[120:123], v[140:143], v[200:203], v[120:123]
	v_mfma_f32_16x16x32_bf16 v[108:111], v[132:135], v[208:211], v[108:111]
	v_mfma_f32_16x16x32_bf16 v[104:107], v[140:143], v[208:211], v[104:107]
	v_mfma_f32_16x16x32_bf16 v[92:95], v[132:135], v[216:219], v[92:95]
	v_mfma_f32_16x16x32_bf16 v[88:91], v[140:143], v[216:219], v[88:91]
	v_mfma_f32_16x16x32_bf16 v[76:79], v[132:135], v[224:227], v[76:79]
	v_mfma_f32_16x16x32_bf16 v[72:75], v[140:143], v[224:227], v[72:75]
	s_setprio 0
	s_setprio 1
	v_mfma_f32_16x16x32_bf16 v[116:119], v[176:179], v[196:199], v[116:119]
	v_mfma_f32_16x16x32_bf16 v[112:115], v[188:191], v[196:199], v[112:115]
	v_mfma_f32_16x16x32_bf16 v[100:103], v[176:179], v[204:207], v[100:103]
	v_mfma_f32_16x16x32_bf16 v[96:99], v[188:191], v[204:207], v[96:99]
	v_mfma_f32_16x16x32_bf16 v[84:87], v[176:179], v[212:215], v[84:87]
	v_mfma_f32_16x16x32_bf16 v[80:83], v[188:191], v[212:215], v[80:83]
	v_mfma_f32_16x16x32_bf16 v[68:71], v[176:179], v[220:223], v[68:71]
	v_mfma_f32_16x16x32_bf16 v[64:67], v[188:191], v[220:223], v[64:67]
	v_mfma_f32_16x16x32_bf16 v[116:119], v[180:183], v[200:203], v[116:119]
	v_mfma_f32_16x16x32_bf16 v[112:115], v[192:195], v[200:203], v[112:115]
	v_mfma_f32_16x16x32_bf16 v[100:103], v[180:183], v[208:211], v[100:103]
	v_mfma_f32_16x16x32_bf16 v[96:99], v[192:195], v[208:211], v[96:99]
	v_mfma_f32_16x16x32_bf16 v[84:87], v[180:183], v[216:219], v[84:87]
	v_mfma_f32_16x16x32_bf16 v[80:83], v[192:195], v[216:219], v[80:83]
	v_mfma_f32_16x16x32_bf16 v[68:71], v[180:183], v[224:227], v[68:71]
	s_setprio 2
	s_barrier
; #define PG8_STAGE(bufoff, gbase, voff) do { _Pragma("unroll") for (int _i = 0; _i < 2; ++_i) \
;         __builtin_amdgcn_global_load_lds((const unsigned*)((const char*)(gbase) + (voff)[_i]), (PG8_LAS unsigned*)(lds + (bufoff) + ldsw + _i * 8192), 16, 0, 0); } while (0)
; #define PG8_LDA(dst, b, h) do { _Pragma("unroll") for (int m = 0; m < 4; ++m) _Pragma("unroll") for (int k = 0; k < 2; ++k) dst[m][k] = *(const PG8_LAS bf16x8*)(lds + PG8_SA(b, h) + aoff + m * 2048 + k * 1024); } while (0)
; #define PG8_LDB(dst, b, h) do { _Pragma("unroll") for (int n = 0; n < 2; ++n) _Pragma("unroll") for (int k = 0; k < 2; ++k) dst[n][k] = *(const PG8_LAS bf16x8*)(lds + PG8_SB(b, h) + boff + n * 2048 + k * 1024); } while (0)
; #define PG8_MMA(ai, bj, At, Bt) do { __builtin_amdgcn_s_setprio(1); _Pragma("unroll") for (int m = 0; m < 4; ++m) _Pragma("unroll") for (int n = 0; n < 2; ++n) _Pragma("unroll") for (int k = 0; k < 2; ++k) \
;         acc[ai][bj][m][n] = __builtin_amdgcn_mfma_f32_16x16x32_bf16(Bt[n][k], At[m][k], acc[ai][bj][m][n], 0, 0, 0); __builtin_amdgcn_s_setprio(0); } while (0)
; template <class Epi, class Sched, bool ALIGN_EPI = false, bool SP2 = false>
; __device__ __forceinline__ void gemm_phase(PG8_LAS unsigned char* lds, const Gemm g, const Sched& S, const Epi& E) {
;     ...
;             PG8_LDB(B0, 0, 0); PG8_LDB(B1, 0, 1); PG8_SCHED; PG8_LDA(At, 0, 0); PG8_STAGE(PG8_SA(1, 1), a1 + hstep, voffA);
;             PG8_WAIT_V(8); PG8_WAIT_L(0); PG8_BAR; PG8_MMA(0, 0, At, B0); PG8_MMA(0, 1, At, B1); PG8_BAR; PG8_SCHED;
;             PG8_LDA(At, 0, 1); PG8_STAGE(PG8_SB(0, 0), b2, voffB); PG8_STAGE(PG8_SB(0, 1), b2 + hstep, voffB); PG8_STAGE(PG8_SA(0, 0), a2, voffA);
;             PG8_WAIT_V(8); PG8_WAIT_L(0); PG8_BAR; PG8_MMA(1, 0, At, B0); PG8_MMA(1, 1, At, B1); PG8_BAR; PG8_SCHED;
;             PG8_LDB(B0, 1, 0); PG8_LDB(B1, 1, 1); PG8_SCHED; PG8_LDA(At, 1, 0); PG8_STAGE(PG8_SA(0, 1), a2 + hstep, voffA);
;             PG8_WAIT_V(8); PG8_WAIT_L(0); PG8_BAR; PG8_MMA(0, 0, At, B0); PG8_MMA(0, 1, At, B1); PG8_BAR; PG8_SCHED;
;             PG8_LDA(At, 1, 1); PG8_STAGE(PG8_SB(1, 0), b3, voffB); PG8_STAGE(PG8_SB(1, 1), b3 + hstep, voffB); PG8_STAGE(PG8_SA(1, 0), a3, voffA);
;             PG8_WAIT_V(8); PG8_WAIT_L(0); PG8_BAR; PG8_MMA(1, 0, At, B0); PG8_MMA(1, 1, At, B1); PG8_BAR; PG8_SCHED;
;     ...
;         if constexpr (ALIGN_EPI) { if (wr == 0) PG8_BAR; }
	v_mfma_f32_16x16x32_bf16 v[64:67], v[192:195], v[224:227], v[64:67]
	s_setprio 0
	s_add_i32 s28, s48, s31
	v_lshl_add_u64 v[160:161], v[160:161], 0, s[10:11]
	s_mov_b32 m0, s28
	ds_read_b128 v[196:199], v175 offset:49152
	ds_read_b128 v[200:203], v175 offset:50176
	ds_read_b128 v[204:207], v175 offset:51200
	ds_read_b128 v[208:211], v175 offset:52224
	ds_read_b128 v[212:215], v175 offset:53248
	ds_read_b128 v[216:219], v175 offset:54272
	ds_read_b128 v[220:223], v175 offset:55296
	ds_read_b128 v[224:227], v175 offset:56320
	global_load_lds_dwordx4 v[160:161], off
	s_add_i32 m0, s28, 0x2000
	s_add_u32 s26, s26, 0x80080
	v_lshl_add_u64 v[160:161], v[184:185], 0, s[10:11]
	s_addc_u32 s27, s27, 0
	s_add_i32 s28, s49, s31
	global_load_lds_dwordx4 v[160:161], off
	v_lshl_add_u64 v[160:161], s[26:27], 0, v[146:147]
	s_mov_b32 m0, s28
	s_nop 0
	global_load_lds_dwordx4 v[160:161], off
	v_lshl_add_u64 v[160:161], s[26:27], 0, v[150:151]
	s_add_i32 m0, s28, 0x2000
	s_nop 0
	global_load_lds_dwordx4 v[160:161], off
	v_lshl_add_u64 v[160:161], v[228:229], 0, s[10:11]
	s_mov_b32 m0, s38
	s_nop 0
	global_load_lds_dwordx4 v[160:161], off
	v_lshl_add_u64 v[160:161], v[230:231], 0, s[10:11]
	s_mov_b32 m0, s39
	s_nop 0
	global_load_lds_dwordx4 v[160:161], off
	s_setprio 1
	s_waitcnt vmcnt(8)
	s_waitcnt lgkmcnt(0)
	s_barrier
	v_mfma_f32_16x16x32_bf16 v[60:63], v[128:131], v[196:199], v[60:63]
	v_mfma_f32_16x16x32_bf16 v[56:59], v[136:139], v[196:199], v[56:59]
	v_mfma_f32_16x16x32_bf16 v[44:47], v[128:131], v[204:207], v[44:47]
	v_mfma_f32_16x16x32_bf16 v[40:43], v[136:139], v[204:207], v[40:43]
	v_mfma_f32_16x16x32_bf16 v[28:31], v[128:131], v[212:215], v[28:31]
	v_mfma_f32_16x16x32_bf16 v[24:27], v[136:139], v[212:215], v[24:27]
	v_mfma_f32_16x16x32_bf16 v[12:15], v[128:131], v[220:223], v[12:15]
	v_mfma_f32_16x16x32_bf16 v[8:11], v[136:139], v[220:223], v[8:11]
	v_mfma_f32_16x16x32_bf16 v[60:63], v[132:135], v[200:203], v[60:63]
	v_mfma_f32_16x16x32_bf16 v[56:59], v[140:143], v[200:203], v[56:59]
	v_mfma_f32_16x16x32_bf16 v[44:47], v[132:135], v[208:211], v[44:47]
	v_mfma_f32_16x16x32_bf16 v[40:43], v[140:143], v[208:211], v[40:43]
	v_mfma_f32_16x16x32_bf16 v[28:31], v[132:135], v[216:219], v[28:31]
	v_mfma_f32_16x16x32_bf16 v[24:27], v[140:143], v[216:219], v[24:27]
	v_mfma_f32_16x16x32_bf16 v[12:15], v[132:135], v[224:227], v[12:15]
	v_mfma_f32_16x16x32_bf16 v[8:11], v[140:143], v[224:227], v[8:11]
	s_setprio 0
	s_setprio 1
	v_mfma_f32_16x16x32_bf16 v[52:55], v[176:179], v[196:199], v[52:55]
	v_mfma_f32_16x16x32_bf16 v[48:51], v[188:191], v[196:199], v[48:51]
	v_mfma_f32_16x16x32_bf16 v[36:39], v[176:179], v[204:207], v[36:39]
	v_mfma_f32_16x16x32_bf16 v[32:35], v[188:191], v[204:207], v[32:35]
	v_mfma_f32_16x16x32_bf16 v[20:23], v[176:179], v[212:215], v[20:23]
	v_mfma_f32_16x16x32_bf16 v[16:19], v[188:191], v[212:215], v[16:19]
	v_mfma_f32_16x16x32_bf16 v[4:7], v[176:179], v[220:223], v[4:7]
	v_mfma_f32_16x16x32_bf16 v[0:3], v[188:191], v[220:223], v[0:3]
	v_mfma_f32_16x16x32_bf16 v[52:55], v[180:183], v[200:203], v[52:55]
	v_mfma_f32_16x16x32_bf16 v[48:51], v[192:195], v[200:203], v[48:51]
	v_mfma_f32_16x16x32_bf16 v[36:39], v[180:183], v[208:211], v[36:39]
	v_mfma_f32_16x16x32_bf16 v[32:35], v[192:195], v[208:211], v[32:35]
	v_mfma_f32_16x16x32_bf16 v[20:23], v[180:183], v[216:219], v[20:23]
	v_mfma_f32_16x16x32_bf16 v[16:19], v[192:195], v[216:219], v[16:19]
	v_mfma_f32_16x16x32_bf16 v[4:7], v[180:183], v[224:227], v[4:7]
	s_setprio 2
	s_barrier
	v_mfma_f32_16x16x32_bf16 v[0:3], v[192:195], v[224:227], v[0:3]
	s_setprio 0
	s_add_i32 s47, s47, 2
	s_add_u32 s24, s24, 0x100
	s_addc_u32 s25, s25, 0
	s_add_u32 s45, s45, 0x100
	s_addc_u32 s46, s46, 0
	s_cmp_gt_u32 s47, 29
	s_cbranch_scc0 .LBB0_994
	s_and_b64 vcc, exec, s[12:13]
	s_cbranch_vccz .LBB0_997
	s_barrier

;     __device__ __forceinline__ bool next(int i, Unit& u) const { if (!base.next(i >> 1, u)) return false; if (i & 1) { u.pm += 64; u.pn += 8; } return true; }
; #define PG8_STAGE(bufoff, gbase, voff) do { _Pragma("unroll") for (int _i = 0; _i < 2; ++_i) \
;         __builtin_amdgcn_global_load_lds((const unsigned*)((const char*)(gbase) + (voff)[_i]), (PG8_LAS unsigned*)(lds + (bufoff) + ldsw + _i * 8192), 16, 0, 0); } while (0)
; #define PG8_WAIT_V(n) asm volatile("s_waitcnt vmcnt(" #n ")" ::: "memory")
; template <class Epi, class Sched, bool ALIGN_EPI = false, bool SP2 = false>
; __device__ __forceinline__ void gemm_phase(PG8_LAS unsigned char* lds, const Gemm g, const Sched& S, const Epi& E) {
;     ...
;         const bool has_next = S.next(ui + 1, nxt);
;         const char* nA = has_next ? (const char*)g.A + (size_t)nxt.pm * tstep : cA; const char* nB = has_next ? (const char*)g.Bt + (size_t)nxt.pn * tstep : cB;
;         for (int t = 0; t < nt; t += 2) {
;             const bool last = (t == nt - 2);
;             const char* a1 = cA + (size_t)(t + 1) * kstep;
;             const char* a2 = last ? nA : cA + (size_t)(t + 2) * kstep; const char* b2 = last ? nB : cB + (size_t)(t + 2) * kstep;
;             const char* a3 = a2 + kstep; const char* b3 = b2 + kstep;
;             if (last && has_next) S.a_ready(nxt);
;             if constexpr (SP2) {
;             PG8_LDB(B0, 0, 0); PG8_LDB(B1, 0, 1); PG8_SCHED; PG8_LDA(At, 0, 0); PG8_STAGE(PG8_SA(1, 1), a1 + hstep, voffA);
;             PG8_WAIT_V(8); PG8_WAIT_L(0); PG8_BAR; PG8_MMA(0, 0, At, B0); PG8_MMA(0, 1, At, B1); PG8_BAR; PG8_SCHED;
;             PG8_LDA(At, 0, 1); PG8_STAGE(PG8_SB(0, 0), b2, voffB); PG8_STAGE(PG8_SB(0, 1), b2 + hstep, voffB); PG8_STAGE(PG8_SA(0, 0), a2, voffA);
;             PG8_WAIT_V(8); PG8_WAIT_L(0); PG8_BAR; PG8_MMA(1, 0, At, B0); PG8_MMA(1, 1, At, B1); PG8_BAR; PG8_SCHED;
;             PG8_LDB(B0, 1, 0); PG8_LDB(B1, 1, 1); PG8_SCHED; PG8_LDA(At, 1, 0); PG8_STAGE(PG8_SA(0, 1), a2 + hstep, voffA);
;             PG8_WAIT_V(8); PG8_WAIT_L(0); PG8_BAR; PG8_MMA(0, 0, At, B0); PG8_MMA(0, 1, At, B1); PG8_BAR; PG8_SCHED;
;             PG8_LDA(At, 1, 1); PG8_STAGE(PG8_SB(1, 0), b3, voffB); PG8_STAGE(PG8_SB(1, 1), b3 + hstep, voffB); PG8_STAGE(PG8_SA(1, 0), a3, voffA);
;             PG8_WAIT_V(8); PG8_WAIT_L(0); PG8_BAR; PG8_MMA(1, 0, At, B0); PG8_MMA(1, 1, At, B1); PG8_BAR; PG8_SCHED;
.LBB0_1070:
	s_ashr_i32 s19, s18, 31
	s_lshl_b64 s[20:21], s[18:19], 22
	s_add_u32 s20, s72, s20
	s_addc_u32 s21, s73, s21
	s_and_b64 s[22:23], s[0:1], exec
	s_cselect_b32 s19, s21, s27
	s_cselect_b32 s51, s20, s26
	s_ashr_i32 s17, s16, 31
	s_lshl_b64 s[22:23], s[16:17], 22
	v_readlane_b32 s30, v236, 54
	v_readlane_b32 s31, v236, 55
	s_add_u32 s22, s30, s22
	s_addc_u32 s23, s31, s23
	s_and_b64 s[30:31], s[0:1], exec
	s_cselect_b32 s17, s23, s29
	s_cselect_b32 s52, s22, s28
	s_add_u32 s26, s26, 0x200080
	s_addc_u32 s27, s27, 0
	s_add_u32 s53, s28, 0x100
	s_addc_u32 s54, s29, 0
	s_mov_b32 s55, -2
	ds_read_b128 v[64:67], v165
	ds_read_b128 v[108:111], v165 offset:1024
	ds_read_b128 v[116:119], v165 offset:2048
	ds_read_b128 v[128:131], v165 offset:3072
	ds_read_b128 v[156:159], v166
	ds_read_b128 v[168:171], v166 offset:1024
	ds_read_b128 v[172:175], v166 offset:2048
	ds_read_b128 v[176:179], v166 offset:3072
	s_add_u32 s28, s26, 0xffe00080
	s_addc_u32 s29, s27, -1
	s_cmpk_eq_i32 s55, 0x7c
	s_cselect_b32 s31, s19, s29
	s_cselect_b32 s30, s51, s28
	s_cselect_b32 s29, s17, s54
	s_cselect_b32 s28, s52, s53
	v_lshl_add_u64 v[160:161], s[26:27], 0, v[148:149]
	s_add_i32 m0, s35, 0xc000
	ds_read_b128 v[180:183], v167
	ds_read_b128 v[184:187], v167 offset:1024
	ds_read_b128 v[188:191], v167 offset:2048
	ds_read_b128 v[192:195], v167 offset:3072
	ds_read_b128 v[196:199], v167 offset:4096
	ds_read_b128 v[200:203], v167 offset:5120
	ds_read_b128 v[204:207], v167 offset:6144
	ds_read_b128 v[208:211], v167 offset:7168
	global_load_lds_dwordx4 v[160:161], off
	v_lshl_add_u64 v[160:161], s[26:27], 0, v[150:151]
	s_add_i32 m0, s35, 0xe000
	s_nop 0
	global_load_lds_dwordx4 v[160:161], off
	s_setprio 1
	s_waitcnt vmcnt(8)
	s_waitcnt lgkmcnt(0)
	s_barrier
	v_mfma_f32_16x16x32_bf16 v[140:143], v[64:67], v[180:183], 0
	v_mfma_f32_16x16x32_bf16 v[136:139], v[116:119], v[180:183], 0
	v_mfma_f32_16x16x32_bf16 v[120:123], v[64:67], v[188:191], 0
	v_mfma_f32_16x16x32_bf16 v[112:115], v[116:119], v[188:191], 0
	v_mfma_f32_16x16x32_bf16 v[96:99], v[64:67], v[196:199], 0
	v_mfma_f32_16x16x32_bf16 v[92:95], v[116:119], v[196:199], 0
	v_mfma_f32_16x16x32_bf16 v[80:83], v[64:67], v[204:207], 0
	v_mfma_f32_16x16x32_bf16 v[76:79], v[116:119], v[204:207], 0
	v_mfma_f32_16x16x32_bf16 v[140:143], v[108:111], v[184:187], v[140:143]
	v_mfma_f32_16x16x32_bf16 v[136:139], v[128:131], v[184:187], v[136:139]
	v_mfma_f32_16x16x32_bf16 v[120:123], v[108:111], v[192:195], v[120:123]
	v_mfma_f32_16x16x32_bf16 v[112:115], v[128:131], v[192:195], v[112:115]
	v_mfma_f32_16x16x32_bf16 v[96:99], v[108:111], v[200:203], v[96:99]
	v_mfma_f32_16x16x32_bf16 v[92:95], v[128:131], v[200:203], v[92:95]
	v_mfma_f32_16x16x32_bf16 v[80:83], v[108:111], v[208:211], v[80:83]
	v_mfma_f32_16x16x32_bf16 v[76:79], v[128:131], v[208:211], v[76:79]
	s_setprio 0
	s_setprio 1
	v_mfma_f32_16x16x32_bf16 v[132:135], v[156:159], v[180:183], 0
	v_mfma_f32_16x16x32_bf16 v[124:127], v[172:175], v[180:183], 0
	v_mfma_f32_16x16x32_bf16 v[104:107], v[156:159], v[188:191], 0
	v_mfma_f32_16x16x32_bf16 v[100:103], v[172:175], v[188:191], 0
	v_mfma_f32_16x16x32_bf16 v[88:91], v[156:159], v[196:199], 0
	v_mfma_f32_16x16x32_bf16 v[84:87], v[172:175], v[196:199], 0
	v_mfma_f32_16x16x32_bf16 v[72:75], v[156:159], v[204:207], 0
	v_mfma_f32_16x16x32_bf16 v[68:71], v[172:175], v[204:207], 0
	v_mfma_f32_16x16x32_bf16 v[132:135], v[168:171], v[184:187], v[132:135]
	v_mfma_f32_16x16x32_bf16 v[124:127], v[176:179], v[184:187], v[124:127]
	v_mfma_f32_16x16x32_bf16 v[104:107], v[168:171], v[192:195], v[104:107]
	v_mfma_f32_16x16x32_bf16 v[100:103], v[176:179], v[192:195], v[100:103]
	v_mfma_f32_16x16x32_bf16 v[88:91], v[168:171], v[200:203], v[88:91]
	v_mfma_f32_16x16x32_bf16 v[84:87], v[176:179], v[200:203], v[84:87]
	v_mfma_f32_16x16x32_bf16 v[72:75], v[168:171], v[208:211], v[72:75]
	s_setprio 2
	s_barrier
	v_mfma_f32_16x16x32_bf16 v[68:71], v[176:179], v[208:211], v[68:71]
	s_setprio 0
	s_add_i32 s56, s45, s34
	v_lshl_add_u64 v[160:161], s[28:29], 0, v[144:145]
	s_mov_b32 m0, s56
	ds_read_b128 v[180:183], v167 offset:16384
	ds_read_b128 v[184:187], v167 offset:17408
	ds_read_b128 v[188:191], v167 offset:18432
	ds_read_b128 v[192:195], v167 offset:19456
	ds_read_b128 v[196:199], v167 offset:20480
	ds_read_b128 v[200:203], v167 offset:21504
	ds_read_b128 v[204:207], v167 offset:22528
	ds_read_b128 v[208:211], v167 offset:23552
	global_load_lds_dwordx4 v[160:161], off
	s_add_i32 m0, s56, 0x2000
	s_add_u32 s56, s28, 0x200000
	v_lshl_add_u64 v[212:213], s[28:29], 0, v[146:147]
	s_addc_u32 s57, s29, 0
	s_add_i32 s58, s46, s34
	global_load_lds_dwordx4 v[212:213], off
	v_lshl_add_u64 v[214:215], s[56:57], 0, v[144:145]
	s_mov_b32 m0, s58
	v_lshl_add_u64 v[216:217], s[30:31], 0, v[146:147]
	global_load_lds_dwordx4 v[214:215], off
	v_lshl_add_u64 v[214:215], s[56:57], 0, v[146:147]
	s_add_i32 m0, s58, 0x2000
	s_nop 0
	global_load_lds_dwordx4 v[214:215], off
	v_lshl_add_u64 v[214:215], s[30:31], 0, v[144:145]
	s_mov_b32 m0, s35
	s_nop 0
	global_load_lds_dwordx4 v[214:215], off
	s_mov_b32 m0, s36
	s_nop 0
	global_load_lds_dwordx4 v[216:217], off
	s_setprio 1
	s_waitcnt vmcnt(8)
	s_waitcnt lgkmcnt(0)
	s_barrier
; #define PG8_STAGE(bufoff, gbase, voff) do { _Pragma("unroll") for (int _i = 0; _i < 2; ++_i) \
;         __builtin_amdgcn_global_load_lds((const unsigned*)((const char*)(gbase) + (voff)[_i]), (PG8_LAS unsigned*)(lds + (bufoff) + ldsw + _i * 8192), 16, 0, 0); } while (0)
; #define PG8_LDA(dst, b, h) do { _Pragma("unroll") for (int m = 0; m < 4; ++m) _Pragma("unroll") for (int k = 0; k < 2; ++k) dst[m][k] = *(const PG8_LAS bf16x8*)(lds + PG8_SA(b, h) + aoff + m * 2048 + k * 1024); } while (0)
; #define PG8_LDB(dst, b, h) do { _Pragma("unroll") for (int n = 0; n < 2; ++n) _Pragma("unroll") for (int k = 0; k < 2; ++k) dst[n][k] = *(const PG8_LAS bf16x8*)(lds + PG8_SB(b, h) + boff + n * 2048 + k * 1024); } while (0)
; #define PG8_MMA(ai, bj, At, Bt) do { __builtin_amdgcn_s_setprio(1); _Pragma("unroll") for (int m = 0; m < 4; ++m) _Pragma("unroll") for (int n = 0; n < 2; ++n) _Pragma("unroll") for (int k = 0; k < 2; ++k) \
;         acc[ai][bj][m][n] = __builtin_amdgcn_mfma_f32_16x16x32_bf16(Bt[n][k], At[m][k], acc[ai][bj][m][n], 0, 0, 0); __builtin_amdgcn_s_setprio(0); } while (0)
; #define PG8_WAIT_V(n) asm volatile("s_waitcnt vmcnt(" #n ")" ::: "memory")
; template <class Epi, class Sched, bool ALIGN_EPI = false, bool SP2 = false>
; __device__ __forceinline__ void gemm_phase(PG8_LAS unsigned char* lds, const Gemm g, const Sched& S, const Epi& E) {
;     ...
;             PG8_LDB(B0, 0, 0); PG8_LDB(B1, 0, 1); PG8_SCHED; PG8_LDA(At, 0, 0); PG8_STAGE(PG8_SA(1, 1), a1 + hstep, voffA);
;             PG8_WAIT_V(8); PG8_WAIT_L(0); PG8_BAR; PG8_MMA(0, 0, At, B0); PG8_MMA(0, 1, At, B1); PG8_BAR; PG8_SCHED;
;             PG8_LDA(At, 0, 1); PG8_STAGE(PG8_SB(0, 0), b2, voffB); PG8_STAGE(PG8_SB(0, 1), b2 + hstep, voffB); PG8_STAGE(PG8_SA(0, 0), a2, voffA);
;             PG8_WAIT_V(8); PG8_WAIT_L(0); PG8_BAR; PG8_MMA(1, 0, At, B0); PG8_MMA(1, 1, At, B1); PG8_BAR; PG8_SCHED;
;             PG8_LDB(B0, 1, 0); PG8_LDB(B1, 1, 1); PG8_SCHED; PG8_LDA(At, 1, 0); PG8_STAGE(PG8_SA(0, 1), a2 + hstep, voffA);
;             PG8_WAIT_V(8); PG8_WAIT_L(0); PG8_BAR; PG8_MMA(0, 0, At, B0); PG8_MMA(0, 1, At, B1); PG8_BAR; PG8_SCHED;
;             PG8_LDA(At, 1, 1); PG8_STAGE(PG8_SB(1, 0), b3, voffB); PG8_STAGE(PG8_SB(1, 1), b3 + hstep, voffB); PG8_STAGE(PG8_SA(1, 0), a3, voffA);
;             PG8_WAIT_V(8); PG8_WAIT_L(0); PG8_BAR; PG8_MMA(1, 0, At, B0); PG8_MMA(1, 1, At, B1); PG8_BAR; PG8_SCHED;
	v_mfma_f32_16x16x32_bf16 v[60:63], v[64:67], v[180:183], 0
	v_mfma_f32_16x16x32_bf16 v[56:59], v[116:119], v[180:183], 0
	v_mfma_f32_16x16x32_bf16 v[44:47], v[64:67], v[188:191], 0
	v_mfma_f32_16x16x32_bf16 v[40:43], v[116:119], v[188:191], 0
	v_mfma_f32_16x16x32_bf16 v[28:31], v[64:67], v[196:199], 0
	v_mfma_f32_16x16x32_bf16 v[24:27], v[116:119], v[196:199], 0
	v_mfma_f32_16x16x32_bf16 v[12:15], v[64:67], v[204:207], 0
	v_mfma_f32_16x16x32_bf16 v[8:11], v[116:119], v[204:207], 0
	v_mfma_f32_16x16x32_bf16 v[60:63], v[108:111], v[184:187], v[60:63]
	v_mfma_f32_16x16x32_bf16 v[56:59], v[128:131], v[184:187], v[56:59]
	v_mfma_f32_16x16x32_bf16 v[44:47], v[108:111], v[192:195], v[44:47]
	v_mfma_f32_16x16x32_bf16 v[40:43], v[128:131], v[192:195], v[40:43]
	v_mfma_f32_16x16x32_bf16 v[28:31], v[108:111], v[200:203], v[28:31]
	v_mfma_f32_16x16x32_bf16 v[24:27], v[128:131], v[200:203], v[24:27]
	v_mfma_f32_16x16x32_bf16 v[12:15], v[108:111], v[208:211], v[12:15]
	v_mfma_f32_16x16x32_bf16 v[8:11], v[128:131], v[208:211], v[8:11]
	s_setprio 0
	s_setprio 1
	v_mfma_f32_16x16x32_bf16 v[52:55], v[156:159], v[180:183], 0
	v_mfma_f32_16x16x32_bf16 v[48:51], v[172:175], v[180:183], 0
	v_mfma_f32_16x16x32_bf16 v[36:39], v[156:159], v[188:191], 0
	v_mfma_f32_16x16x32_bf16 v[32:35], v[172:175], v[188:191], 0
	v_mfma_f32_16x16x32_bf16 v[20:23], v[156:159], v[196:199], 0
	v_mfma_f32_16x16x32_bf16 v[16:19], v[172:175], v[196:199], 0
	v_mfma_f32_16x16x32_bf16 v[4:7], v[156:159], v[204:207], 0
	v_mfma_f32_16x16x32_bf16 v[0:3], v[172:175], v[204:207], 0
	v_mfma_f32_16x16x32_bf16 v[52:55], v[168:171], v[184:187], v[52:55]
	v_mfma_f32_16x16x32_bf16 v[48:51], v[176:179], v[184:187], v[48:51]
	v_mfma_f32_16x16x32_bf16 v[36:39], v[168:171], v[192:195], v[36:39]
	v_mfma_f32_16x16x32_bf16 v[32:35], v[176:179], v[192:195], v[32:35]
	v_mfma_f32_16x16x32_bf16 v[20:23], v[168:171], v[200:203], v[20:23]
	v_mfma_f32_16x16x32_bf16 v[16:19], v[176:179], v[200:203], v[16:19]
	v_mfma_f32_16x16x32_bf16 v[4:7], v[168:171], v[208:211], v[4:7]
	s_setprio 2
	s_barrier
	v_mfma_f32_16x16x32_bf16 v[0:3], v[176:179], v[208:211], v[0:3]
	s_setprio 0
	s_add_i32 s56, 0, 0x18000
	s_add_i32 s57, 0, 0x1c000
	v_add_u32_e32 v128, s56, v163
	v_add_u32_e32 v176, s57, v163
	ds_read_b128 v[64:67], v128
	ds_read_b128 v[108:111], v128 offset:1024
	ds_read_b128 v[116:119], v128 offset:2048
	ds_read_b128 v[128:131], v128 offset:3072
	ds_read_b128 v[156:159], v176
	ds_read_b128 v[168:171], v176 offset:1024
	ds_read_b128 v[172:175], v176 offset:2048
	ds_read_b128 v[176:179], v176 offset:3072
	s_add_u32 s30, s30, 0x200000
	s_addc_u32 s31, s31, 0
	s_mov_b32 m0, s37
	v_lshl_add_u64 v[218:219], s[30:31], 0, v[144:145]
	ds_read_b128 v[180:183], v167 offset:32768
	ds_read_b128 v[184:187], v167 offset:33792
	ds_read_b128 v[188:191], v167 offset:34816
	ds_read_b128 v[192:195], v167 offset:35840
	ds_read_b128 v[196:199], v167 offset:36864
	ds_read_b128 v[200:203], v167 offset:37888
	ds_read_b128 v[204:207], v167 offset:38912
	ds_read_b128 v[208:211], v167 offset:39936
	global_load_lds_dwordx4 v[218:219], off
	v_lshl_add_u64 v[218:219], s[30:31], 0, v[146:147]
	s_mov_b32 m0, s38
	s_nop 0
	global_load_lds_dwordx4 v[218:219], off
	s_setprio 1
	s_waitcnt vmcnt(8)
	s_waitcnt lgkmcnt(0)
	s_barrier
	v_mfma_f32_16x16x32_bf16 v[140:143], v[64:67], v[180:183], v[140:143]
	v_mfma_f32_16x16x32_bf16 v[136:139], v[116:119], v[180:183], v[136:139]
	v_mfma_f32_16x16x32_bf16 v[120:123], v[64:67], v[188:191], v[120:123]
	v_mfma_f32_16x16x32_bf16 v[112:115], v[116:119], v[188:191], v[112:115]
	v_mfma_f32_16x16x32_bf16 v[96:99], v[64:67], v[196:199], v[96:99]
	v_mfma_f32_16x16x32_bf16 v[92:95], v[116:119], v[196:199], v[92:95]
	v_mfma_f32_16x16x32_bf16 v[80:83], v[64:67], v[204:207], v[80:83]
	v_mfma_f32_16x16x32_bf16 v[76:79], v[116:119], v[204:207], v[76:79]
	v_mfma_f32_16x16x32_bf16 v[140:143], v[108:111], v[184:187], v[140:143]
	v_mfma_f32_16x16x32_bf16 v[136:139], v[128:131], v[184:187], v[136:139]
	v_mfma_f32_16x16x32_bf16 v[120:123], v[108:111], v[192:195], v[120:123]
	v_mfma_f32_16x16x32_bf16 v[112:115], v[128:131], v[192:195], v[112:115]
	v_mfma_f32_16x16x32_bf16 v[96:99], v[108:111], v[200:203], v[96:99]
	v_mfma_f32_16x16x32_bf16 v[92:95], v[128:131], v[200:203], v[92:95]
	v_mfma_f32_16x16x32_bf16 v[80:83], v[108:111], v[208:211], v[80:83]
	v_mfma_f32_16x16x32_bf16 v[76:79], v[128:131], v[208:211], v[76:79]
	s_setprio 0
	s_setprio 1
	v_mfma_f32_16x16x32_bf16 v[132:135], v[156:159], v[180:183], v[132:135]
	v_mfma_f32_16x16x32_bf16 v[124:127], v[172:175], v[180:183], v[124:127]
	v_mfma_f32_16x16x32_bf16 v[104:107], v[156:159], v[188:191], v[104:107]
	v_mfma_f32_16x16x32_bf16 v[100:103], v[172:175], v[188:191], v[100:103]
	v_mfma_f32_16x16x32_bf16 v[88:91], v[156:159], v[196:199], v[88:91]
	v_mfma_f32_16x16x32_bf16 v[84:87], v[172:175], v[196:199], v[84:87]
	v_mfma_f32_16x16x32_bf16 v[72:75], v[156:159], v[204:207], v[72:75]
	v_mfma_f32_16x16x32_bf16 v[68:71], v[172:175], v[204:207], v[68:71]
	v_mfma_f32_16x16x32_bf16 v[132:135], v[168:171], v[184:187], v[132:135]
	v_mfma_f32_16x16x32_bf16 v[124:127], v[176:179], v[184:187], v[124:127]
	v_mfma_f32_16x16x32_bf16 v[104:107], v[168:171], v[192:195], v[104:107]
	v_mfma_f32_16x16x32_bf16 v[100:103], v[176:179], v[192:195], v[100:103]
	v_mfma_f32_16x16x32_bf16 v[88:91], v[168:171], v[200:203], v[88:91]
	v_mfma_f32_16x16x32_bf16 v[84:87], v[176:179], v[200:203], v[84:87]
	v_mfma_f32_16x16x32_bf16 v[72:75], v[168:171], v[208:211], v[72:75]
	s_setprio 2
	s_barrier
; #define PG8_STAGE(bufoff, gbase, voff) do { _Pragma("unroll") for (int _i = 0; _i < 2; ++_i) \
;         __builtin_amdgcn_global_load_lds((const unsigned*)((const char*)(gbase) + (voff)[_i]), (PG8_LAS unsigned*)(lds + (bufoff) + ldsw + _i * 8192), 16, 0, 0); } while (0)
; #define PG8_LDA(dst, b, h) do { _Pragma("unroll") for (int m = 0; m < 4; ++m) _Pragma("unroll") for (int k = 0; k < 2; ++k) dst[m][k] = *(const PG8_LAS bf16x8*)(lds + PG8_SA(b, h) + aoff + m * 2048 + k * 1024); } while (0)
; #define PG8_LDB(dst, b, h) do { _Pragma("unroll") for (int n = 0; n < 2; ++n) _Pragma("unroll") for (int k = 0; k < 2; ++k) dst[n][k] = *(const PG8_LAS bf16x8*)(lds + PG8_SB(b, h) + boff + n * 2048 + k * 1024); } while (0)
; #define PG8_MMA(ai, bj, At, Bt) do { __builtin_amdgcn_s_setprio(1); _Pragma("unroll") for (int m = 0; m < 4; ++m) _Pragma("unroll") for (int n = 0; n < 2; ++n) _Pragma("unroll") for (int k = 0; k < 2; ++k) \
;         acc[ai][bj][m][n] = __builtin_amdgcn_mfma_f32_16x16x32_bf16(Bt[n][k], At[m][k], acc[ai][bj][m][n], 0, 0, 0); __builtin_amdgcn_s_setprio(0); } while (0)
; #define PG8_WAIT_V(n) asm volatile("s_waitcnt vmcnt(" #n ")" ::: "memory")
; template <class Epi, class Sched, bool ALIGN_EPI = false, bool SP2 = false>
; __device__ __forceinline__ void gemm_phase(PG8_LAS unsigned char* lds, const Gemm g, const Sched& S, const Epi& E) {
;     ...
;             PG8_LDB(B0, 0, 0); PG8_LDB(B1, 0, 1); PG8_SCHED; PG8_LDA(At, 0, 0); PG8_STAGE(PG8_SA(1, 1), a1 + hstep, voffA);
;             PG8_WAIT_V(8); PG8_WAIT_L(0); PG8_BAR; PG8_MMA(0, 0, At, B0); PG8_MMA(0, 1, At, B1); PG8_BAR; PG8_SCHED;
;             PG8_LDA(At, 0, 1); PG8_STAGE(PG8_SB(0, 0), b2, voffB); PG8_STAGE(PG8_SB(0, 1), b2 + hstep, voffB); PG8_STAGE(PG8_SA(0, 0), a2, voffA);
;             PG8_WAIT_V(8); PG8_WAIT_L(0); PG8_BAR; PG8_MMA(1, 0, At, B0); PG8_MMA(1, 1, At, B1); PG8_BAR; PG8_SCHED;
;             PG8_LDB(B0, 1, 0); PG8_LDB(B1, 1, 1); PG8_SCHED; PG8_LDA(At, 1, 0); PG8_STAGE(PG8_SA(0, 1), a2 + hstep, voffA);
;             PG8_WAIT_V(8); PG8_WAIT_L(0); PG8_BAR; PG8_MMA(0, 0, At, B0); PG8_MMA(0, 1, At, B1); PG8_BAR; PG8_SCHED;
;             PG8_LDA(At, 1, 1); PG8_STAGE(PG8_SB(1, 0), b3, voffB); PG8_STAGE(PG8_SB(1, 1), b3 + hstep, voffB); PG8_STAGE(PG8_SA(1, 0), a3, voffA);
;             PG8_WAIT_V(8); PG8_WAIT_L(0); PG8_BAR; PG8_MMA(1, 0, At, B0); PG8_MMA(1, 1, At, B1); PG8_BAR; PG8_SCHED;
	v_mfma_f32_16x16x32_bf16 v[68:71], v[176:179], v[208:211], v[68:71]
	s_setprio 0
	s_add_i32 s30, s56, s34
	v_lshl_add_u64 v[160:161], v[160:161], 0, s[4:5]
	s_mov_b32 m0, s30
	ds_read_b128 v[180:183], v167 offset:49152
	ds_read_b128 v[184:187], v167 offset:50176
	ds_read_b128 v[188:191], v167 offset:51200
	ds_read_b128 v[192:195], v167 offset:52224
	ds_read_b128 v[196:199], v167 offset:53248
	ds_read_b128 v[200:203], v167 offset:54272
	ds_read_b128 v[204:207], v167 offset:55296
	ds_read_b128 v[208:211], v167 offset:56320
	global_load_lds_dwordx4 v[160:161], off
	s_add_i32 m0, s30, 0x2000
	s_add_u32 s28, s28, 0x200080
	v_lshl_add_u64 v[160:161], v[212:213], 0, s[4:5]
	s_addc_u32 s29, s29, 0
	s_add_i32 s30, s57, s34
	global_load_lds_dwordx4 v[160:161], off
	v_lshl_add_u64 v[160:161], s[28:29], 0, v[144:145]
	s_mov_b32 m0, s30
	s_nop 0
	global_load_lds_dwordx4 v[160:161], off
	v_lshl_add_u64 v[160:161], s[28:29], 0, v[146:147]
	s_add_i32 m0, s30, 0x2000
	s_nop 0
	global_load_lds_dwordx4 v[160:161], off
	v_lshl_add_u64 v[160:161], v[214:215], 0, s[4:5]
	s_mov_b32 m0, s42
	s_nop 0
	global_load_lds_dwordx4 v[160:161], off
	v_lshl_add_u64 v[160:161], v[216:217], 0, s[4:5]
	s_mov_b32 m0, s43
	s_nop 0
	global_load_lds_dwordx4 v[160:161], off
	s_setprio 1
	s_waitcnt vmcnt(8)
	s_waitcnt lgkmcnt(0)
	s_barrier
	v_mfma_f32_16x16x32_bf16 v[60:63], v[64:67], v[180:183], v[60:63]
	v_mfma_f32_16x16x32_bf16 v[56:59], v[116:119], v[180:183], v[56:59]
	v_mfma_f32_16x16x32_bf16 v[44:47], v[64:67], v[188:191], v[44:47]
	v_mfma_f32_16x16x32_bf16 v[40:43], v[116:119], v[188:191], v[40:43]
	v_mfma_f32_16x16x32_bf16 v[28:31], v[64:67], v[196:199], v[28:31]
	v_mfma_f32_16x16x32_bf16 v[24:27], v[116:119], v[196:199], v[24:27]
	v_mfma_f32_16x16x32_bf16 v[12:15], v[64:67], v[204:207], v[12:15]
	v_mfma_f32_16x16x32_bf16 v[8:11], v[116:119], v[204:207], v[8:11]
	v_mfma_f32_16x16x32_bf16 v[60:63], v[108:111], v[184:187], v[60:63]
	v_mfma_f32_16x16x32_bf16 v[56:59], v[128:131], v[184:187], v[56:59]
	v_mfma_f32_16x16x32_bf16 v[44:47], v[108:111], v[192:195], v[44:47]
	v_mfma_f32_16x16x32_bf16 v[40:43], v[128:131], v[192:195], v[40:43]
	v_mfma_f32_16x16x32_bf16 v[28:31], v[108:111], v[200:203], v[28:31]
	v_mfma_f32_16x16x32_bf16 v[24:27], v[128:131], v[200:203], v[24:27]
	v_mfma_f32_16x16x32_bf16 v[12:15], v[108:111], v[208:211], v[12:15]
	v_mfma_f32_16x16x32_bf16 v[8:11], v[128:131], v[208:211], v[8:11]
	s_setprio 0
	s_setprio 1
	v_mfma_f32_16x16x32_bf16 v[52:55], v[156:159], v[180:183], v[52:55]
	v_mfma_f32_16x16x32_bf16 v[48:51], v[172:175], v[180:183], v[48:51]
	v_mfma_f32_16x16x32_bf16 v[36:39], v[156:159], v[188:191], v[36:39]
	v_mfma_f32_16x16x32_bf16 v[32:35], v[172:175], v[188:191], v[32:35]
	v_mfma_f32_16x16x32_bf16 v[20:23], v[156:159], v[196:199], v[20:23]
	v_mfma_f32_16x16x32_bf16 v[16:19], v[172:175], v[196:199], v[16:19]
	v_mfma_f32_16x16x32_bf16 v[4:7], v[156:159], v[204:207], v[4:7]
	v_mfma_f32_16x16x32_bf16 v[0:3], v[172:175], v[204:207], v[0:3]
	v_mfma_f32_16x16x32_bf16 v[52:55], v[168:171], v[184:187], v[52:55]
	v_mfma_f32_16x16x32_bf16 v[48:51], v[176:179], v[184:187], v[48:51]
	v_mfma_f32_16x16x32_bf16 v[36:39], v[168:171], v[192:195], v[36:39]
	v_mfma_f32_16x16x32_bf16 v[32:35], v[176:179], v[192:195], v[32:35]
	v_mfma_f32_16x16x32_bf16 v[20:23], v[168:171], v[200:203], v[20:23]
	v_mfma_f32_16x16x32_bf16 v[16:19], v[176:179], v[200:203], v[16:19]
	v_mfma_f32_16x16x32_bf16 v[4:7], v[168:171], v[208:211], v[4:7]
	s_setprio 2
	s_barrier
	v_mfma_f32_16x16x32_bf16 v[0:3], v[176:179], v[208:211], v[0:3]
	s_setprio 0
	s_add_i32 s55, s55, 2
	s_add_u32 s26, s26, 0x100
	s_addc_u32 s27, s27, 0
	s_add_u32 s53, s53, 0x100
	s_addc_u32 s54, s54, 0
	s_cmpk_gt_u32 s55, 0x7d
.LBB0_1071:
	ds_read_b128 v[64:67], v165
	ds_read_b128 v[108:111], v165 offset:1024
	ds_read_b128 v[116:119], v165 offset:2048
	ds_read_b128 v[128:131], v165 offset:3072
	ds_read_b128 v[156:159], v166
	ds_read_b128 v[168:171], v166 offset:1024
	ds_read_b128 v[172:175], v166 offset:2048
	ds_read_b128 v[176:179], v166 offset:3072
	s_add_u32 s28, s26, 0xffe00080
	s_addc_u32 s29, s27, -1
	s_cmpk_eq_i32 s55, 0x7c
	s_cselect_b32 s31, s19, s29
	s_cselect_b32 s30, s51, s28
	s_cselect_b32 s29, s17, s54
	s_cselect_b32 s28, s52, s53
	v_lshl_add_u64 v[160:161], s[26:27], 0, v[148:149]
	s_add_i32 m0, s35, 0xc000
	ds_read_b128 v[180:183], v167
	ds_read_b128 v[184:187], v167 offset:1024
	ds_read_b128 v[188:191], v167 offset:2048
	ds_read_b128 v[192:195], v167 offset:3072
	ds_read_b128 v[196:199], v167 offset:4096
	ds_read_b128 v[200:203], v167 offset:5120
	ds_read_b128 v[204:207], v167 offset:6144
	ds_read_b128 v[208:211], v167 offset:7168
	global_load_lds_dwordx4 v[160:161], off
	v_lshl_add_u64 v[160:161], s[26:27], 0, v[150:151]
	s_add_i32 m0, s35, 0xe000
	s_nop 0
	global_load_lds_dwordx4 v[160:161], off
	s_setprio 1
	s_waitcnt vmcnt(8)
	s_waitcnt lgkmcnt(0)
	s_barrier
; #define PG8_STAGE(bufoff, gbase, voff) do { _Pragma("unroll") for (int _i = 0; _i < 2; ++_i) \
;         __builtin_amdgcn_global_load_lds((const unsigned*)((const char*)(gbase) + (voff)[_i]), (PG8_LAS unsigned*)(lds + (bufoff) + ldsw + _i * 8192), 16, 0, 0); } while (0)
; #define PG8_LDA(dst, b, h) do { _Pragma("unroll") for (int m = 0; m < 4; ++m) _Pragma("unroll") for (int k = 0; k < 2; ++k) dst[m][k] = *(const PG8_LAS bf16x8*)(lds + PG8_SA(b, h) + aoff + m * 2048 + k * 1024); } while (0)
; #define PG8_LDB(dst, b, h) do { _Pragma("unroll") for (int n = 0; n < 2; ++n) _Pragma("unroll") for (int k = 0; k < 2; ++k) dst[n][k] = *(const PG8_LAS bf16x8*)(lds + PG8_SB(b, h) + boff + n * 2048 + k * 1024); } while (0)
; #define PG8_MMA(ai, bj, At, Bt) do { __builtin_amdgcn_s_setprio(1); _Pragma("unroll") for (int m = 0; m < 4; ++m) _Pragma("unroll") for (int n = 0; n < 2; ++n) _Pragma("unroll") for (int k = 0; k < 2; ++k) \
;         acc[ai][bj][m][n] = __builtin_amdgcn_mfma_f32_16x16x32_bf16(Bt[n][k], At[m][k], acc[ai][bj][m][n], 0, 0, 0); __builtin_amdgcn_s_setprio(0); } while (0)
; #define PG8_WAIT_V(n) asm volatile("s_waitcnt vmcnt(" #n ")" ::: "memory")
; template <class Epi, class Sched, bool ALIGN_EPI = false, bool SP2 = false>
; __device__ __forceinline__ void gemm_phase(PG8_LAS unsigned char* lds, const Gemm g, const Sched& S, const Epi& E) {
;     ...
;             PG8_LDB(B0, 0, 0); PG8_LDB(B1, 0, 1); PG8_SCHED; PG8_LDA(At, 0, 0); PG8_STAGE(PG8_SA(1, 1), a1 + hstep, voffA);
;             PG8_WAIT_V(8); PG8_WAIT_L(0); PG8_BAR; PG8_MMA(0, 0, At, B0); PG8_MMA(0, 1, At, B1); PG8_BAR; PG8_SCHED;
;             PG8_LDA(At, 0, 1); PG8_STAGE(PG8_SB(0, 0), b2, voffB); PG8_STAGE(PG8_SB(0, 1), b2 + hstep, voffB); PG8_STAGE(PG8_SA(0, 0), a2, voffA);
;             PG8_WAIT_V(8); PG8_WAIT_L(0); PG8_BAR; PG8_MMA(1, 0, At, B0); PG8_MMA(1, 1, At, B1); PG8_BAR; PG8_SCHED;
;             PG8_LDB(B0, 1, 0); PG8_LDB(B1, 1, 1); PG8_SCHED; PG8_LDA(At, 1, 0); PG8_STAGE(PG8_SA(0, 1), a2 + hstep, voffA);
;             PG8_WAIT_V(8); PG8_WAIT_L(0); PG8_BAR; PG8_MMA(0, 0, At, B0); PG8_MMA(0, 1, At, B1); PG8_BAR; PG8_SCHED;
;             PG8_LDA(At, 1, 1); PG8_STAGE(PG8_SB(1, 0), b3, voffB); PG8_STAGE(PG8_SB(1, 1), b3 + hstep, voffB); PG8_STAGE(PG8_SA(1, 0), a3, voffA);
;             PG8_WAIT_V(8); PG8_WAIT_L(0); PG8_BAR; PG8_MMA(1, 0, At, B0); PG8_MMA(1, 1, At, B1); PG8_BAR; PG8_SCHED;
	v_mfma_f32_16x16x32_bf16 v[140:143], v[64:67], v[180:183], v[140:143]
	v_mfma_f32_16x16x32_bf16 v[136:139], v[116:119], v[180:183], v[136:139]
	v_mfma_f32_16x16x32_bf16 v[120:123], v[64:67], v[188:191], v[120:123]
	v_mfma_f32_16x16x32_bf16 v[112:115], v[116:119], v[188:191], v[112:115]
	v_mfma_f32_16x16x32_bf16 v[96:99], v[64:67], v[196:199], v[96:99]
	v_mfma_f32_16x16x32_bf16 v[92:95], v[116:119], v[196:199], v[92:95]
	v_mfma_f32_16x16x32_bf16 v[80:83], v[64:67], v[204:207], v[80:83]
	v_mfma_f32_16x16x32_bf16 v[76:79], v[116:119], v[204:207], v[76:79]
	v_mfma_f32_16x16x32_bf16 v[140:143], v[108:111], v[184:187], v[140:143]
	v_mfma_f32_16x16x32_bf16 v[136:139], v[128:131], v[184:187], v[136:139]
	v_mfma_f32_16x16x32_bf16 v[120:123], v[108:111], v[192:195], v[120:123]
	v_mfma_f32_16x16x32_bf16 v[112:115], v[128:131], v[192:195], v[112:115]
	v_mfma_f32_16x16x32_bf16 v[96:99], v[108:111], v[200:203], v[96:99]
	v_mfma_f32_16x16x32_bf16 v[92:95], v[128:131], v[200:203], v[92:95]
	v_mfma_f32_16x16x32_bf16 v[80:83], v[108:111], v[208:211], v[80:83]
	v_mfma_f32_16x16x32_bf16 v[76:79], v[128:131], v[208:211], v[76:79]
	s_setprio 0
	s_setprio 1
	v_mfma_f32_16x16x32_bf16 v[132:135], v[156:159], v[180:183], v[132:135]
	v_mfma_f32_16x16x32_bf16 v[124:127], v[172:175], v[180:183], v[124:127]
	v_mfma_f32_16x16x32_bf16 v[104:107], v[156:159], v[188:191], v[104:107]
	v_mfma_f32_16x16x32_bf16 v[100:103], v[172:175], v[188:191], v[100:103]
	v_mfma_f32_16x16x32_bf16 v[88:91], v[156:159], v[196:199], v[88:91]
	v_mfma_f32_16x16x32_bf16 v[84:87], v[172:175], v[196:199], v[84:87]
	v_mfma_f32_16x16x32_bf16 v[72:75], v[156:159], v[204:207], v[72:75]
	v_mfma_f32_16x16x32_bf16 v[68:71], v[172:175], v[204:207], v[68:71]
	v_mfma_f32_16x16x32_bf16 v[132:135], v[168:171], v[184:187], v[132:135]
	v_mfma_f32_16x16x32_bf16 v[124:127], v[176:179], v[184:187], v[124:127]
	v_mfma_f32_16x16x32_bf16 v[104:107], v[168:171], v[192:195], v[104:107]
	v_mfma_f32_16x16x32_bf16 v[100:103], v[176:179], v[192:195], v[100:103]
	v_mfma_f32_16x16x32_bf16 v[88:91], v[168:171], v[200:203], v[88:91]
	v_mfma_f32_16x16x32_bf16 v[84:87], v[176:179], v[200:203], v[84:87]
	v_mfma_f32_16x16x32_bf16 v[72:75], v[168:171], v[208:211], v[72:75]
	s_setprio 2
	s_barrier
	v_mfma_f32_16x16x32_bf16 v[68:71], v[176:179], v[208:211], v[68:71]
	s_setprio 0
	s_add_i32 s56, s45, s34
	v_lshl_add_u64 v[160:161], s[28:29], 0, v[144:145]
	s_mov_b32 m0, s56
	ds_read_b128 v[180:183], v167 offset:16384
	ds_read_b128 v[184:187], v167 offset:17408
	ds_read_b128 v[188:191], v167 offset:18432
	ds_read_b128 v[192:195], v167 offset:19456
	ds_read_b128 v[196:199], v167 offset:20480
	ds_read_b128 v[200:203], v167 offset:21504
	ds_read_b128 v[204:207], v167 offset:22528
	ds_read_b128 v[208:211], v167 offset:23552
	global_load_lds_dwordx4 v[160:161], off
	s_add_i32 m0, s56, 0x2000
	s_add_u32 s56, s28, 0x200000
	v_lshl_add_u64 v[212:213], s[28:29], 0, v[146:147]
	s_addc_u32 s57, s29, 0
	s_add_i32 s58, s46, s34
	global_load_lds_dwordx4 v[212:213], off
	v_lshl_add_u64 v[214:215], s[56:57], 0, v[144:145]
	s_mov_b32 m0, s58
	v_lshl_add_u64 v[216:217], s[30:31], 0, v[146:147]
	global_load_lds_dwordx4 v[214:215], off
	v_lshl_add_u64 v[214:215], s[56:57], 0, v[146:147]
	s_add_i32 m0, s58, 0x2000
	s_nop 0
	global_load_lds_dwordx4 v[214:215], off
	v_lshl_add_u64 v[214:215], s[30:31], 0, v[144:145]
	s_mov_b32 m0, s35
	s_nop 0
	global_load_lds_dwordx4 v[214:215], off
	s_mov_b32 m0, s36
	s_nop 0
	global_load_lds_dwordx4 v[216:217], off
	s_setprio 1
	s_waitcnt vmcnt(8)
	s_waitcnt lgkmcnt(0)
	s_barrier
	v_mfma_f32_16x16x32_bf16 v[60:63], v[64:67], v[180:183], v[60:63]
	v_mfma_f32_16x16x32_bf16 v[56:59], v[116:119], v[180:183], v[56:59]
	v_mfma_f32_16x16x32_bf16 v[44:47], v[64:67], v[188:191], v[44:47]
	v_mfma_f32_16x16x32_bf16 v[40:43], v[116:119], v[188:191], v[40:43]
	v_mfma_f32_16x16x32_bf16 v[28:31], v[64:67], v[196:199], v[28:31]
	v_mfma_f32_16x16x32_bf16 v[24:27], v[116:119], v[196:199], v[24:27]
	v_mfma_f32_16x16x32_bf16 v[12:15], v[64:67], v[204:207], v[12:15]
	v_mfma_f32_16x16x32_bf16 v[8:11], v[116:119], v[204:207], v[8:11]
	v_mfma_f32_16x16x32_bf16 v[60:63], v[108:111], v[184:187], v[60:63]
	v_mfma_f32_16x16x32_bf16 v[56:59], v[128:131], v[184:187], v[56:59]
	v_mfma_f32_16x16x32_bf16 v[44:47], v[108:111], v[192:195], v[44:47]
	v_mfma_f32_16x16x32_bf16 v[40:43], v[128:131], v[192:195], v[40:43]
	v_mfma_f32_16x16x32_bf16 v[28:31], v[108:111], v[200:203], v[28:31]
	v_mfma_f32_16x16x32_bf16 v[24:27], v[128:131], v[200:203], v[24:27]
	v_mfma_f32_16x16x32_bf16 v[12:15], v[108:111], v[208:211], v[12:15]
	v_mfma_f32_16x16x32_bf16 v[8:11], v[128:131], v[208:211], v[8:11]
	s_setprio 0
	s_setprio 1
	v_mfma_f32_16x16x32_bf16 v[52:55], v[156:159], v[180:183], v[52:55]
	v_mfma_f32_16x16x32_bf16 v[48:51], v[172:175], v[180:183], v[48:51]
	v_mfma_f32_16x16x32_bf16 v[36:39], v[156:159], v[188:191], v[36:39]
	v_mfma_f32_16x16x32_bf16 v[32:35], v[172:175], v[188:191], v[32:35]
	v_mfma_f32_16x16x32_bf16 v[20:23], v[156:159], v[196:199], v[20:23]
	v_mfma_f32_16x16x32_bf16 v[16:19], v[172:175], v[196:199], v[16:19]
	v_mfma_f32_16x16x32_bf16 v[4:7], v[156:159], v[204:207], v[4:7]
	v_mfma_f32_16x16x32_bf16 v[0:3], v[172:175], v[204:207], v[0:3]
	v_mfma_f32_16x16x32_bf16 v[52:55], v[168:171], v[184:187], v[52:55]
	v_mfma_f32_16x16x32_bf16 v[48:51], v[176:179], v[184:187], v[48:51]
	v_mfma_f32_16x16x32_bf16 v[36:39], v[168:171], v[192:195], v[36:39]
	v_mfma_f32_16x16x32_bf16 v[32:35], v[176:179], v[192:195], v[32:35]
	v_mfma_f32_16x16x32_bf16 v[20:23], v[168:171], v[200:203], v[20:23]
	v_mfma_f32_16x16x32_bf16 v[16:19], v[176:179], v[200:203], v[16:19]
	v_mfma_f32_16x16x32_bf16 v[4:7], v[168:171], v[208:211], v[4:7]
	s_setprio 2
	s_barrier
; #define PG8_STAGE(bufoff, gbase, voff) do { _Pragma("unroll") for (int _i = 0; _i < 2; ++_i) \
;         __builtin_amdgcn_global_load_lds((const unsigned*)((const char*)(gbase) + (voff)[_i]), (PG8_LAS unsigned*)(lds + (bufoff) + ldsw + _i * 8192), 16, 0, 0); } while (0)
; #define PG8_LDA(dst, b, h) do { _Pragma("unroll") for (int m = 0; m < 4; ++m) _Pragma("unroll") for (int k = 0; k < 2; ++k) dst[m][k] = *(const PG8_LAS bf16x8*)(lds + PG8_SA(b, h) + aoff + m * 2048 + k * 1024); } while (0)
; #define PG8_LDB(dst, b, h) do { _Pragma("unroll") for (int n = 0; n < 2; ++n) _Pragma("unroll") for (int k = 0; k < 2; ++k) dst[n][k] = *(const PG8_LAS bf16x8*)(lds + PG8_SB(b, h) + boff + n * 2048 + k * 1024); } while (0)
; #define PG8_MMA(ai, bj, At, Bt) do { __builtin_amdgcn_s_setprio(1); _Pragma("unroll") for (int m = 0; m < 4; ++m) _Pragma("unroll") for (int n = 0; n < 2; ++n) _Pragma("unroll") for (int k = 0; k < 2; ++k) \
;         acc[ai][bj][m][n] = __builtin_amdgcn_mfma_f32_16x16x32_bf16(Bt[n][k], At[m][k], acc[ai][bj][m][n], 0, 0, 0); __builtin_amdgcn_s_setprio(0); } while (0)
; #define PG8_WAIT_V(n) asm volatile("s_waitcnt vmcnt(" #n ")" ::: "memory")
; template <class Epi, class Sched, bool ALIGN_EPI = false, bool SP2 = false>
; __device__ __forceinline__ void gemm_phase(PG8_LAS unsigned char* lds, const Gemm g, const Sched& S, const Epi& E) {
;     ...
;             PG8_LDB(B0, 0, 0); PG8_LDB(B1, 0, 1); PG8_SCHED; PG8_LDA(At, 0, 0); PG8_STAGE(PG8_SA(1, 1), a1 + hstep, voffA);
;             PG8_WAIT_V(8); PG8_WAIT_L(0); PG8_BAR; PG8_MMA(0, 0, At, B0); PG8_MMA(0, 1, At, B1); PG8_BAR; PG8_SCHED;
;             PG8_LDA(At, 0, 1); PG8_STAGE(PG8_SB(0, 0), b2, voffB); PG8_STAGE(PG8_SB(0, 1), b2 + hstep, voffB); PG8_STAGE(PG8_SA(0, 0), a2, voffA);
;             PG8_WAIT_V(8); PG8_WAIT_L(0); PG8_BAR; PG8_MMA(1, 0, At, B0); PG8_MMA(1, 1, At, B1); PG8_BAR; PG8_SCHED;
;             PG8_LDB(B0, 1, 0); PG8_LDB(B1, 1, 1); PG8_SCHED; PG8_LDA(At, 1, 0); PG8_STAGE(PG8_SA(0, 1), a2 + hstep, voffA);
;             PG8_WAIT_V(8); PG8_WAIT_L(0); PG8_BAR; PG8_MMA(0, 0, At, B0); PG8_MMA(0, 1, At, B1); PG8_BAR; PG8_SCHED;
;             PG8_LDA(At, 1, 1); PG8_STAGE(PG8_SB(1, 0), b3, voffB); PG8_STAGE(PG8_SB(1, 1), b3 + hstep, voffB); PG8_STAGE(PG8_SA(1, 0), a3, voffA);
;             PG8_WAIT_V(8); PG8_WAIT_L(0); PG8_BAR; PG8_MMA(1, 0, At, B0); PG8_MMA(1, 1, At, B1); PG8_BAR; PG8_SCHED;
	v_mfma_f32_16x16x32_bf16 v[0:3], v[176:179], v[208:211], v[0:3]
	s_setprio 0
	s_add_i32 s56, 0, 0x18000
	s_add_i32 s57, 0, 0x1c000
	v_add_u32_e32 v128, s56, v163
	v_add_u32_e32 v176, s57, v163
	ds_read_b128 v[64:67], v128
	ds_read_b128 v[108:111], v128 offset:1024
	ds_read_b128 v[116:119], v128 offset:2048
	ds_read_b128 v[128:131], v128 offset:3072
	ds_read_b128 v[156:159], v176
	ds_read_b128 v[168:171], v176 offset:1024
	ds_read_b128 v[172:175], v176 offset:2048
	ds_read_b128 v[176:179], v176 offset:3072
	s_add_u32 s30, s30, 0x200000
	s_addc_u32 s31, s31, 0
	s_mov_b32 m0, s37
	v_lshl_add_u64 v[218:219], s[30:31], 0, v[144:145]
	ds_read_b128 v[180:183], v167 offset:32768
	ds_read_b128 v[184:187], v167 offset:33792
	ds_read_b128 v[188:191], v167 offset:34816
	ds_read_b128 v[192:195], v167 offset:35840
	ds_read_b128 v[196:199], v167 offset:36864
	ds_read_b128 v[200:203], v167 offset:37888
	ds_read_b128 v[204:207], v167 offset:38912
	ds_read_b128 v[208:211], v167 offset:39936
	global_load_lds_dwordx4 v[218:219], off
	v_lshl_add_u64 v[218:219], s[30:31], 0, v[146:147]
	s_mov_b32 m0, s38
	s_nop 0
	global_load_lds_dwordx4 v[218:219], off
	s_setprio 1
	s_waitcnt vmcnt(8)
	s_waitcnt lgkmcnt(0)
	s_barrier
	v_mfma_f32_16x16x32_bf16 v[140:143], v[64:67], v[180:183], v[140:143]
	v_mfma_f32_16x16x32_bf16 v[136:139], v[116:119], v[180:183], v[136:139]
	v_mfma_f32_16x16x32_bf16 v[120:123], v[64:67], v[188:191], v[120:123]
	v_mfma_f32_16x16x32_bf16 v[112:115], v[116:119], v[188:191], v[112:115]
	v_mfma_f32_16x16x32_bf16 v[96:99], v[64:67], v[196:199], v[96:99]
	v_mfma_f32_16x16x32_bf16 v[92:95], v[116:119], v[196:199], v[92:95]
	v_mfma_f32_16x16x32_bf16 v[80:83], v[64:67], v[204:207], v[80:83]
	v_mfma_f32_16x16x32_bf16 v[76:79], v[116:119], v[204:207], v[76:79]
	v_mfma_f32_16x16x32_bf16 v[140:143], v[108:111], v[184:187], v[140:143]
	v_mfma_f32_16x16x32_bf16 v[136:139], v[128:131], v[184:187], v[136:139]
	v_mfma_f32_16x16x32_bf16 v[120:123], v[108:111], v[192:195], v[120:123]
	v_mfma_f32_16x16x32_bf16 v[112:115], v[128:131], v[192:195], v[112:115]
	v_mfma_f32_16x16x32_bf16 v[96:99], v[108:111], v[200:203], v[96:99]
	v_mfma_f32_16x16x32_bf16 v[92:95], v[128:131], v[200:203], v[92:95]
	v_mfma_f32_16x16x32_bf16 v[80:83], v[108:111], v[208:211], v[80:83]
	v_mfma_f32_16x16x32_bf16 v[76:79], v[128:131], v[208:211], v[76:79]
	s_setprio 0
	s_setprio 1
	v_mfma_f32_16x16x32_bf16 v[132:135], v[156:159], v[180:183], v[132:135]
	v_mfma_f32_16x16x32_bf16 v[124:127], v[172:175], v[180:183], v[124:127]
	v_mfma_f32_16x16x32_bf16 v[104:107], v[156:159], v[188:191], v[104:107]
	v_mfma_f32_16x16x32_bf16 v[100:103], v[172:175], v[188:191], v[100:103]
	v_mfma_f32_16x16x32_bf16 v[88:91], v[156:159], v[196:199], v[88:91]
	v_mfma_f32_16x16x32_bf16 v[84:87], v[172:175], v[196:199], v[84:87]
	v_mfma_f32_16x16x32_bf16 v[72:75], v[156:159], v[204:207], v[72:75]
	v_mfma_f32_16x16x32_bf16 v[68:71], v[172:175], v[204:207], v[68:71]
	v_mfma_f32_16x16x32_bf16 v[132:135], v[168:171], v[184:187], v[132:135]
	v_mfma_f32_16x16x32_bf16 v[124:127], v[176:179], v[184:187], v[124:127]
	v_mfma_f32_16x16x32_bf16 v[104:107], v[168:171], v[192:195], v[104:107]
	v_mfma_f32_16x16x32_bf16 v[100:103], v[176:179], v[192:195], v[100:103]
	v_mfma_f32_16x16x32_bf16 v[88:91], v[168:171], v[200:203], v[88:91]
	v_mfma_f32_16x16x32_bf16 v[84:87], v[176:179], v[200:203], v[84:87]
	v_mfma_f32_16x16x32_bf16 v[72:75], v[168:171], v[208:211], v[72:75]
	s_setprio 2
	s_barrier
; #define PG8_STAGE(bufoff, gbase, voff) do { _Pragma("unroll") for (int _i = 0; _i < 2; ++_i) \
;         __builtin_amdgcn_global_load_lds((const unsigned*)((const char*)(gbase) + (voff)[_i]), (PG8_LAS unsigned*)(lds + (bufoff) + ldsw + _i * 8192), 16, 0, 0); } while (0)
; #define PG8_LDA(dst, b, h) do { _Pragma("unroll") for (int m = 0; m < 4; ++m) _Pragma("unroll") for (int k = 0; k < 2; ++k) dst[m][k] = *(const PG8_LAS bf16x8*)(lds + PG8_SA(b, h) + aoff + m * 2048 + k * 1024); } while (0)
; #define PG8_LDB(dst, b, h) do { _Pragma("unroll") for (int n = 0; n < 2; ++n) _Pragma("unroll") for (int k = 0; k < 2; ++k) dst[n][k] = *(const PG8_LAS bf16x8*)(lds + PG8_SB(b, h) + boff + n * 2048 + k * 1024); } while (0)
; #define PG8_MMA(ai, bj, At, Bt) do { __builtin_amdgcn_s_setprio(1); _Pragma("unroll") for (int m = 0; m < 4; ++m) _Pragma("unroll") for (int n = 0; n < 2; ++n) _Pragma("unroll") for (int k = 0; k < 2; ++k) \
;         acc[ai][bj][m][n] = __builtin_amdgcn_mfma_f32_16x16x32_bf16(Bt[n][k], At[m][k], acc[ai][bj][m][n], 0, 0, 0); __builtin_amdgcn_s_setprio(0); } while (0)
; template <class Epi, class Sched, bool ALIGN_EPI = false, bool SP2 = false>
; __device__ __forceinline__ void gemm_phase(PG8_LAS unsigned char* lds, const Gemm g, const Sched& S, const Epi& E) {
;     ...
;             PG8_LDB(B0, 0, 0); PG8_LDB(B1, 0, 1); PG8_SCHED; PG8_LDA(At, 0, 0); PG8_STAGE(PG8_SA(1, 1), a1 + hstep, voffA);
;             PG8_WAIT_V(8); PG8_WAIT_L(0); PG8_BAR; PG8_MMA(0, 0, At, B0); PG8_MMA(0, 1, At, B1); PG8_BAR; PG8_SCHED;
;             PG8_LDA(At, 0, 1); PG8_STAGE(PG8_SB(0, 0), b2, voffB); PG8_STAGE(PG8_SB(0, 1), b2 + hstep, voffB); PG8_STAGE(PG8_SA(0, 0), a2, voffA);
;             PG8_WAIT_V(8); PG8_WAIT_L(0); PG8_BAR; PG8_MMA(1, 0, At, B0); PG8_MMA(1, 1, At, B1); PG8_BAR; PG8_SCHED;
;             PG8_LDB(B0, 1, 0); PG8_LDB(B1, 1, 1); PG8_SCHED; PG8_LDA(At, 1, 0); PG8_STAGE(PG8_SA(0, 1), a2 + hstep, voffA);
;             PG8_WAIT_V(8); PG8_WAIT_L(0); PG8_BAR; PG8_MMA(0, 0, At, B0); PG8_MMA(0, 1, At, B1); PG8_BAR; PG8_SCHED;
;             PG8_LDA(At, 1, 1); PG8_STAGE(PG8_SB(1, 0), b3, voffB); PG8_STAGE(PG8_SB(1, 1), b3 + hstep, voffB); PG8_STAGE(PG8_SA(1, 0), a3, voffA);
;             PG8_WAIT_V(8); PG8_WAIT_L(0); PG8_BAR; PG8_MMA(1, 0, At, B0); PG8_MMA(1, 1, At, B1); PG8_BAR; PG8_SCHED;
;     ...
;         if constexpr (ALIGN_EPI) { if (wr == 0) PG8_BAR; }
	v_mfma_f32_16x16x32_bf16 v[68:71], v[176:179], v[208:211], v[68:71]
	s_setprio 0
	s_add_i32 s30, s56, s34
	v_lshl_add_u64 v[160:161], v[160:161], 0, s[4:5]
	s_mov_b32 m0, s30
	ds_read_b128 v[180:183], v167 offset:49152
	ds_read_b128 v[184:187], v167 offset:50176
	ds_read_b128 v[188:191], v167 offset:51200
	ds_read_b128 v[192:195], v167 offset:52224
	ds_read_b128 v[196:199], v167 offset:53248
	ds_read_b128 v[200:203], v167 offset:54272
	ds_read_b128 v[204:207], v167 offset:55296
	ds_read_b128 v[208:211], v167 offset:56320
	global_load_lds_dwordx4 v[160:161], off
	s_add_i32 m0, s30, 0x2000
	s_add_u32 s28, s28, 0x200080
	v_lshl_add_u64 v[160:161], v[212:213], 0, s[4:5]
	s_addc_u32 s29, s29, 0
	s_add_i32 s30, s57, s34
	global_load_lds_dwordx4 v[160:161], off
	v_lshl_add_u64 v[160:161], s[28:29], 0, v[144:145]
	s_mov_b32 m0, s30
	s_nop 0
	global_load_lds_dwordx4 v[160:161], off
	v_lshl_add_u64 v[160:161], s[28:29], 0, v[146:147]
	s_add_i32 m0, s30, 0x2000
	s_nop 0
	global_load_lds_dwordx4 v[160:161], off
	v_lshl_add_u64 v[160:161], v[214:215], 0, s[4:5]
	s_mov_b32 m0, s42
	s_nop 0
	global_load_lds_dwordx4 v[160:161], off
	v_lshl_add_u64 v[160:161], v[216:217], 0, s[4:5]
	s_mov_b32 m0, s43
	s_nop 0
	global_load_lds_dwordx4 v[160:161], off
	s_setprio 1
	s_waitcnt vmcnt(8)
	s_waitcnt lgkmcnt(0)
	s_barrier
	v_mfma_f32_16x16x32_bf16 v[60:63], v[64:67], v[180:183], v[60:63]
	v_mfma_f32_16x16x32_bf16 v[56:59], v[116:119], v[180:183], v[56:59]
	v_mfma_f32_16x16x32_bf16 v[44:47], v[64:67], v[188:191], v[44:47]
	v_mfma_f32_16x16x32_bf16 v[40:43], v[116:119], v[188:191], v[40:43]
	v_mfma_f32_16x16x32_bf16 v[28:31], v[64:67], v[196:199], v[28:31]
	v_mfma_f32_16x16x32_bf16 v[24:27], v[116:119], v[196:199], v[24:27]
	v_mfma_f32_16x16x32_bf16 v[12:15], v[64:67], v[204:207], v[12:15]
	v_mfma_f32_16x16x32_bf16 v[8:11], v[116:119], v[204:207], v[8:11]
	v_mfma_f32_16x16x32_bf16 v[60:63], v[108:111], v[184:187], v[60:63]
	v_mfma_f32_16x16x32_bf16 v[56:59], v[128:131], v[184:187], v[56:59]
	v_mfma_f32_16x16x32_bf16 v[44:47], v[108:111], v[192:195], v[44:47]
	v_mfma_f32_16x16x32_bf16 v[40:43], v[128:131], v[192:195], v[40:43]
	v_mfma_f32_16x16x32_bf16 v[28:31], v[108:111], v[200:203], v[28:31]
	v_mfma_f32_16x16x32_bf16 v[24:27], v[128:131], v[200:203], v[24:27]
	v_mfma_f32_16x16x32_bf16 v[12:15], v[108:111], v[208:211], v[12:15]
	v_mfma_f32_16x16x32_bf16 v[8:11], v[128:131], v[208:211], v[8:11]
	s_setprio 0
	s_setprio 1
	v_mfma_f32_16x16x32_bf16 v[52:55], v[156:159], v[180:183], v[52:55]
	v_mfma_f32_16x16x32_bf16 v[48:51], v[172:175], v[180:183], v[48:51]
	v_mfma_f32_16x16x32_bf16 v[36:39], v[156:159], v[188:191], v[36:39]
	v_mfma_f32_16x16x32_bf16 v[32:35], v[172:175], v[188:191], v[32:35]
	v_mfma_f32_16x16x32_bf16 v[20:23], v[156:159], v[196:199], v[20:23]
	v_mfma_f32_16x16x32_bf16 v[16:19], v[172:175], v[196:199], v[16:19]
	v_mfma_f32_16x16x32_bf16 v[4:7], v[156:159], v[204:207], v[4:7]
	v_mfma_f32_16x16x32_bf16 v[0:3], v[172:175], v[204:207], v[0:3]
	v_mfma_f32_16x16x32_bf16 v[52:55], v[168:171], v[184:187], v[52:55]
	v_mfma_f32_16x16x32_bf16 v[48:51], v[176:179], v[184:187], v[48:51]
	v_mfma_f32_16x16x32_bf16 v[36:39], v[168:171], v[192:195], v[36:39]
	v_mfma_f32_16x16x32_bf16 v[32:35], v[176:179], v[192:195], v[32:35]
	v_mfma_f32_16x16x32_bf16 v[20:23], v[168:171], v[200:203], v[20:23]
	v_mfma_f32_16x16x32_bf16 v[16:19], v[176:179], v[200:203], v[16:19]
	v_mfma_f32_16x16x32_bf16 v[4:7], v[168:171], v[208:211], v[4:7]
	s_setprio 2
	s_barrier
	v_mfma_f32_16x16x32_bf16 v[0:3], v[176:179], v[208:211], v[0:3]
	s_setprio 0
	s_add_i32 s55, s55, 2
	s_add_u32 s26, s26, 0x100
	s_addc_u32 s27, s27, 0
	s_add_u32 s53, s53, 0x100
	s_addc_u32 s54, s54, 0
	s_cmpk_gt_u32 s55, 0x7d
	s_cbranch_scc0 .LBB0_1071
	s_and_b64 vcc, exec, s[6:7]
	s_cbranch_vccz .LBB0_1074
	s_barrier
